# packed f32 VALU ops split into scalar pairs everywhere (GEMM epilogues, norm loops, combine, rescale paths)
# speedup vs baseline: 1.0157x; 1.0046x over previous
; __global__ void __launch_bounds__(NTHREADS, 2) fwd_megakernel(Args a) {
;     ...
;             for (int k = wave * 128; k < wave * 128 + 128; ++k) { const float w = wp[(size_t)k * NMOD6];
; #pragma unroll
;                 for (int s = 0; s < 5; ++s) acc[s] += sl[s * 1024 + k] * w; }
.LBB0_19:
	global_load_dword v22, v[14:15], off
	v_mov_b32_e32 v17, s54
	ds_read2st64_b32 v[24:25], v17 offset1:16
	ds_read2st64_b32 v[26:27], v17 offset0:32 offset1:48
	ds_read_b32 v17, v17 offset:16384
	s_add_i32 s54, s54, 4
	s_add_i32 s52, s52, -4
	v_lshl_add_u64 v[14:15], v[14:15], 0, s[38:39]
	s_cmp_lg_u32 s52, 0
	s_waitcnt vmcnt(0) lgkmcnt(2)
	v_fma_f32 v20, v22, v24, v20
	v_fma_f32 v21, v22, v25, v21
	s_waitcnt lgkmcnt(1)
	v_fma_f32 v18, v22, v26, v18
	v_fma_f32 v19, v22, v27, v19
	s_waitcnt lgkmcnt(0)
	v_fmac_f32_e32 v7, v22, v17
	s_cbranch_scc1 .LBB0_19
	s_mov_b32 s54, s33

; __global__ void __launch_bounds__(NTHREADS, 2) fwd_megakernel(Args a) {
;     ...
;         if (bx == G - 1) {
;             for (int i = tid; i < 128 * 16; i += NTHREADS) { const int pos = i / 16, f = i % 16; const float inv = powf(10000.0f, -(float)f / 16.0f); const float ang = (float)pos * inv;
;                 ROPE[2 * i] = cosf(ang); ROPE[2 * i + 1] = sinf(ang); }
;         }
.LBB0_33:
	s_or_b64 exec, exec, s[4:5]
	s_add_i32 s0, s34, -1
	s_cmp_lg_u32 s2, s0
	v_lshlrev_b32_e32 v6, 3, v222
	s_cbranch_scc1 .LBB0_45
	v_and_b32_e32 v1, 15, v222
	v_cvt_f32_ubyte0_e32 v1, v1
	v_mul_f32_e32 v1, 0xbd800000, v1
	v_mov_b32_e32 v2, 0x461c4000
	v_cmp_eq_f32_e32 vcc, 0, v1
	s_mov_b32 s0, 0x3f2aaaab
	s_movk_i32 s3, 0x204
	v_cndmask_b32_e64 v5, v2, 1.0, vcc
	v_frexp_mant_f32_e32 v2, v5
	v_cmp_gt_f32_e64 s[0:1], s0, v2
	s_mov_b32 s5, 0x42b17218
	s_mov_b32 s4, 0x7f800000
	v_cndmask_b32_e64 v3, 1.0, 2.0, s[0:1]
	v_mul_f32_e32 v2, v2, v3
	v_add_f32_e32 v7, 1.0, v2
	v_rcp_f32_e32 v14, v7
	v_add_f32_e32 v3, -1.0, v7
	v_sub_f32_e32 v9, v2, v3
	v_add_f32_e32 v3, -1.0, v2
	v_mul_f32_e32 v15, v3, v14
	v_mul_f32_e32 v8, v7, v15
	v_fma_f32 v10, v15, v7, -v8
	v_fmac_f32_e32 v10, v15, v9
	v_add_f32_e32 v2, v8, v10
	v_sub_f32_e32 v9, v3, v2
	v_add_f32_e64 v12, v2, -v8
	v_add_f32_e64 v13, v3, -v9
	v_mov_b32_e32 v11, v2
	v_add_f32_e64 v2, v12, -v10
	v_add_f32_e64 v3, v13, -v11
	v_mov_b32_e32 v10, 0x3e91f4c4
	v_add_f32_e32 v2, v2, v3
	v_add_f32_e32 v2, v9, v2
	v_mul_f32_e32 v3, v14, v2
	v_add_f32_e32 v2, v15, v3
	v_sub_f32_e32 v7, v2, v15
	v_sub_f32_e32 v7, v3, v7
	v_mul_f32_e32 v3, v2, v2
	v_fma_f32 v9, v2, v2, -v3
	v_add_f32_e32 v8, v7, v7
	v_fmac_f32_e32 v9, v2, v8
	v_add_f32_e32 v8, v3, v9
	v_fmac_f32_e32 v10, 0x3e76c4e1, v8
	v_fmaak_f32 v10, v8, v10, 0x3ecccdef
	v_sub_f32_e32 v3, v8, v3
	v_sub_f32_e32 v16, v9, v3
	v_mul_f32_e32 v3, v8, v10
	v_fma_f32 v9, v8, v10, -v3
	v_fmac_f32_e32 v9, v16, v10
	v_add_f32_e32 v10, v3, v9
	v_add_f32_e32 v11, 0x3f2aaaaa, v10
	v_sub_f32_e32 v3, v10, v3
	v_sub_f32_e32 v3, v9, v3
	v_add_f32_e32 v9, 0xbf2aaaaa, v11
	v_add_f32_e32 v3, 0x31739010, v3
	v_sub_f32_e32 v9, v10, v9
	v_mul_f32_e32 v12, v2, v8
	v_mul_f32_e32 v13, v3, v9
	v_add_f32_e32 v14, v2, v8
	v_add_f32_e32 v15, v3, v9
	v_fma_f32 v10, v8, v2, -v12
	v_fmac_f32_e32 v10, v8, v7
	v_mov_b32_e32 v13, v15
	v_fmac_f32_e32 v10, v16, v2
	v_add_f32_e32 v8, v12, v10
	v_add_f32_e32 v9, v13, v11
	s_mov_b64 s[12:13], 0
	v_sub_f32_e32 v3, v8, v12
	v_sub_f32_e32 v3, v10, v3
	v_sub_f32_e32 v10, v11, v9
	v_add_f32_e32 v13, v15, v10
	v_cvt_f64_f32_e32 v[14:15], v5
	v_frexp_exp_i32_f64_e32 v5, v[14:15]
	v_subbrev_co_u32_e64 v5, s[0:1], 0, v5, s[0:1]
	v_cvt_f32_i32_e32 v5, v5
	v_mul_f32_e32 v10, v8, v9
	v_mul_f32_e32 v11, v9, v8
	s_mov_b32 s0, 0x3f317218
	v_fma_f32 v12, v8, v9, -v10
	v_fmac_f32_e32 v12, v8, v13
	v_mul_f32_e32 v8, 0x3f317218, v5
	v_fmac_f32_e32 v12, v3, v9
	v_fma_f32 v3, v5, s0, -v8
	v_fmamk_f32 v14, v5, 0xb102e308, v3
	v_ldexp_f32 v15, v2, 1
	v_add_f32_e32 v9, v10, v12
	v_add_f32_e32 v2, v8, v14
	v_add_f32_e32 v3, v9, v15
	v_mov_b32_e32 v16, v9
	v_mov_b32_e32 v17, v3
	v_mov_b32_e32 v11, v15
	v_add_f32_e64 v10, v16, -v10
	v_add_f32_e64 v11, v17, -v11
	v_mov_b32_e32 v13, v9
	v_ldexp_f32 v5, v7, 1
	v_add_f32_e64 v10, v12, -v10
	v_add_f32_e64 v11, v13, -v11
	v_mov_b32_e32 v15, v2
	v_add_f32_e32 v5, v5, v10
	v_add_f32_e32 v9, v5, v11
	v_add_f32_e64 v10, v2, -v8
	v_add_f32_e64 v11, v3, -v9
	v_add_f32_e32 v12, v2, v8
	v_add_f32_e32 v13, v3, v9
	v_mov_b32_e32 v8, v9
	v_mov_b32_e32 v11, v13
	v_add_f32_e64 v16, v14, -v10
	v_add_f32_e64 v17, v15, -v11
	v_add_f32_e32 v10, v14, v10
	v_add_f32_e32 v11, v15, v11
	v_mov_b32_e32 v9, v2
	v_add_f32_e64 v14, v11, -v2
	v_add_f32_e64 v15, v10, -v3
	v_add_f32_e64 v18, v12, -v14
	v_add_f32_e64 v19, v13, -v14
	v_mov_b32_e32 v12, v13
	v_mov_b32_e32 v13, v11
	v_pk_mov_b32 v[14:15], v[2:3], v[14:15] op_sel:[1,0]
	v_mov_b32_e32 v18, v16
	v_add_f32_e64 v12, v12, -v14
	v_add_f32_e64 v13, v13, -v15
	v_mov_b32_e32 v17, v11
	v_add_f32_e64 v2, v8, -v12
	v_add_f32_e64 v3, v9, -v13
	s_mov_b32 s14, 0xfe5163ab
	v_add_f32_e32 v8, v18, v2
	v_add_f32_e32 v9, v19, v3
	s_mov_b32 s15, 0x3c439041
	v_add_f32_e32 v12, v8, v9
	v_add_f32_e32 v13, v9, v8
	s_mov_b32 s33, 0xdb629599
	v_pk_add_f32 v[10:11], v[10:11], v[12:13] op_sel:[1,0] op_sel_hi:[0,1]
	v_mov_b32_e32 v9, v10
	v_add_f32_e64 v14, v8, -v16
	v_add_f32_e64 v15, v9, -v17
	v_mov_b32_e32 v3, v12
	v_sub_f32_e32 v5, v8, v14
	v_add_f32_e64 v2, v2, -v14
	v_add_f32_e64 v3, v3, -v15
	v_sub_f32_e32 v5, v16, v5
	v_add_f32_e32 v2, v2, v5
	v_add_f32_e32 v2, v2, v3
	v_add_f32_e32 v3, v10, v2
	v_sub_f32_e32 v5, v3, v10
	v_sub_f32_e32 v2, v2, v5
	v_mul_f32_e32 v5, v1, v3
	v_fma_f32 v3, v1, v3, -v5
	v_fmac_f32_e32 v3, v1, v2
	v_add_f32_e32 v2, v5, v3
	v_cmp_class_f32_e64 s[0:1], v5, s3
	v_sub_f32_e32 v7, v2, v5
	v_sub_f32_e32 v3, v3, v7
	v_cndmask_b32_e64 v2, v2, v5, s[0:1]
	v_mov_b32_e32 v5, 0x37000000
	v_cmp_eq_f32_e64 s[0:1], s5, v2
	s_waitcnt lgkmcnt(0)
	s_mov_b32 s44, 0xf534ddc0
	s_mov_b32 s45, 0xfc2757d1
	v_cndmask_b32_e64 v5, 0, v5, s[0:1]
	v_sub_f32_e32 v7, v2, v5
	s_mov_b32 s0, 0x3fb8aa3b
	v_mul_f32_e32 v8, 0x3fb8aa3b, v7
	v_fma_f32 v9, v7, s0, -v8
	v_rndne_f32_e32 v10, v8
	v_fmamk_f32 v9, v7, 0x32a5705f, v9
	v_sub_f32_e32 v8, v8, v10
	v_add_f32_e32 v8, v8, v9
	v_exp_f32_e32 v8, v8
	v_cvt_i32_f32_e32 v9, v10
	v_cmp_neq_f32_e64 s[0:1], |v2|, s4
	v_lshrrev_b32_e32 v10, 4, v222
	s_mov_b32 s46, 0x4e441529
	v_cndmask_b32_e64 v2, 0, v3, s[0:1]
	s_mov_b32 s0, 0xc2ce8ed0
	v_ldexp_f32 v3, v8, v9
	v_cmp_ngt_f32_e64 s[0:1], s0, v7
	v_add_f32_e32 v2, v5, v2
	v_mov_b32_e32 v5, 0x7f800000
	v_cndmask_b32_e64 v3, 0, v3, s[0:1]
	v_cmp_nlt_f32_e64 s[0:1], s5, v7
	s_mov_b32 s47, 0xa2f9836e
	s_mov_b32 s58, 0x3fc90fda
	v_cndmask_b32_e64 v3, v5, v3, s[0:1]
	v_fma_f32 v2, v3, v2, v3
	v_cmp_class_f32_e64 s[0:1], v3, s3
	s_mov_b32 s59, 0x3f22f983
	s_mov_b32 s70, 0xbfc90fda
	v_cndmask_b32_e64 v2, v2, v3, s[0:1]
	v_cmp_neq_f32_e64 s[0:1], v1, |v1|
	v_mov_b32_e32 v11, 0xbab64f3b
	s_brev_b32 s71, 1
	v_cndmask_b32_e64 v3, v5, 0, s[0:1]
	v_cndmask_b32_e64 v3, v3, 1.0, vcc
	v_cmp_class_f32_e64 s[0:1], v1, s3
	v_add_u32_e32 v5, 0xfffffe00, v222
	s_brev_b32 s3, 18
	v_cndmask_b32_e64 v1, |v2|, v3, s[0:1]
	v_mov_b32_e32 v3, 0
	v_mov_b32_e32 v7, v3
	v_lshl_add_u64 v[8:9], s[30:31], 0, v[6:7]
	s_mov_b64 s[0:1], 0x2fbc000
	v_lshl_add_u64 v[8:9], v[8:9], 0, s[0:1]
	v_mov_b32_e32 v7, 0x3c0881c4
	s_movk_i32 s72, 0x1f8
	v_mov_b32_e32 v12, 0x7fc00000
	s_mov_b64 s[38:39], 0x1000
	s_movk_i32 s73, 0x5ff
	v_not_b32_e32 v13, 63
	v_not_b32_e32 v14, 31
	s_branch .LBB0_36

; __device__ __forceinline__ unsigned pk2(float lo, float hi) { return f2bf(lo) | (f2bf(hi) << 16); }
; __device__ __forceinline__ void norm_mod_phase(const float* lat, long lat_bs, const float* cx, long ctx_bs, const float* modl, int shoff, int scoff, bf16* XN, int skip_ctx, int gw, int NGW, float* xcopy, const float* part, int nkc, const float* pgate) {
;     ...
;     for (int row = gw; row < MROWS; row += NGW) {
;         const int s = sn; f32x4 v[4]; float ss = 0.f;
; #pragma unroll
;         for (int j = 0; j < 4; ++j) v[j] = vn[j];
;         if (row + NGW < MROWS) { const float* srcn = row_src(row + NGW, lat, lat_bs, cx, ctx_bs, sn); const f32x4* xr = (const f32x4*)srcn + lane;
; #pragma unroll
;             for (int j = 0; j < 4; ++j) vn[j] = xr[64 * j]; }
;         if (skip_ctx && s == 4) continue;
; #pragma unroll
;         for (int j = 0; j < 4; ++j) ss += (v[j].x * v[j].x + v[j].y * v[j].y) + (v[j].z * v[j].z + v[j].w * v[j].w);
;         if (xcopy && s == 4) {
;             const int b_ = row / TPB, cr = b_ * CTXL + (row - b_ * TPB); const f32x4* gp = (const f32x4*)(pgate + 4 * NMOD6) + lane;
;             f32x4 sm[4];
; #pragma unroll
;             for (int j = 0; j < 4; ++j) sm[j] = (f32x4){0.f, 0.f, 0.f, 0.f};
;             for (int kc = 0; kc < nkc; ++kc) { const f32x4* pp = (const f32x4*)(part + ((size_t)kc * 1024 + cr) * DMODEL) + lane;
; #pragma unroll
;                 for (int j = 0; j < 4; ++j) sm[j] += pp[64 * j]; }
;             f32x4* xc = (f32x4*)(xcopy + (size_t)row * DMODEL) + lane; ss = 0.f;
; #pragma unroll
;             for (int j = 0; j < 4; ++j) { v[j] += gp[64 * j] * sm[j]; xc[64 * j] = v[j]; ss += (v[j].x * v[j].x + v[j].y * v[j].y) + (v[j].z * v[j].z + v[j].w * v[j].w); } }
;         const float rstd = 1.0f / sqrtf(wave_sum(ss) * (1.0f / DMODEL) + EPS);
;         const f32x4* sh = (const f32x4*)(modl + s * NMOD6 + shoff) + lane; const f32x4* sc = (const f32x4*)(modl + s * NMOD6 + scoff) + lane;
;         v2u* o8 = (v2u*)(XN + (size_t)row * DMODEL) + lane;
; #pragma unroll
;         for (int j = 0; j < 4; ++j) { const f32x4 a = sh[64 * j], m = sc[64 * j]; const f32x4 y = v[j] * rstd * (m + 1.0f) + a; v2u w; w.x = pk2(y.x, y.y); w.y = pk2(y.z, y.w); o8[64 * j] = w; }
.LBB0_114:
	v_mul_f32_e32 v44, v14, v14
	v_mul_f32_e32 v45, v15, v15
	v_mul_f32_e32 v46, v12, v12
	v_mul_f32_e32 v47, v13, v13
	s_mulk_i32 s4, 0x1800
	v_mov_b32_e32 v48, v46
	v_mov_b32_e32 v49, v45
	v_pk_mov_b32 v[44:45], v[46:47], v[44:45] op_sel:[1,0]
	s_ashr_i32 s5, s4, 31
	v_add_f32_e32 v44, v44, v48
	v_add_f32_e32 v45, v45, v49
	s_lshl_b64 s[4:5], s[4:5], 2
	v_add_f32_e32 v52, v44, v44
	v_add_f32_e32 v53, v44, v45
	v_mul_f32_e32 v44, v10, v10
	v_mul_f32_e32 v45, v11, v11
	v_mul_f32_e32 v46, v8, v8
	v_mul_f32_e32 v47, v9, v9
	s_add_u32 s48, s68, s4
	v_mov_b32_e32 v48, v46
	v_mov_b32_e32 v49, v45
	v_pk_mov_b32 v[44:45], v[46:47], v[44:45] op_sel:[1,0]
	s_addc_u32 s49, s69, s5
	v_add_f32_e32 v44, v44, v48
	v_add_f32_e32 v45, v45, v49
	v_lshl_add_u64 v[60:61], s[48:49], 0, v[32:33]
	v_add_f32_e32 v54, v44, v44
	v_add_f32_e32 v55, v44, v45
	v_mul_f32_e32 v44, v4, v4
	v_add_co_u32_e32 v48, vcc, s1, v60
	v_fma_f32 v56, v4, v4, v44
	v_fma_f32 v57, v5, v5, v44
	v_mul_f32_e32 v44, v6, v6
	v_addc_co_u32_e32 v49, vcc, 0, v61, vcc
	v_fma_f32 v58, v6, v6, v44
	v_fma_f32 v59, v7, v7, v44
	global_load_dwordx4 v[44:47], v32, s[48:49]
	global_load_dwordx4 v[116:119], v[48:49], off offset:1024
	global_load_dwordx4 v[120:123], v32, s[48:49] offset:1024
	global_load_dwordx4 v[100:103], v[48:49], off offset:2048
	global_load_dwordx4 v[104:107], v32, s[48:49] offset:2048
	global_load_dwordx4 v[108:111], v[48:49], off offset:3072
	global_load_dwordx4 v[112:115], v32, s[48:49] offset:3072
	global_load_dwordx4 v[48:51], v[48:49], off
	s_and_b64 vcc, exec, s[46:47]
	s_cbranch_vccnz .Lnorm1_nopf
	global_load_dwordx4 v[16:19], v32, s[100:101]
	global_load_dwordx4 v[20:23], v32, s[100:101] offset:1024
	global_load_dwordx4 v[24:27], v32, s[100:101] offset:2048
	global_load_dwordx4 v[28:31], v32, s[100:101] offset:3072
	s_waitcnt vmcnt(4)
	s_branch .Lnorm1_join

; __device__ __forceinline__ unsigned pk2(float lo, float hi) { return f2bf(lo) | (f2bf(hi) << 16); }
; __device__ __forceinline__ float wave_sum(float v) {
; #pragma unroll
;     for (int o = 1; o < 64; o <<= 1) v += __shfl_xor(v, o);
;     return v;
; __device__ __forceinline__ void norm_mod_phase(const float* lat, long lat_bs, const float* cx, long ctx_bs, const float* modl, int shoff, int scoff, bf16* XN, int skip_ctx, int gw, int NGW, float* xcopy, const float* part, int nkc, const float* pgate) {
;     ...
;         for (int j = 0; j < 4; ++j) ss += (v[j].x * v[j].x + v[j].y * v[j].y) + (v[j].z * v[j].z + v[j].w * v[j].w);
;         if (xcopy && s == 4) {
;             const int b_ = row / TPB, cr = b_ * CTXL + (row - b_ * TPB); const f32x4* gp = (const f32x4*)(pgate + 4 * NMOD6) + lane;
;             f32x4 sm[4];
; #pragma unroll
;             for (int j = 0; j < 4; ++j) sm[j] = (f32x4){0.f, 0.f, 0.f, 0.f};
;             for (int kc = 0; kc < nkc; ++kc) { const f32x4* pp = (const f32x4*)(part + ((size_t)kc * 1024 + cr) * DMODEL) + lane;
; #pragma unroll
;                 for (int j = 0; j < 4; ++j) sm[j] += pp[64 * j]; }
;             f32x4* xc = (f32x4*)(xcopy + (size_t)row * DMODEL) + lane; ss = 0.f;
; #pragma unroll
;             for (int j = 0; j < 4; ++j) { v[j] += gp[64 * j] * sm[j]; xc[64 * j] = v[j]; ss += (v[j].x * v[j].x + v[j].y * v[j].y) + (v[j].z * v[j].z + v[j].w * v[j].w); } }
;         const float rstd = 1.0f / sqrtf(wave_sum(ss) * (1.0f / DMODEL) + EPS);
;         const f32x4* sh = (const f32x4*)(modl + s * NMOD6 + shoff) + lane; const f32x4* sc = (const f32x4*)(modl + s * NMOD6 + scoff) + lane;
;         v2u* o8 = (v2u*)(XN + (size_t)row * DMODEL) + lane;
; #pragma unroll
;         for (int j = 0; j < 4; ++j) { const f32x4 a = sh[64 * j], m = sc[64 * j]; const f32x4 y = v[j] * rstd * (m + 1.0f) + a; v2u w; w.x = pk2(y.x, y.y); w.y = pk2(y.z, y.w); o8[64 * j] = w; }
.Lnorm1_join:
	v_mul_f32_e32 v56, v0, v0
	v_mul_f32_e32 v58, v1, v1
	v_mul_f32_e32 v54, v2, v2
	v_mul_f32_e32 v52, v3, v3
	v_add_f32_e32 v56, v56, v58
	v_add_f32_e32 v57, v57, v59
	v_add_f32_e32 v52, v54, v52
	v_add_f32_e32 v53, v55, v53
	v_add_f32_e32 v48, 1.0, v48
	v_add_f32_e32 v49, 1.0, v49
	v_add_f32_e32 v52, v56, v52
	v_add_f32_e32 v53, v57, v53
	v_add_f32_e32 v50, 1.0, v50
	v_add_f32_e32 v51, 1.0, v51
	v_add_f32_e32 v52, v52, v53
	ds_bpermute_b32 v53, v38, v52
	s_waitcnt lgkmcnt(0)
	v_add_f32_e32 v52, v52, v53
	ds_bpermute_b32 v53, v39, v52
	s_waitcnt lgkmcnt(0)
	v_add_f32_e32 v52, v52, v53
	ds_bpermute_b32 v53, v40, v52
	s_waitcnt lgkmcnt(0)
	v_add_f32_e32 v52, v52, v53
	ds_bpermute_b32 v53, v41, v52
	s_waitcnt lgkmcnt(0)
	v_add_f32_e32 v52, v52, v53
	ds_bpermute_b32 v53, v42, v52
	s_waitcnt lgkmcnt(0)
	v_add_f32_e32 v52, v52, v53
	ds_bpermute_b32 v53, v43, v52
	s_waitcnt lgkmcnt(0)
	v_add_f32_e32 v52, v52, v53
	v_fmamk_f32 v52, v52, 0x3a800000, v36
	v_mul_f32_e32 v53, 0x4f800000, v52
	v_cmp_gt_f32_e32 vcc, s0, v52
	s_nop 1
	v_cndmask_b32_e32 v52, v52, v53, vcc
	v_sqrt_f32_e32 v53, v52
	s_nop 0
	v_add_u32_e32 v54, -1, v53
	v_add_u32_e32 v55, 1, v53
	v_fma_f32 v56, -v54, v53, v52
	v_fma_f32 v57, -v55, v53, v52
	v_cmp_ge_f32_e64 s[4:5], 0, v56
	s_nop 1
	v_cndmask_b32_e64 v53, v53, v54, s[4:5]
	v_cmp_lt_f32_e64 s[4:5], 0, v57
	s_nop 1
	v_cndmask_b32_e64 v53, v53, v55, s[4:5]
	v_mul_f32_e32 v54, 0x37800000, v53
	v_cndmask_b32_e32 v53, v53, v54, vcc
	v_cmp_class_f32_e32 vcc, v52, v37
	s_nop 1
	v_cndmask_b32_e32 v54, v53, v52, vcc
	v_div_scale_f32 v55, s[4:5], v54, v54, 1.0
	v_rcp_f32_e32 v56, v55
	v_div_scale_f32 v57, vcc, 1.0, v54, 1.0
	v_lshl_add_u64 v[52:53], v[60:61], 0, s[10:11]
	v_fma_f32 v58, -v55, v56, 1.0
	v_fmac_f32_e32 v56, v58, v56
	v_mul_f32_e32 v58, v57, v56
	v_fma_f32 v59, -v55, v58, v57
	v_fmac_f32_e32 v58, v59, v56
	v_fma_f32 v55, -v55, v58, v57
	v_div_fmas_f32 v55, v55, v56, v58
	v_div_fixup_f32 v54, v55, v54, 1.0
	v_mul_f32_e32 v12, v12, v54
	v_mul_f32_e32 v13, v13, v54
	v_mul_f32_e32 v14, v14, v54
	v_mul_f32_e32 v15, v15, v54
	v_fma_f32 v12, v48, v12, v44
	v_fma_f32 v13, v49, v13, v45
	v_fma_f32 v14, v50, v14, v46
	v_fma_f32 v15, v51, v15, v47
	v_bfe_u32 v44, v12, 16, 1
	v_bfe_u32 v45, v13, 16, 1
	v_add3_u32 v12, v12, v44, s3
	v_lshrrev_b32_e32 v12, 16, v12
	v_add3_u32 v13, v13, v45, s3
	v_and_or_b32 v12, v13, s14, v12
	v_bfe_u32 v13, v14, 16, 1
	v_add3_u32 v13, v14, v13, s3
	v_bfe_u32 v14, v15, 16, 1
	v_lshrrev_b32_e32 v13, 16, v13
	v_add3_u32 v14, v15, v14, s3
	v_and_or_b32 v13, v14, s14, v13
	global_store_dwordx2 v[34:35], v[12:13], off
	v_mul_f32_e32 v8, v8, v54
	v_mul_f32_e32 v9, v9, v54
	v_mul_f32_e32 v10, v10, v54
	v_mul_f32_e32 v11, v11, v54
	v_mul_f32_e32 v4, v4, v54
	v_mul_f32_e32 v5, v5, v54
	v_mul_f32_e32 v6, v6, v54
	v_mul_f32_e32 v7, v7, v54
	s_andn2_b64 vcc, exec, s[46:47]
	s_mov_b32 s4, s44
	v_add_f32_e32 v14, 1.0, v118
	v_add_f32_e32 v15, 1.0, v119
	v_add_f32_e32 v12, 1.0, v116
	v_add_f32_e32 v13, 1.0, v117
	v_fma_f32 v10, v14, v10, v122
	v_fma_f32 v11, v15, v11, v123
	v_fma_f32 v8, v12, v8, v120
	v_fma_f32 v9, v13, v9, v121
	v_bfe_u32 v14, v10, 16, 1
	v_bfe_u32 v12, v8, 16, 1
	v_bfe_u32 v13, v9, 16, 1
	v_bfe_u32 v15, v11, 16, 1
	v_add3_u32 v8, v8, v12, s3
	v_add3_u32 v10, v10, v14, s3
	v_add3_u32 v9, v9, v13, s3
	v_add3_u32 v11, v11, v15, s3
	v_lshrrev_b32_e32 v8, 16, v8
	v_lshrrev_b32_e32 v10, 16, v10
	v_and_or_b32 v8, v9, s14, v8
	v_and_or_b32 v9, v11, s14, v10
	global_store_dwordx2 v[34:35], v[8:9], off offset:512
	s_nop 0
	v_add_f32_e32 v10, 1.0, v102
	v_add_f32_e32 v11, 1.0, v103
	v_add_f32_e32 v8, 1.0, v100
	v_add_f32_e32 v9, 1.0, v101
	v_fma_f32 v6, v6, v10, v106
	v_fma_f32 v7, v7, v11, v107
	v_fma_f32 v4, v4, v8, v104
	v_fma_f32 v5, v5, v9, v105
	v_bfe_u32 v10, v6, 16, 1
	v_bfe_u32 v8, v4, 16, 1
	v_bfe_u32 v9, v5, 16, 1
	v_bfe_u32 v11, v7, 16, 1
	v_add3_u32 v4, v4, v8, s3
	v_add3_u32 v6, v6, v10, s3
	v_add3_u32 v5, v5, v9, s3
	v_add3_u32 v7, v7, v11, s3
	v_lshrrev_b32_e32 v4, 16, v4
	v_lshrrev_b32_e32 v6, 16, v6
	v_and_or_b32 v4, v5, s14, v4
	v_and_or_b32 v5, v7, s14, v6
	global_store_dwordx2 v[34:35], v[4:5], off offset:1024
	v_mul_f32_e32 v52, v0, v54
	v_mul_f32_e32 v53, v1, v54
	v_mul_f32_e32 v55, v3, v54
	v_mul_f32_e32 v54, v2, v54
	s_waitcnt vmcnt(3)
	v_mov_b64_e32 v[0:1], v[28:29]
	v_mov_b64_e32 v[4:5], v[24:25]
	v_mov_b64_e32 v[8:9], v[20:21]
	v_mov_b64_e32 v[12:13], v[16:17]
	v_mov_b64_e32 v[2:3], v[30:31]
	v_mov_b64_e32 v[6:7], v[26:27]
	v_mov_b64_e32 v[10:11], v[22:23]
	v_mov_b64_e32 v[14:15], v[18:19]
	v_add_f32_e32 v46, 1.0, v110
	v_add_f32_e32 v47, 1.0, v111
	v_add_f32_e32 v44, 1.0, v108
	v_add_f32_e32 v45, 1.0, v109
	v_fma_f32 v46, v54, v46, v114
	v_fma_f32 v47, v55, v47, v115
	v_fma_f32 v44, v52, v44, v112
	v_fma_f32 v45, v53, v45, v113
	v_bfe_u32 v50, v46, 16, 1
	v_bfe_u32 v48, v44, 16, 1
	v_bfe_u32 v49, v45, 16, 1
	v_bfe_u32 v51, v47, 16, 1
	v_add3_u32 v44, v44, v48, s3
	v_add3_u32 v46, v46, v50, s3
	v_add3_u32 v45, v45, v49, s3
	v_add3_u32 v47, v47, v51, s3
	v_lshrrev_b32_e32 v44, 16, v44
	v_lshrrev_b32_e32 v46, 16, v46
	v_and_or_b32 v44, v45, s14, v44
	v_and_or_b32 v45, v47, s14, v46
	global_store_dwordx2 v[34:35], v[44:45], off offset:1536
	v_lshl_add_u64 v[34:35], v[34:35], 0, s[12:13]
	s_cbranch_vccz .LBB0_120

; __device__ __forceinline__ unsigned cvt_pk_bf16(float lo, float hi) { unsigned r; asm volatile("v_cvt_pk_bf16_f32 %0, %1, %2" : "=v"(r) : "v"(lo), "v"(hi)); return r; }
;     __device__ __forceinline__ void operator()(const f32x4 (&acc)[2][2][4][2], const Unit& u, int wr, int wc, int fr, int fq) const {
;         const int row0 = u.pm * BM + wr * 64 + fr; int colt = u.pn * BM; bf16_t* base = O;
;         float sc = 1.f; if (split_cols) { const int t = colt / split_cols; base += (size_t)t * split_stride; colt -= t * split_cols; if (t == 0) sc = scale0; }
;         const int col0 = colt + wc * 32 + 8 * fq, bcol0 = u.pn * BM + wc * 32 + 8 * fq;
;         f32x4 bv[2][2];
; #pragma unroll
;         for (int bj = 0; bj < 2; ++bj)
; #pragma unroll
;             for (int n = 0; n < 2; ++n) bv[bj][n] = bias ? *(const f32x4*)(bias + bcol0 + bj * HALF + 4 * n) : (f32x4){0.f, 0.f, 0.f, 0.f};
; #pragma unroll
;         for (int ai = 0; ai < 2; ++ai)
; #pragma unroll
;             for (int m = 0; m < 4; ++m) { bf16_t* rowp = base + (size_t)(row0 + ai * HALF + m * 16) * ldc + col0;
; #pragma unroll
;                 for (int bj = 0; bj < 2; ++bj) { f32x4 v0 = acc[ai][bj][m][0] + bv[bj][0], v1 = acc[ai][bj][m][1] + bv[bj][1];
;                     if (ACT == 1) { f32x2 a = gelu_pk((f32x2){v0[0], v0[1]}), b = gelu_pk((f32x2){v0[2], v0[3]}), c = gelu_pk((f32x2){v1[0], v1[1]}), d = gelu_pk((f32x2){v1[2], v1[3]});
;                         v0 = (f32x4){a.x, a.y, b.x, b.y}; v1 = (f32x4){c.x, c.y, d.x, d.y}; }
;                     v0 = v0 * sc; v1 = v1 * sc; u32x4 w; w.x = cvt_pk_bf16(v0[0], v0[1]); w.y = cvt_pk_bf16(v0[2], v0[3]); w.z = cvt_pk_bf16(v1[0], v1[1]); w.w = cvt_pk_bf16(v1[2], v1[3]);
;                     *(u32x4*)(rowp + bj * HALF) = w; } }
;     }
.LBB0_192:
	s_lshr_b32 s51, s82, 31
	s_add_i32 s51, s82, s51
	s_ashr_i32 s58, s51, 1
	s_ashr_i32 s59, s58, 31
	s_lshl_b32 s49, s82, 8
	s_lshl_b64 s[64:65], s[58:59], 10
	s_add_u32 s64, s44, s64
	s_addc_u32 s65, s45, s65
	s_lshl_b32 s51, s58, 9
	s_sub_i32 s49, s49, s51
	s_add_i32 s51, s82, 1
	s_cmp_lt_u32 s51, 3
	v_or_b32_e32 v146, s49, v149
	s_cselect_b64 vcc, -1, 0
	v_ashrrev_i32_e32 v147, 31, v146
	v_cndmask_b32_e32 v144, 1.0, v166, vcc
	v_lshl_add_u32 v167, s56, 8, v145
	v_lshl_add_u64 v[146:147], v[146:147], 1, s[64:65]
	v_add_f32_e32 v126, 0, v126
	v_add_f32_e32 v127, 0, v127
	v_add_f32_e32 v124, 0, v124
	v_add_f32_e32 v125, 0, v125
	v_add_f32_e32 v122, 0, v122
	v_add_f32_e32 v123, 0, v123
	v_add_f32_e32 v120, 0, v120
	v_add_f32_e32 v121, 0, v121
	v_mad_i64_i32 v[168:169], s[58:59], v167, s81, v[146:147]
	v_mul_f32_e32 v126, v144, v126
	v_mul_f32_e32 v127, v144, v127
	v_mul_f32_e32 v124, v144, v124
	v_mul_f32_e32 v125, v144, v125
	v_mul_f32_e32 v170, v144, v122
	v_mul_f32_e32 v171, v144, v123
	v_mul_f32_e32 v122, v144, v120
	v_mul_f32_e32 v123, v144, v121
	v_cvt_pk_bf16_f32 v120, v124, v125
	v_cvt_pk_bf16_f32 v121, v126, v127
	v_add_f32_e32 v110, 0, v110
	v_add_f32_e32 v111, 0, v111
	v_add_f32_e32 v108, 0, v108
	v_add_f32_e32 v109, 0, v109
	v_cvt_pk_bf16_f32 v122, v122, v123
	v_cvt_pk_bf16_f32 v123, v170, v171
	global_store_dwordx4 v[168:169], v[120:123], off
	v_add_f32_e32 v118, 0, v118
	v_add_f32_e32 v119, 0, v119
	v_add_f32_e32 v116, 0, v116
	v_add_f32_e32 v117, 0, v117
	v_mul_f32_e32 v120, v144, v110
	v_mul_f32_e32 v121, v144, v111
	v_mul_f32_e32 v110, v144, v108
	v_mul_f32_e32 v111, v144, v109
	v_mul_f32_e32 v118, v144, v118
	v_mul_f32_e32 v119, v144, v119
	v_mul_f32_e32 v116, v144, v116
	v_mul_f32_e32 v117, v144, v117
	v_cvt_pk_bf16_f32 v108, v116, v117
	v_cvt_pk_bf16_f32 v109, v118, v119
	v_cvt_pk_bf16_f32 v110, v110, v111
	v_cvt_pk_bf16_f32 v111, v120, v121
	global_store_dwordx4 v[168:169], v[108:111], off offset:256
	v_add_f32_e32 v112, 0, v112
	v_add_f32_e32 v113, 0, v113
	v_add_f32_e32 v106, 0, v106
	v_add_f32_e32 v107, 0, v107
	v_or_b32_e32 v108, 16, v167
	v_add_f32_e32 v110, 0, v114
	v_add_f32_e32 v111, 0, v115
	v_add_f32_e32 v104, 0, v104
	v_add_f32_e32 v105, 0, v105
	v_mad_i64_i32 v[108:109], s[58:59], v108, s81, v[146:147]
	v_mul_f32_e32 v110, v144, v110
	v_mul_f32_e32 v111, v144, v111
	v_mul_f32_e32 v112, v144, v112
	v_mul_f32_e32 v113, v144, v113
	v_mul_f32_e32 v114, v144, v106
	v_mul_f32_e32 v115, v144, v107
	v_mul_f32_e32 v106, v144, v104
	v_mul_f32_e32 v107, v144, v105
	v_cvt_pk_bf16_f32 v104, v112, v113
	v_cvt_pk_bf16_f32 v105, v110, v111
	v_add_f32_e32 v94, 0, v94
	v_add_f32_e32 v95, 0, v95
	v_add_f32_e32 v92, 0, v92
	v_add_f32_e32 v93, 0, v93
	v_cvt_pk_bf16_f32 v106, v106, v107
	v_cvt_pk_bf16_f32 v107, v114, v115
	global_store_dwordx4 v[108:109], v[104:107], off
	v_add_f32_e32 v102, 0, v102
	v_add_f32_e32 v103, 0, v103
	v_add_f32_e32 v100, 0, v100
	v_add_f32_e32 v101, 0, v101
	v_mul_f32_e32 v104, v144, v94
	v_mul_f32_e32 v105, v144, v95
	v_mul_f32_e32 v94, v144, v92
	v_mul_f32_e32 v95, v144, v93
	v_mul_f32_e32 v102, v144, v102
	v_mul_f32_e32 v103, v144, v103
	v_mul_f32_e32 v100, v144, v100
	v_mul_f32_e32 v101, v144, v101
	v_cvt_pk_bf16_f32 v92, v100, v101
	v_cvt_pk_bf16_f32 v93, v102, v103
	v_cvt_pk_bf16_f32 v94, v94, v95
	v_cvt_pk_bf16_f32 v95, v104, v105
	global_store_dwordx4 v[108:109], v[92:95], off offset:256
	v_add_f32_e32 v96, 0, v96
	v_add_f32_e32 v97, 0, v97
	v_add_f32_e32 v90, 0, v90
	v_add_f32_e32 v91, 0, v91
	v_or_b32_e32 v92, 32, v167
	v_add_f32_e32 v94, 0, v98
	v_add_f32_e32 v95, 0, v99
	v_add_f32_e32 v88, 0, v88
	v_add_f32_e32 v89, 0, v89
	v_mad_i64_i32 v[92:93], s[58:59], v92, s81, v[146:147]
	v_mul_f32_e32 v94, v144, v94
	v_mul_f32_e32 v95, v144, v95
	v_mul_f32_e32 v96, v144, v96
	v_mul_f32_e32 v97, v144, v97
	v_mul_f32_e32 v98, v144, v90
	v_mul_f32_e32 v99, v144, v91
	v_mul_f32_e32 v90, v144, v88
	v_mul_f32_e32 v91, v144, v89
	v_cvt_pk_bf16_f32 v88, v96, v97
	v_cvt_pk_bf16_f32 v89, v94, v95
	v_add_f32_e32 v78, 0, v78
	v_add_f32_e32 v79, 0, v79
	v_add_f32_e32 v76, 0, v76
	v_add_f32_e32 v77, 0, v77
	v_cvt_pk_bf16_f32 v90, v90, v91
	v_cvt_pk_bf16_f32 v91, v98, v99
	global_store_dwordx4 v[92:93], v[88:91], off
	v_add_f32_e32 v86, 0, v86
	v_add_f32_e32 v87, 0, v87
	v_add_f32_e32 v84, 0, v84
	v_add_f32_e32 v85, 0, v85
	v_mul_f32_e32 v88, v144, v78
	v_mul_f32_e32 v89, v144, v79
	v_mul_f32_e32 v78, v144, v76
	v_mul_f32_e32 v79, v144, v77
	v_mul_f32_e32 v86, v144, v86
	v_mul_f32_e32 v87, v144, v87
	v_mul_f32_e32 v84, v144, v84
	v_mul_f32_e32 v85, v144, v85
	v_cvt_pk_bf16_f32 v76, v84, v85
	v_cvt_pk_bf16_f32 v77, v86, v87
	v_cvt_pk_bf16_f32 v78, v78, v79
	v_cvt_pk_bf16_f32 v79, v88, v89
	global_store_dwordx4 v[92:93], v[76:79], off offset:256
	v_add_f32_e32 v80, 0, v80
	v_add_f32_e32 v81, 0, v81
	v_add_f32_e32 v74, 0, v74
	v_add_f32_e32 v75, 0, v75
	v_or_b32_e32 v76, 48, v167
	v_add_f32_e32 v78, 0, v82
	v_add_f32_e32 v79, 0, v83
	v_add_f32_e32 v72, 0, v72
	v_add_f32_e32 v73, 0, v73
	v_mad_i64_i32 v[76:77], s[58:59], v76, s81, v[146:147]
	v_mul_f32_e32 v78, v144, v78
	v_mul_f32_e32 v79, v144, v79
	v_mul_f32_e32 v80, v144, v80
	v_mul_f32_e32 v81, v144, v81
	v_mul_f32_e32 v82, v144, v74
	v_mul_f32_e32 v83, v144, v75
	v_mul_f32_e32 v74, v144, v72
	v_mul_f32_e32 v75, v144, v73
	v_cvt_pk_bf16_f32 v72, v80, v81
	v_cvt_pk_bf16_f32 v73, v78, v79
	v_add_f32_e32 v68, 0, v68
	v_add_f32_e32 v69, 0, v69
	v_add_f32_e32 v66, 0, v66
	v_add_f32_e32 v67, 0, v67
	v_add_f32_e32 v64, 0, v64
	v_add_f32_e32 v65, 0, v65
	v_cvt_pk_bf16_f32 v74, v74, v75
	v_cvt_pk_bf16_f32 v75, v82, v83
	global_store_dwordx4 v[76:77], v[72:75], off
; __device__ __forceinline__ unsigned cvt_pk_bf16(float lo, float hi) { unsigned r; asm volatile("v_cvt_pk_bf16_f32 %0, %1, %2" : "=v"(r) : "v"(lo), "v"(hi)); return r; }
;     __device__ __forceinline__ void operator()(const f32x4 (&acc)[2][2][4][2], const Unit& u, int wr, int wc, int fr, int fq) const {
;         const int row0 = u.pm * BM + wr * 64 + fr; int colt = u.pn * BM; bf16_t* base = O;
;         float sc = 1.f; if (split_cols) { const int t = colt / split_cols; base += (size_t)t * split_stride; colt -= t * split_cols; if (t == 0) sc = scale0; }
;         const int col0 = colt + wc * 32 + 8 * fq, bcol0 = u.pn * BM + wc * 32 + 8 * fq;
;         f32x4 bv[2][2];
; #pragma unroll
;         for (int bj = 0; bj < 2; ++bj)
; #pragma unroll
;             for (int n = 0; n < 2; ++n) bv[bj][n] = bias ? *(const f32x4*)(bias + bcol0 + bj * HALF + 4 * n) : (f32x4){0.f, 0.f, 0.f, 0.f};
; #pragma unroll
;         for (int ai = 0; ai < 2; ++ai)
; #pragma unroll
;             for (int m = 0; m < 4; ++m) { bf16_t* rowp = base + (size_t)(row0 + ai * HALF + m * 16) * ldc + col0;
; #pragma unroll
;                 for (int bj = 0; bj < 2; ++bj) { f32x4 v0 = acc[ai][bj][m][0] + bv[bj][0], v1 = acc[ai][bj][m][1] + bv[bj][1];
;                     if (ACT == 1) { f32x2 a = gelu_pk((f32x2){v0[0], v0[1]}), b = gelu_pk((f32x2){v0[2], v0[3]}), c = gelu_pk((f32x2){v1[0], v1[1]}), d = gelu_pk((f32x2){v1[2], v1[3]});
;                         v0 = (f32x4){a.x, a.y, b.x, b.y}; v1 = (f32x4){c.x, c.y, d.x, d.y}; }
;                     v0 = v0 * sc; v1 = v1 * sc; u32x4 w; w.x = cvt_pk_bf16(v0[0], v0[1]); w.y = cvt_pk_bf16(v0[2], v0[3]); w.z = cvt_pk_bf16(v1[0], v1[1]); w.w = cvt_pk_bf16(v1[2], v1[3]);
;                     *(u32x4*)(rowp + bj * HALF) = w; } }
;     }
	v_add_f32_e32 v70, 0, v70
	v_add_f32_e32 v71, 0, v71
	v_mul_f32_e32 v68, v144, v68
	v_mul_f32_e32 v69, v144, v69
	v_mul_f32_e32 v72, v144, v66
	v_mul_f32_e32 v73, v144, v67
	v_mul_f32_e32 v66, v144, v64
	v_mul_f32_e32 v67, v144, v65
	v_cvt_pk_bf16_f32 v64, v68, v69
	v_mul_f32_e32 v70, v144, v70
	v_mul_f32_e32 v71, v144, v71
	v_cvt_pk_bf16_f32 v65, v70, v71
	v_cvt_pk_bf16_f32 v66, v66, v67
	v_cvt_pk_bf16_f32 v67, v72, v73
	global_store_dwordx4 v[76:77], v[64:67], off offset:256
	v_add_f32_e32 v62, 0, v62
	v_add_f32_e32 v63, 0, v63
	v_add_f32_e32 v60, 0, v60
	v_add_f32_e32 v61, 0, v61
	v_add_u32_e32 v64, 0x80, v167
	v_add_f32_e32 v58, 0, v58
	v_add_f32_e32 v59, 0, v59
	v_add_f32_e32 v56, 0, v56
	v_add_f32_e32 v57, 0, v57
	v_mad_i64_i32 v[64:65], s[58:59], v64, s81, v[146:147]
	v_mul_f32_e32 v62, v144, v62
	v_mul_f32_e32 v63, v144, v63
	v_mul_f32_e32 v60, v144, v60
	v_mul_f32_e32 v61, v144, v61
	v_mul_f32_e32 v66, v144, v58
	v_mul_f32_e32 v67, v144, v59
	v_mul_f32_e32 v58, v144, v56
	v_mul_f32_e32 v59, v144, v57
	v_cvt_pk_bf16_f32 v56, v60, v61
	v_cvt_pk_bf16_f32 v57, v62, v63
	v_add_f32_e32 v46, 0, v46
	v_add_f32_e32 v47, 0, v47
	v_add_f32_e32 v44, 0, v44
	v_add_f32_e32 v45, 0, v45
	v_cvt_pk_bf16_f32 v58, v58, v59
	v_cvt_pk_bf16_f32 v59, v66, v67
	global_store_dwordx4 v[64:65], v[56:59], off
	v_add_f32_e32 v54, 0, v54
	v_add_f32_e32 v55, 0, v55
	v_add_f32_e32 v52, 0, v52
	v_add_f32_e32 v53, 0, v53
	v_mul_f32_e32 v56, v144, v46
	v_mul_f32_e32 v57, v144, v47
	v_mul_f32_e32 v46, v144, v44
	v_mul_f32_e32 v47, v144, v45
	v_mul_f32_e32 v54, v144, v54
	v_mul_f32_e32 v55, v144, v55
	v_mul_f32_e32 v52, v144, v52
	v_mul_f32_e32 v53, v144, v53
	v_cvt_pk_bf16_f32 v44, v52, v53
	v_cvt_pk_bf16_f32 v45, v54, v55
	v_cvt_pk_bf16_f32 v46, v46, v47
	v_cvt_pk_bf16_f32 v47, v56, v57
	global_store_dwordx4 v[64:65], v[44:47], off offset:256
	v_add_f32_e32 v48, 0, v48
	v_add_f32_e32 v49, 0, v49
	v_add_f32_e32 v42, 0, v42
	v_add_f32_e32 v43, 0, v43
	v_add_u32_e32 v44, 0x90, v167
	v_add_f32_e32 v46, 0, v50
	v_add_f32_e32 v47, 0, v51
	v_add_f32_e32 v40, 0, v40
	v_add_f32_e32 v41, 0, v41
	v_mad_i64_i32 v[44:45], s[58:59], v44, s81, v[146:147]
	v_mul_f32_e32 v46, v144, v46
	v_mul_f32_e32 v47, v144, v47
	v_mul_f32_e32 v48, v144, v48
	v_mul_f32_e32 v49, v144, v49
	v_mul_f32_e32 v50, v144, v42
	v_mul_f32_e32 v51, v144, v43
	v_mul_f32_e32 v42, v144, v40
	v_mul_f32_e32 v43, v144, v41
	v_cvt_pk_bf16_f32 v40, v48, v49
	v_cvt_pk_bf16_f32 v41, v46, v47
	v_add_f32_e32 v30, 0, v30
	v_add_f32_e32 v31, 0, v31
	v_add_f32_e32 v28, 0, v28
	v_add_f32_e32 v29, 0, v29
	v_cvt_pk_bf16_f32 v42, v42, v43
	v_cvt_pk_bf16_f32 v43, v50, v51
	global_store_dwordx4 v[44:45], v[40:43], off
	v_add_f32_e32 v38, 0, v38
	v_add_f32_e32 v39, 0, v39
	v_add_f32_e32 v36, 0, v36
	v_add_f32_e32 v37, 0, v37
	v_mul_f32_e32 v40, v144, v30
	v_mul_f32_e32 v41, v144, v31
	v_mul_f32_e32 v30, v144, v28
	v_mul_f32_e32 v31, v144, v29
	v_mul_f32_e32 v38, v144, v38
	v_mul_f32_e32 v39, v144, v39
	v_mul_f32_e32 v36, v144, v36
	v_mul_f32_e32 v37, v144, v37
	v_cvt_pk_bf16_f32 v28, v36, v37
	v_cvt_pk_bf16_f32 v29, v38, v39
	v_cvt_pk_bf16_f32 v30, v30, v31
	v_cvt_pk_bf16_f32 v31, v40, v41
	global_store_dwordx4 v[44:45], v[28:31], off offset:256
	v_add_f32_e32 v32, 0, v32
	v_add_f32_e32 v33, 0, v33
	v_add_f32_e32 v26, 0, v26
	v_add_f32_e32 v27, 0, v27
	v_add_u32_e32 v28, 0xa0, v167
	v_add_f32_e32 v30, 0, v34
	v_add_f32_e32 v31, 0, v35
	v_add_f32_e32 v24, 0, v24
	v_add_f32_e32 v25, 0, v25
	v_mad_i64_i32 v[28:29], s[58:59], v28, s81, v[146:147]
	v_mul_f32_e32 v30, v144, v30
	v_mul_f32_e32 v31, v144, v31
	v_mul_f32_e32 v32, v144, v32
	v_mul_f32_e32 v33, v144, v33
	v_mul_f32_e32 v34, v144, v26
	v_mul_f32_e32 v35, v144, v27
	v_mul_f32_e32 v26, v144, v24
	v_mul_f32_e32 v27, v144, v25
	v_cvt_pk_bf16_f32 v24, v32, v33
	v_cvt_pk_bf16_f32 v25, v30, v31
	v_add_f32_e32 v14, 0, v14
	v_add_f32_e32 v15, 0, v15
	v_add_f32_e32 v12, 0, v12
	v_add_f32_e32 v13, 0, v13
	v_cvt_pk_bf16_f32 v26, v26, v27
	v_cvt_pk_bf16_f32 v27, v34, v35
	global_store_dwordx4 v[28:29], v[24:27], off
	v_add_f32_e32 v22, 0, v22
	v_add_f32_e32 v23, 0, v23
	v_add_f32_e32 v20, 0, v20
	v_add_f32_e32 v21, 0, v21
	v_mul_f32_e32 v24, v144, v14
	v_mul_f32_e32 v25, v144, v15
	v_mul_f32_e32 v14, v144, v12
	v_mul_f32_e32 v15, v144, v13
	v_mul_f32_e32 v22, v144, v22
	v_mul_f32_e32 v23, v144, v23
	v_mul_f32_e32 v20, v144, v20
	v_mul_f32_e32 v21, v144, v21
	v_cvt_pk_bf16_f32 v12, v20, v21
	v_cvt_pk_bf16_f32 v13, v22, v23
	v_cvt_pk_bf16_f32 v14, v14, v15
	v_cvt_pk_bf16_f32 v15, v24, v25
	global_store_dwordx4 v[28:29], v[12:15], off offset:256
	v_add_f32_e32 v16, 0, v16
	v_add_f32_e32 v17, 0, v17
	v_add_f32_e32 v10, 0, v10
	v_add_f32_e32 v11, 0, v11
	v_add_u32_e32 v12, 0xb0, v167
	v_add_f32_e32 v14, 0, v18
	v_add_f32_e32 v15, 0, v19
	v_add_f32_e32 v8, 0, v8
	v_add_f32_e32 v9, 0, v9
	v_mad_i64_i32 v[12:13], s[58:59], v12, s81, v[146:147]
	v_mul_f32_e32 v14, v144, v14
	v_mul_f32_e32 v15, v144, v15
	v_mul_f32_e32 v16, v144, v16
	v_mul_f32_e32 v17, v144, v17
	v_mul_f32_e32 v18, v144, v10
	v_mul_f32_e32 v19, v144, v11
	v_mul_f32_e32 v10, v144, v8
	v_mul_f32_e32 v11, v144, v9
	v_cvt_pk_bf16_f32 v8, v16, v17
	v_cvt_pk_bf16_f32 v9, v14, v15
	v_add_f32_e32 v2, 0, v2
	v_add_f32_e32 v3, 0, v3
	v_add_f32_e32 v0, 0, v0
	v_add_f32_e32 v1, 0, v1
	v_cvt_pk_bf16_f32 v10, v10, v11
	v_cvt_pk_bf16_f32 v11, v18, v19
	global_store_dwordx4 v[12:13], v[8:11], off
	v_add_f32_e32 v6, 0, v6
	v_add_f32_e32 v7, 0, v7
	v_add_f32_e32 v4, 0, v4
	v_add_f32_e32 v5, 0, v5
	v_mul_f32_e32 v8, v144, v2
	v_mul_f32_e32 v9, v144, v3
	v_mul_f32_e32 v2, v144, v0
	v_mul_f32_e32 v3, v144, v1
	s_andn2_b64 vcc, exec, s[4:5]
	s_mov_b64 s[4:5], -1
	v_mul_f32_e32 v6, v144, v6
	v_mul_f32_e32 v7, v144, v7
	v_mul_f32_e32 v4, v144, v4
	v_mul_f32_e32 v5, v144, v5
	v_cvt_pk_bf16_f32 v0, v4, v5
	v_cvt_pk_bf16_f32 v1, v6, v7
	v_cvt_pk_bf16_f32 v2, v2, v3
	v_cvt_pk_bf16_f32 v3, v8, v9
	global_store_dwordx4 v[12:13], v[0:3], off offset:256
	s_cbranch_vccnz .LBB0_181
	s_andn2_b64 vcc, exec, s[8:9]
	s_cbranch_vccnz .LBB0_180
	s_barrier
	s_branch .LBB0_180

.LBB0_370:
	v_max_f32_e32 v34, v82, v82
	v_max_f32_e32 v82, 0, v34
	v_exp_f32_e64 v83, -v82
	v_add_f32_e32 v241, v241, v82
	v_xor_b32_e32 v34, 0x80000000, v241
	v_mov_b32_e32 v35, v34
	v_mov_b32_e32 v36, v34
	v_mov_b32_e32 v37, v34
	v_mov_b32_e32 v38, v34
	v_mov_b32_e32 v39, v34
	v_mov_b32_e32 v40, v34
	v_mov_b32_e32 v41, v34
	v_mov_b32_e32 v42, v34
	v_mov_b32_e32 v43, v34
	v_mov_b32_e32 v44, v34
	v_mov_b32_e32 v45, v34
	v_mov_b32_e32 v46, v34
	v_mov_b32_e32 v47, v34
	v_mov_b32_e32 v48, v34
	v_mov_b32_e32 v49, v34
	s_and_saveexec_b64 s[72:73], s[4:5]
	ds_write_b32 v240, v83
	s_or_b64 exec, exec, s[72:73]
	v_sub_f32_e32 v50, v50, v82
	v_sub_f32_e32 v51, v51, v82
	v_add_f32_e64 v52, v52, -v82
	v_add_f32_e64 v53, v53, -v82
	v_add_f32_e64 v54, v54, -v82
	v_add_f32_e64 v55, v55, -v82
	v_add_f32_e64 v56, v56, -v82
	v_add_f32_e64 v57, v57, -v82
	v_add_f32_e64 v58, v58, -v82
	v_add_f32_e64 v59, v59, -v82
	v_add_f32_e64 v60, v60, -v82
	v_add_f32_e64 v61, v61, -v82
	v_add_f32_e64 v62, v62, -v82
	v_add_f32_e64 v63, v63, -v82
	v_add_f32_e64 v64, v64, -v82
	v_add_f32_e64 v65, v65, -v82
	v_sub_f32_e32 v81, v81, v82
	v_sub_f32_e32 v80, v80, v82
	v_sub_f32_e32 v79, v79, v82
	v_sub_f32_e32 v78, v78, v82
	v_sub_f32_e32 v77, v77, v82
	v_sub_f32_e32 v76, v76, v82
	v_sub_f32_e32 v75, v75, v82
	v_sub_f32_e32 v74, v74, v82
	v_sub_f32_e32 v73, v73, v82
	v_sub_f32_e32 v72, v72, v82
	v_sub_f32_e32 v71, v71, v82
	v_sub_f32_e32 v70, v70, v82
	v_sub_f32_e32 v69, v69, v82
	v_sub_f32_e32 v68, v68, v82
	v_sub_f32_e32 v67, v67, v82
	v_sub_f32_e32 v66, v66, v82
	v_mul_f32_e32 v209, v209, v83
	s_branch .LBB0_356
.LBB0_373:
	v_max_f32_e32 v34, v82, v82
	v_max_f32_e32 v82, 0, v34
	v_exp_f32_e64 v83, -v82
	v_add_f32_e32 v241, v241, v82
	v_xor_b32_e32 v34, 0x80000000, v241
	v_mov_b32_e32 v35, v34
	v_mov_b32_e32 v36, v34
	v_mov_b32_e32 v37, v34
	v_mov_b32_e32 v38, v34
	v_mov_b32_e32 v39, v34
	v_mov_b32_e32 v40, v34
	v_mov_b32_e32 v41, v34
	v_mov_b32_e32 v42, v34
	v_mov_b32_e32 v43, v34
	v_mov_b32_e32 v44, v34
	v_mov_b32_e32 v45, v34
	v_mov_b32_e32 v46, v34
	v_mov_b32_e32 v47, v34
	v_mov_b32_e32 v48, v34
	v_mov_b32_e32 v49, v34
	s_and_saveexec_b64 s[70:71], s[4:5]
	ds_write_b32 v240, v83
	s_or_b64 exec, exec, s[70:71]
	v_sub_f32_e32 v50, v50, v82
	v_sub_f32_e32 v51, v51, v82
	v_add_f32_e64 v52, v52, -v82
	v_add_f32_e64 v53, v53, -v82
	v_add_f32_e64 v54, v54, -v82
	v_add_f32_e64 v55, v55, -v82
	v_add_f32_e64 v56, v56, -v82
	v_add_f32_e64 v57, v57, -v82
	v_add_f32_e64 v58, v58, -v82
	v_add_f32_e64 v59, v59, -v82
	v_add_f32_e64 v60, v60, -v82
	v_add_f32_e64 v61, v61, -v82
	v_add_f32_e64 v62, v62, -v82
	v_add_f32_e64 v63, v63, -v82
	v_add_f32_e64 v64, v64, -v82
	v_add_f32_e64 v65, v65, -v82
	v_sub_f32_e32 v81, v81, v82
	v_sub_f32_e32 v80, v80, v82
	v_sub_f32_e32 v79, v79, v82
	v_sub_f32_e32 v78, v78, v82
	v_sub_f32_e32 v77, v77, v82
	v_sub_f32_e32 v76, v76, v82
	v_sub_f32_e32 v75, v75, v82
	v_sub_f32_e32 v74, v74, v82
	v_sub_f32_e32 v73, v73, v82
	v_sub_f32_e32 v72, v72, v82
	v_sub_f32_e32 v71, v71, v82
	v_sub_f32_e32 v70, v70, v82
	v_sub_f32_e32 v69, v69, v82
	v_sub_f32_e32 v68, v68, v82
	v_sub_f32_e32 v67, v67, v82
	v_sub_f32_e32 v66, v66, v82
	v_mul_f32_e32 v220, v220, v83
	s_branch .LBB0_366

.LBB0_437:
	v_max_f32_e32 v34, v98, v98
	v_max_f32_e32 v98, 0, v34
	v_exp_f32_e64 v99, -v98
	v_add_f32_e32 v241, v241, v98
	v_xor_b32_e32 v34, 0x80000000, v241
	v_mov_b32_e32 v35, v34
	v_mov_b32_e32 v36, v34
	v_mov_b32_e32 v37, v34
	v_mov_b32_e32 v38, v34
	v_mov_b32_e32 v39, v34
	v_mov_b32_e32 v40, v34
	v_mov_b32_e32 v41, v34
	v_mov_b32_e32 v42, v34
	v_mov_b32_e32 v43, v34
	v_mov_b32_e32 v44, v34
	v_mov_b32_e32 v45, v34
	v_mov_b32_e32 v46, v34
	v_mov_b32_e32 v47, v34
	v_mov_b32_e32 v48, v34
	v_mov_b32_e32 v49, v34
	s_and_saveexec_b64 s[66:67], s[4:5]
	ds_write_b32 v240, v99
	s_or_b64 exec, exec, s[66:67]
	v_sub_f32_e32 v50, v50, v98
	v_sub_f32_e32 v51, v51, v98
	v_add_f32_e64 v52, v52, -v98
	v_add_f32_e64 v53, v53, -v98
	v_add_f32_e64 v54, v54, -v98
	v_add_f32_e64 v55, v55, -v98
	v_add_f32_e64 v56, v56, -v98
	v_add_f32_e64 v57, v57, -v98
	v_add_f32_e64 v58, v58, -v98
	v_add_f32_e64 v59, v59, -v98
	v_add_f32_e64 v60, v60, -v98
	v_add_f32_e64 v61, v61, -v98
	v_add_f32_e64 v62, v62, -v98
	v_add_f32_e64 v63, v63, -v98
	v_add_f32_e64 v64, v64, -v98
	v_add_f32_e64 v65, v65, -v98
	v_sub_f32_e32 v81, v81, v98
	v_sub_f32_e32 v80, v80, v98
	v_sub_f32_e32 v79, v79, v98
	v_sub_f32_e32 v78, v78, v98
	v_sub_f32_e32 v77, v77, v98
	v_sub_f32_e32 v76, v76, v98
	v_sub_f32_e32 v75, v75, v98
	v_sub_f32_e32 v74, v74, v98
	v_sub_f32_e32 v73, v73, v98
	v_sub_f32_e32 v72, v72, v98
	v_sub_f32_e32 v71, v71, v98
	v_sub_f32_e32 v70, v70, v98
	v_sub_f32_e32 v69, v69, v98
	v_sub_f32_e32 v68, v68, v98
	v_sub_f32_e32 v67, v67, v98
	v_sub_f32_e32 v66, v66, v98
	v_mul_f32_e32 v220, v220, v99
	s_branch .LBB0_345
.LBB0_440:
	v_max_f32_e32 v34, v82, v82
	v_max_f32_e32 v82, 0, v34
	v_exp_f32_e64 v83, -v82
	v_add_f32_e32 v241, v241, v82
	v_xor_b32_e32 v34, 0x80000000, v241
	v_mov_b32_e32 v35, v34
	v_mov_b32_e32 v36, v34
	v_mov_b32_e32 v37, v34
	v_mov_b32_e32 v38, v34
	v_mov_b32_e32 v39, v34
	v_mov_b32_e32 v40, v34
	v_mov_b32_e32 v41, v34
	v_mov_b32_e32 v42, v34
	v_mov_b32_e32 v43, v34
	v_mov_b32_e32 v44, v34
	v_mov_b32_e32 v45, v34
	v_mov_b32_e32 v46, v34
	v_mov_b32_e32 v47, v34
	v_mov_b32_e32 v48, v34
	v_mov_b32_e32 v49, v34
	s_and_saveexec_b64 s[70:71], s[4:5]
	ds_write_b32 v240, v83
	s_or_b64 exec, exec, s[70:71]
	v_sub_f32_e32 v50, v50, v82
	v_sub_f32_e32 v51, v51, v82
	v_add_f32_e64 v52, v52, -v82
	v_add_f32_e64 v53, v53, -v82
	v_add_f32_e64 v54, v54, -v82
	v_add_f32_e64 v55, v55, -v82
	v_add_f32_e64 v56, v56, -v82
	v_add_f32_e64 v57, v57, -v82
	v_add_f32_e64 v58, v58, -v82
	v_add_f32_e64 v59, v59, -v82
	v_add_f32_e64 v60, v60, -v82
	v_add_f32_e64 v61, v61, -v82
	v_add_f32_e64 v62, v62, -v82
	v_add_f32_e64 v63, v63, -v82
	v_add_f32_e64 v64, v64, -v82
	v_add_f32_e64 v65, v65, -v82
	v_sub_f32_e32 v81, v81, v82
	v_sub_f32_e32 v80, v80, v82
	v_sub_f32_e32 v79, v79, v82
	v_sub_f32_e32 v78, v78, v82
	v_sub_f32_e32 v77, v77, v82
	v_sub_f32_e32 v76, v76, v82
	v_sub_f32_e32 v75, v75, v82
	v_sub_f32_e32 v74, v74, v82
	v_sub_f32_e32 v73, v73, v82
	v_sub_f32_e32 v72, v72, v82
	v_sub_f32_e32 v71, v71, v82
	v_sub_f32_e32 v70, v70, v82
	v_sub_f32_e32 v69, v69, v82
	v_sub_f32_e32 v68, v68, v82
	v_sub_f32_e32 v67, v67, v82
	v_sub_f32_e32 v66, v66, v82
	v_mul_f32_e32 v216, v216, v83
	s_branch .LBB0_384
.LBB0_443:
	v_max_f32_e32 v34, v82, v82
	v_max_f32_e32 v82, 0, v34
	v_exp_f32_e64 v83, -v82
	v_add_f32_e32 v241, v241, v82
	v_xor_b32_e32 v34, 0x80000000, v241
	v_mov_b32_e32 v35, v34
	v_mov_b32_e32 v36, v34
	v_mov_b32_e32 v37, v34
	v_mov_b32_e32 v38, v34
	v_mov_b32_e32 v39, v34
	v_mov_b32_e32 v40, v34
	v_mov_b32_e32 v41, v34
	v_mov_b32_e32 v42, v34
	v_mov_b32_e32 v43, v34
	v_mov_b32_e32 v44, v34
	v_mov_b32_e32 v45, v34
	v_mov_b32_e32 v46, v34
	v_mov_b32_e32 v47, v34
	v_mov_b32_e32 v48, v34
	v_mov_b32_e32 v49, v34
	s_and_saveexec_b64 s[70:71], s[4:5]
	ds_write_b32 v240, v83
	s_or_b64 exec, exec, s[70:71]
	v_sub_f32_e32 v50, v50, v82
	v_sub_f32_e32 v51, v51, v82
	v_add_f32_e64 v52, v52, -v82
	v_add_f32_e64 v53, v53, -v82
	v_add_f32_e64 v54, v54, -v82
	v_add_f32_e64 v55, v55, -v82
	v_add_f32_e64 v56, v56, -v82
	v_add_f32_e64 v57, v57, -v82
	v_add_f32_e64 v58, v58, -v82
	v_add_f32_e64 v59, v59, -v82
	v_add_f32_e64 v60, v60, -v82
	v_add_f32_e64 v61, v61, -v82
	v_add_f32_e64 v62, v62, -v82
	v_add_f32_e64 v63, v63, -v82
	v_add_f32_e64 v64, v64, -v82
	v_add_f32_e64 v65, v65, -v82
	v_sub_f32_e32 v81, v81, v82
	v_sub_f32_e32 v80, v80, v82
	v_sub_f32_e32 v79, v79, v82
	v_sub_f32_e32 v78, v78, v82
	v_sub_f32_e32 v77, v77, v82
	v_sub_f32_e32 v76, v76, v82
	v_sub_f32_e32 v75, v75, v82
	v_sub_f32_e32 v74, v74, v82
	v_sub_f32_e32 v73, v73, v82
	v_sub_f32_e32 v72, v72, v82
	v_sub_f32_e32 v71, v71, v82
	v_sub_f32_e32 v70, v70, v82
	v_sub_f32_e32 v69, v69, v82
	v_sub_f32_e32 v68, v68, v82
	v_sub_f32_e32 v67, v67, v82
	v_sub_f32_e32 v66, v66, v82
	v_mul_f32_e32 v246, v246, v83
	s_branch .LBB0_394

.LBB0_449:
	v_max_f32_e32 v34, v82, v82
	v_max_f32_e32 v82, 0, v34
	v_exp_f32_e64 v83, -v82
	v_add_f32_e32 v241, v241, v82
	v_xor_b32_e32 v34, 0x80000000, v241
	v_mov_b32_e32 v35, v34
	v_mov_b32_e32 v36, v34
	v_mov_b32_e32 v37, v34
	v_mov_b32_e32 v38, v34
	v_mov_b32_e32 v39, v34
	v_mov_b32_e32 v40, v34
	v_mov_b32_e32 v41, v34
	v_mov_b32_e32 v42, v34
	v_mov_b32_e32 v43, v34
	v_mov_b32_e32 v44, v34
	v_mov_b32_e32 v45, v34
	v_mov_b32_e32 v46, v34
	v_mov_b32_e32 v47, v34
	v_mov_b32_e32 v48, v34
	v_mov_b32_e32 v49, v34
	s_and_saveexec_b64 s[66:67], s[4:5]
	ds_write_b32 v240, v83
	s_or_b64 exec, exec, s[66:67]
	v_sub_f32_e32 v50, v50, v82
	v_sub_f32_e32 v51, v51, v82
	v_add_f32_e64 v52, v52, -v82
	v_add_f32_e64 v53, v53, -v82
	v_add_f32_e64 v54, v54, -v82
	v_add_f32_e64 v55, v55, -v82
	v_add_f32_e64 v56, v56, -v82
	v_add_f32_e64 v57, v57, -v82
	v_add_f32_e64 v58, v58, -v82
	v_add_f32_e64 v59, v59, -v82
	v_add_f32_e64 v60, v60, -v82
	v_add_f32_e64 v61, v61, -v82
	v_add_f32_e64 v62, v62, -v82
	v_add_f32_e64 v63, v63, -v82
	v_add_f32_e64 v64, v64, -v82
	v_add_f32_e64 v65, v65, -v82
	v_sub_f32_e32 v81, v81, v82
	v_sub_f32_e32 v80, v80, v82
	v_sub_f32_e32 v79, v79, v82
	v_sub_f32_e32 v78, v78, v82
	v_sub_f32_e32 v77, v77, v82
	v_sub_f32_e32 v76, v76, v82
	v_sub_f32_e32 v75, v75, v82
	v_sub_f32_e32 v74, v74, v82
	v_sub_f32_e32 v73, v73, v82
	v_sub_f32_e32 v72, v72, v82
	v_sub_f32_e32 v71, v71, v82
	v_sub_f32_e32 v70, v70, v82
	v_sub_f32_e32 v69, v69, v82
	v_sub_f32_e32 v68, v68, v82
	v_sub_f32_e32 v67, v67, v82
	v_sub_f32_e32 v66, v66, v82
	v_mul_f32_e32 v194, v194, v83
	s_branch .LBB0_414
.LBB0_452:
	v_max_f32_e32 v66, v66, v66
	v_max_f32_e32 v82, 0, v66
	v_exp_f32_e64 v84, -v82
	v_add_f32_e32 v66, v241, v82
	v_xor_b32_e32 v66, 0x80000000, v66
	v_mov_b32_e32 v67, v66
	v_mov_b32_e32 v68, v66
	v_mov_b32_e32 v69, v66
	v_mov_b32_e32 v70, v66
	v_mov_b32_e32 v71, v66
	v_mov_b32_e32 v72, v66
	v_mov_b32_e32 v73, v66
	v_mov_b32_e32 v74, v66
	v_mov_b32_e32 v75, v66
	v_mov_b32_e32 v76, v66
	v_mov_b32_e32 v77, v66
	v_mov_b32_e32 v78, v66
	v_mov_b32_e32 v79, v66
	v_mov_b32_e32 v80, v66
	v_mov_b32_e32 v81, v66
	s_and_saveexec_b64 s[64:65], s[4:5]
	ds_write_b32 v240, v84
	s_or_b64 exec, exec, s[64:65]
	v_sub_f32_e32 v34, v34, v82
	v_sub_f32_e32 v35, v35, v82
	v_add_f32_e64 v36, v36, -v82
	v_add_f32_e64 v37, v37, -v82
	v_add_f32_e64 v38, v38, -v82
	v_add_f32_e64 v39, v39, -v82
	v_add_f32_e64 v40, v40, -v82
	v_add_f32_e64 v41, v41, -v82
	v_add_f32_e64 v42, v42, -v82
	v_add_f32_e64 v43, v43, -v82
	v_add_f32_e64 v44, v44, -v82
	v_add_f32_e64 v45, v45, -v82
	v_add_f32_e64 v46, v46, -v82
	v_add_f32_e64 v47, v47, -v82
	v_add_f32_e64 v48, v48, -v82
	v_add_f32_e64 v49, v49, -v82
	v_sub_f32_e32 v65, v65, v82
	v_sub_f32_e32 v64, v64, v82
	v_sub_f32_e32 v63, v63, v82
	v_sub_f32_e32 v62, v62, v82
	v_sub_f32_e32 v61, v61, v82
	v_sub_f32_e32 v60, v60, v82
	v_sub_f32_e32 v59, v59, v82
	v_sub_f32_e32 v58, v58, v82
	v_sub_f32_e32 v57, v57, v82
	v_sub_f32_e32 v56, v56, v82
	v_sub_f32_e32 v55, v55, v82
	v_sub_f32_e32 v54, v54, v82
	v_sub_f32_e32 v53, v53, v82
	v_sub_f32_e32 v52, v52, v82
	v_sub_f32_e32 v51, v51, v82
	v_sub_f32_e32 v50, v50, v82
	v_mul_f32_e32 v83, v83, v84
	s_branch .LBB0_424

.LBB0_489:
	s_waitcnt lgkmcnt(14)
	v_mfma_f32_32x32x16_bf16 v[32:47], v[156:159], v[192:195], v[32:47]
	v_exp_f32_e32 v112, v112
	v_exp_f32_e32 v113, v113
	v_exp_f32_e32 v114, v114
	v_exp_f32_e32 v115, v115
	s_waitcnt lgkmcnt(12)
	v_mfma_f32_32x32x16_bf16 v[16:31], v[156:159], v[188:191], v[16:31]
	v_exp_f32_e32 v116, v116
	v_exp_f32_e32 v117, v117
	v_exp_f32_e32 v118, v118
	v_exp_f32_e32 v119, v119
	v_add_u32_e32 v0, s52, v221
	ds_read_b128 v[64:67], v0
	ds_read_b128 v[160:163], v0 offset:512
	s_waitcnt lgkmcnt(12)
	v_mfma_f32_32x32x16_bf16 v[32:47], v[152:155], v[184:187], v[32:47]
	v_exp_f32_e32 v120, v120
	v_exp_f32_e32 v121, v121
	v_exp_f32_e32 v122, v122
	v_exp_f32_e32 v123, v123
	ds_read_b128 v[192:195], v0 offset:2048
	ds_read_b128 v[184:187], v0 offset:2560
	s_waitcnt lgkmcnt(12)
	v_mfma_f32_32x32x16_bf16 v[16:31], v[152:155], v[84:87], v[16:31]
	v_exp_f32_e32 v124, v124
	v_exp_f32_e32 v125, v125
	v_exp_f32_e32 v126, v126
	v_exp_f32_e32 v127, v127
	ds_read_b128 v[188:191], v0 offset:4096
	ds_read_b128 v[176:179], v0 offset:4608
	s_waitcnt lgkmcnt(12)
	v_mfma_f32_32x32x16_bf16 v[32:47], v[144:147], v[80:83], v[32:47]
	v_exp_f32_e32 v96, v96
	v_exp_f32_e32 v97, v97
	v_exp_f32_e32 v98, v98
	v_exp_f32_e32 v99, v99
	ds_read_b128 v[180:183], v0 offset:6144
	ds_read_b128 v[172:175], v0 offset:6656
	s_waitcnt lgkmcnt(12)
	v_mfma_f32_32x32x16_bf16 v[16:31], v[144:147], v[10:13], v[16:31]
	v_exp_f32_e32 v100, v100
	v_exp_f32_e32 v101, v101
	v_exp_f32_e32 v102, v102
	v_exp_f32_e32 v103, v103
	s_waitcnt lgkmcnt(10)
	v_mfma_f32_32x32x16_bf16 v[32:47], v[136:139], v[6:9], v[32:47]
	v_exp_f32_e32 v104, v104
	v_exp_f32_e32 v105, v105
	v_exp_f32_e32 v106, v106
	v_exp_f32_e32 v107, v107
	s_waitcnt lgkmcnt(8)
	v_mfma_f32_32x32x16_bf16 v[16:31], v[136:139], v[2:5], v[16:31]
	v_exp_f32_e32 v108, v108
	v_exp_f32_e32 v109, v109
	v_exp_f32_e32 v110, v110
	v_exp_f32_e32 v111, v111
	s_waitcnt vmcnt(2) lgkmcnt(0)
	s_barrier
	s_andn2_b64 vcc, exec, s[10:11]
	v_add_u32_e32 v0, s3, v224
	s_cbranch_vccnz .LBB0_491
	s_waitcnt lgkmcnt(0)
	ds_read_b128 v[2:5], v0 offset:96
	ds_read_b128 v[6:9], v0 offset:64
	ds_read_b128 v[10:13], v0 offset:32
	ds_read_b128 v[68:71], v0
	s_waitcnt lgkmcnt(3)
	v_mul_f32_e32 v44, v44, v2
	v_mul_f32_e32 v45, v45, v3
	s_waitcnt lgkmcnt(2)
	v_mul_f32_e32 v40, v40, v6
	v_mul_f32_e32 v41, v41, v7
	s_waitcnt lgkmcnt(1)
	v_mul_f32_e32 v36, v36, v10
	v_mul_f32_e32 v37, v37, v11
	v_mul_f32_e32 v46, v46, v4
	v_mul_f32_e32 v47, v47, v5
	v_mul_f32_e32 v42, v42, v8
	v_mul_f32_e32 v43, v43, v9
	v_mul_f32_e32 v38, v38, v12
	v_mul_f32_e32 v39, v39, v13
	s_waitcnt lgkmcnt(0)
	v_mul_f32_e32 v34, v34, v70
	v_mul_f32_e32 v35, v35, v71
	v_mul_f32_e32 v32, v32, v68
	v_mul_f32_e32 v33, v33, v69
	v_mul_f32_e32 v28, v28, v2
	v_mul_f32_e32 v29, v29, v3
	v_mul_f32_e32 v24, v24, v6
	v_mul_f32_e32 v25, v25, v7
	v_mul_f32_e32 v20, v20, v10
	v_mul_f32_e32 v21, v21, v11
	v_mul_f32_e32 v30, v30, v4
	v_mul_f32_e32 v31, v31, v5
	v_mul_f32_e32 v26, v26, v8
	v_mul_f32_e32 v27, v27, v9
	v_mul_f32_e32 v22, v22, v12
	v_mul_f32_e32 v23, v23, v13
	v_mul_f32_e32 v18, v18, v70
	v_mul_f32_e32 v19, v19, v71
	v_mul_f32_e32 v16, v16, v68
	v_mul_f32_e32 v17, v17, v69

.LBB0_492:
	s_waitcnt lgkmcnt(14)
	v_mfma_f32_32x32x16_bf16 v[32:47], v[156:159], v[168:171], v[32:47]
	v_exp_f32_e32 v80, v80
	v_exp_f32_e32 v81, v81
	v_exp_f32_e32 v82, v82
	v_exp_f32_e32 v83, v83
	s_waitcnt lgkmcnt(12)
	v_mfma_f32_32x32x16_bf16 v[16:31], v[156:159], v[164:167], v[16:31]
	v_exp_f32_e32 v84, v84
	v_exp_f32_e32 v85, v85
	v_exp_f32_e32 v86, v86
	v_exp_f32_e32 v87, v87
	v_add_u32_e32 v14, s80, v221
	ds_read_b128 v[188:191], v14
	ds_read_b128 v[184:187], v14 offset:512
	s_waitcnt lgkmcnt(12)
	v_mfma_f32_32x32x16_bf16 v[32:47], v[152:155], v[160:163], v[32:47]
	v_exp_f32_e32 v88, v88
	v_exp_f32_e32 v89, v89
	v_exp_f32_e32 v90, v90
	v_exp_f32_e32 v91, v91
	ds_read_b128 v[180:183], v14 offset:2048
	ds_read_b128 v[176:179], v14 offset:2560
	s_waitcnt lgkmcnt(12)
	v_mfma_f32_32x32x16_bf16 v[16:31], v[152:155], v[116:119], v[16:31]
	v_exp_f32_e32 v92, v92
	v_exp_f32_e32 v93, v93
	v_exp_f32_e32 v94, v94
	v_exp_f32_e32 v95, v95
	ds_read_b128 v[172:175], v14 offset:4096
	ds_read_b128 v[168:171], v14 offset:4608
	s_waitcnt lgkmcnt(12)
	v_mfma_f32_32x32x16_bf16 v[32:47], v[144:147], v[112:115], v[32:47]
	v_exp_f32_e32 v64, v64
	v_exp_f32_e32 v65, v65
	v_exp_f32_e32 v66, v66
	v_exp_f32_e32 v67, v67
	ds_read_b128 v[164:167], v14 offset:6144
	ds_read_b128 v[160:163], v14 offset:6656
	s_waitcnt lgkmcnt(12)
	v_mfma_f32_32x32x16_bf16 v[16:31], v[144:147], v[10:13], v[16:31]
	v_exp_f32_e32 v68, v68
	v_exp_f32_e32 v69, v69
	v_exp_f32_e32 v70, v70
	v_exp_f32_e32 v71, v71
	s_waitcnt lgkmcnt(10)
	v_mfma_f32_32x32x16_bf16 v[32:47], v[136:139], v[6:9], v[32:47]
	v_exp_f32_e32 v72, v72
	v_exp_f32_e32 v73, v73
	v_exp_f32_e32 v74, v74
	v_exp_f32_e32 v75, v75
	s_waitcnt lgkmcnt(8)
	v_mfma_f32_32x32x16_bf16 v[16:31], v[136:139], v[2:5], v[16:31]
	v_exp_f32_e32 v76, v76
	v_exp_f32_e32 v77, v77
	v_exp_f32_e32 v78, v78
	v_exp_f32_e32 v79, v79
	s_waitcnt vmcnt(2) lgkmcnt(0)
	s_barrier
	s_andn2_b64 vcc, exec, s[10:11]
	s_cbranch_vccnz .LBB0_494
	s_waitcnt lgkmcnt(0)
	ds_read_b128 v[2:5], v0 offset:96
	ds_read_b128 v[6:9], v0 offset:64
	ds_read_b128 v[10:13], v0 offset:32
	ds_read_b128 v[96:99], v0
	s_waitcnt lgkmcnt(3)
	v_mul_f32_e32 v44, v44, v2
	v_mul_f32_e32 v45, v45, v3
	s_waitcnt lgkmcnt(2)
	v_mul_f32_e32 v40, v40, v6
	v_mul_f32_e32 v41, v41, v7
	s_waitcnt lgkmcnt(1)
	v_mul_f32_e32 v36, v36, v10
	v_mul_f32_e32 v37, v37, v11
	v_mul_f32_e32 v46, v46, v4
	v_mul_f32_e32 v47, v47, v5
	v_mul_f32_e32 v42, v42, v8
	v_mul_f32_e32 v43, v43, v9
	v_mul_f32_e32 v38, v38, v12
	v_mul_f32_e32 v39, v39, v13
	s_waitcnt lgkmcnt(0)
	v_mul_f32_e32 v34, v34, v98
	v_mul_f32_e32 v35, v35, v99
	v_mul_f32_e32 v32, v32, v96
	v_mul_f32_e32 v33, v33, v97
	v_mul_f32_e32 v28, v28, v2
	v_mul_f32_e32 v29, v29, v3
	v_mul_f32_e32 v24, v24, v6
	v_mul_f32_e32 v25, v25, v7
	v_mul_f32_e32 v20, v20, v10
	v_mul_f32_e32 v21, v21, v11
	v_mul_f32_e32 v30, v30, v4
	v_mul_f32_e32 v31, v31, v5
	v_mul_f32_e32 v26, v26, v8
	v_mul_f32_e32 v27, v27, v9
	v_mul_f32_e32 v22, v22, v12
	v_mul_f32_e32 v23, v23, v13
	v_mul_f32_e32 v18, v18, v98
	v_mul_f32_e32 v19, v19, v99
	v_mul_f32_e32 v16, v16, v96
	v_mul_f32_e32 v17, v17, v97

.LBB0_518:
	s_waitcnt lgkmcnt(0)
	ds_read_b128 v[2:5], v0 offset:96
	ds_read_b128 v[6:9], v0 offset:64
	ds_read_b128 v[10:13], v0 offset:32
	ds_read_b128 v[64:67], v0
	s_waitcnt lgkmcnt(3)
	v_mul_f32_e32 v44, v44, v2
	v_mul_f32_e32 v45, v45, v3
	s_waitcnt lgkmcnt(2)
	v_mul_f32_e32 v40, v40, v6
	v_mul_f32_e32 v41, v41, v7
	s_waitcnt lgkmcnt(1)
	v_mul_f32_e32 v36, v36, v10
	v_mul_f32_e32 v37, v37, v11
	v_mul_f32_e32 v46, v46, v4
	v_mul_f32_e32 v47, v47, v5
	v_mul_f32_e32 v42, v42, v8
	v_mul_f32_e32 v43, v43, v9
	v_mul_f32_e32 v38, v38, v12
	v_mul_f32_e32 v39, v39, v13
	s_waitcnt lgkmcnt(0)
	v_mul_f32_e32 v34, v34, v66
	v_mul_f32_e32 v35, v35, v67
	v_mul_f32_e32 v32, v32, v64
	v_mul_f32_e32 v33, v33, v65
	v_mul_f32_e32 v28, v28, v2
	v_mul_f32_e32 v29, v29, v3
	v_mul_f32_e32 v24, v24, v6
	v_mul_f32_e32 v25, v25, v7
	v_mul_f32_e32 v20, v20, v10
	v_mul_f32_e32 v21, v21, v11
	v_mul_f32_e32 v30, v30, v4
	v_mul_f32_e32 v31, v31, v5
	v_mul_f32_e32 v26, v26, v8
	v_mul_f32_e32 v27, v27, v9
	v_mul_f32_e32 v22, v22, v12
	v_mul_f32_e32 v23, v23, v13
	v_mul_f32_e32 v18, v18, v66
	v_mul_f32_e32 v19, v19, v67
	v_mul_f32_e32 v16, v16, v64
	v_mul_f32_e32 v17, v17, v65

.LBB0_539:
	s_waitcnt lgkmcnt(0)
	ds_read_b128 v[2:5], v0 offset:96
	ds_read_b128 v[6:9], v0 offset:64
	ds_read_b128 v[10:13], v0 offset:32
	ds_read_b128 v[96:99], v0
	s_waitcnt lgkmcnt(3)
	v_mul_f32_e32 v44, v44, v2
	v_mul_f32_e32 v45, v45, v3
	s_waitcnt lgkmcnt(2)
	v_mul_f32_e32 v40, v40, v6
	v_mul_f32_e32 v41, v41, v7
	s_waitcnt lgkmcnt(1)
	v_mul_f32_e32 v36, v36, v10
	v_mul_f32_e32 v37, v37, v11
	v_mul_f32_e32 v46, v46, v4
	v_mul_f32_e32 v47, v47, v5
	v_mul_f32_e32 v42, v42, v8
	v_mul_f32_e32 v43, v43, v9
	v_mul_f32_e32 v38, v38, v12
	v_mul_f32_e32 v39, v39, v13
	s_waitcnt lgkmcnt(0)
	v_mul_f32_e32 v34, v34, v98
	v_mul_f32_e32 v35, v35, v99
	v_mul_f32_e32 v32, v32, v96
	v_mul_f32_e32 v33, v33, v97
	v_mul_f32_e32 v28, v28, v2
	v_mul_f32_e32 v29, v29, v3
	v_mul_f32_e32 v24, v24, v6
	v_mul_f32_e32 v25, v25, v7
	v_mul_f32_e32 v20, v20, v10
	v_mul_f32_e32 v21, v21, v11
	v_mul_f32_e32 v30, v30, v4
	v_mul_f32_e32 v31, v31, v5
	v_mul_f32_e32 v26, v26, v8
	v_mul_f32_e32 v27, v27, v9
	v_mul_f32_e32 v22, v22, v12
	v_mul_f32_e32 v23, v23, v13
	v_mul_f32_e32 v18, v18, v98
	v_mul_f32_e32 v19, v19, v99
	v_mul_f32_e32 v16, v16, v96
	v_mul_f32_e32 v17, v17, v97

.LBB0_557:
	s_waitcnt lgkmcnt(14)
	v_mfma_f32_32x32x16_bf16 v[32:47], v[156:159], v[120:123], v[32:47]
	v_exp_f32_e32 v96, v96
	v_exp_f32_e32 v97, v97
	v_exp_f32_e32 v98, v98
	v_exp_f32_e32 v99, v99
	s_waitcnt lgkmcnt(12)
	v_mfma_f32_32x32x16_bf16 v[16:31], v[156:159], v[116:119], v[16:31]
	v_exp_f32_e32 v100, v100
	v_exp_f32_e32 v101, v101
	v_exp_f32_e32 v102, v102
	v_exp_f32_e32 v103, v103
	s_waitcnt lgkmcnt(10)
	v_mfma_f32_32x32x16_bf16 v[32:47], v[152:155], v[112:115], v[32:47]
	v_exp_f32_e32 v104, v104
	v_exp_f32_e32 v105, v105
	v_exp_f32_e32 v106, v106
	v_exp_f32_e32 v107, v107
	s_waitcnt lgkmcnt(8)
	v_mfma_f32_32x32x16_bf16 v[16:31], v[152:155], v[84:87], v[16:31]
	v_exp_f32_e32 v108, v108
	v_exp_f32_e32 v109, v109
	v_exp_f32_e32 v110, v110
	v_exp_f32_e32 v111, v111
	s_waitcnt lgkmcnt(6)
	v_mfma_f32_32x32x16_bf16 v[32:47], v[144:147], v[80:83], v[32:47]
	v_exp_f32_e32 v48, v48
	v_exp_f32_e32 v49, v49
	v_exp_f32_e32 v50, v50
	v_exp_f32_e32 v51, v51
	s_waitcnt lgkmcnt(4)
	v_mfma_f32_32x32x16_bf16 v[16:31], v[144:147], v[10:13], v[16:31]
	v_exp_f32_e32 v52, v52
	v_exp_f32_e32 v53, v53
	v_exp_f32_e32 v54, v54
	v_exp_f32_e32 v55, v55
	s_waitcnt lgkmcnt(2)
	v_mfma_f32_32x32x16_bf16 v[32:47], v[136:139], v[6:9], v[32:47]
	v_exp_f32_e32 v56, v56
	v_exp_f32_e32 v57, v57
	v_exp_f32_e32 v58, v58
	v_exp_f32_e32 v59, v59
	s_waitcnt lgkmcnt(0)
	v_mfma_f32_32x32x16_bf16 v[16:31], v[136:139], v[2:5], v[16:31]
	v_exp_f32_e32 v60, v60
	v_exp_f32_e32 v61, v61
	v_exp_f32_e32 v62, v62
	v_exp_f32_e32 v63, v63
	s_andn2_b64 vcc, exec, s[6:7]
	v_lshl_add_u32 v2, v214, 4, s3
	s_cbranch_vccnz .LBB0_559
	s_waitcnt lgkmcnt(0)
	ds_read_b128 v[4:7], v2 offset:96
	ds_read_b128 v[8:11], v2 offset:64
	ds_read_b128 v[12:15], v2 offset:32
	ds_read_b128 v[64:67], v2
	s_waitcnt lgkmcnt(3)
	v_mul_f32_e32 v46, v46, v6
	v_mul_f32_e32 v47, v47, v7
	s_waitcnt lgkmcnt(2)
	v_mul_f32_e32 v42, v42, v10
	v_mul_f32_e32 v43, v43, v11
	s_waitcnt lgkmcnt(1)
	v_mul_f32_e32 v38, v38, v14
	v_mul_f32_e32 v39, v39, v15
	s_waitcnt lgkmcnt(0)
	v_mul_f32_e32 v34, v34, v66
	v_mul_f32_e32 v35, v35, v67
	v_mul_f32_e32 v44, v44, v4
	v_mul_f32_e32 v45, v45, v5
	v_mul_f32_e32 v40, v40, v8
	v_mul_f32_e32 v41, v41, v9
	v_mul_f32_e32 v36, v36, v12
	v_mul_f32_e32 v37, v37, v13
	v_mul_f32_e32 v32, v32, v64
	v_mul_f32_e32 v33, v33, v65
	v_mul_f32_e32 v30, v30, v6
	v_mul_f32_e32 v31, v31, v7
	v_mul_f32_e32 v26, v26, v10
	v_mul_f32_e32 v27, v27, v11
	v_mul_f32_e32 v22, v22, v14
	v_mul_f32_e32 v23, v23, v15
	v_mul_f32_e32 v18, v18, v66
	v_mul_f32_e32 v19, v19, v67
	v_mul_f32_e32 v28, v28, v4
	v_mul_f32_e32 v29, v29, v5
	v_mul_f32_e32 v24, v24, v8
	v_mul_f32_e32 v25, v25, v9
	v_mul_f32_e32 v20, v20, v12
	v_mul_f32_e32 v21, v21, v13
	v_mul_f32_e32 v16, v16, v64
	v_mul_f32_e32 v17, v17, v65

;     __device__ __forceinline__ void operator()(const f32x4 (&acc)[2][2][4][2], const Unit& u, int wr, int wc, int fr, int fq) const {
;     ...
;             for (int n = 0; n < 2; ++n) { const f32x4 gv = *(const f32x4*)(g + col0 + bj * HALF + n * 16); f32x4 bs[2][4];
; #pragma unroll
;                 for (int ai = 0; ai < 2; ++ai)
; #pragma unroll
;                     for (int m = 0; m < 4; ++m) bs[ai][m] = *(const f32x4*)(src + off0 + (size_t)(ai * HALF + m * 16) * 1024 + bj * HALF + n * 16);
; #pragma unroll
;                 for (int ai = 0; ai < 2; ++ai)
; #pragma unroll
;                     for (int m = 0; m < 4; ++m) *(f32x4*)(dst + off0 + (size_t)(ai * HALF + m * 16) * 1024 + bj * HALF + n * 16) = bs[ai][m] + gv * acc[ai][bj][m][n];
;                 asm volatile("" ::: "memory"); }
.LBB0_640:
	s_lshl_b64 s[6:7], s[70:71], 2
	v_lshl_or_b32 v142, s63, 8, v173
	s_add_u32 s6, s76, s6
	v_ashrrev_i32_e32 v143, 31, v142
	s_addc_u32 s7, s77, s7
	v_lshl_add_u64 v[144:145], v[132:133], 0, v[142:143]
	v_lshl_add_u64 v[148:149], v[142:143], 2, s[6:7]
	v_lshlrev_b64 v[142:143], 2, v[144:145]
	v_lshl_add_u64 v[150:151], s[64:65], 0, v[142:143]
	v_add_co_u32_e32 v152, vcc, s75, v150
	global_load_dwordx4 v[190:193], v[148:149], off
	s_nop 0
	v_addc_co_u32_e32 v153, vcc, 0, v151, vcc
	v_add_co_u32_e32 v156, vcc, s88, v150
	global_load_dwordx4 v[194:197], v[150:151], off
	global_load_dwordx4 v[198:201], v[152:153], off
	v_addc_co_u32_e32 v157, vcc, 0, v151, vcc
	v_add_co_u32_e32 v158, vcc, s89, v150
	s_ashr_i32 s63, s62, 31
	s_nop 0
	v_addc_co_u32_e32 v159, vcc, 0, v151, vcc
	v_add_co_u32_e32 v160, vcc, s93, v150
	global_load_dwordx4 v[202:205], v[156:157], off
	global_load_dwordx4 v[206:209], v[158:159], off
	v_addc_co_u32_e32 v161, vcc, 0, v151, vcc
	v_add_co_u32_e32 v164, vcc, s94, v150
	global_load_dwordx4 v[210:213], v[160:161], off
	s_nop 0
	v_addc_co_u32_e32 v165, vcc, 0, v151, vcc
	v_add_co_u32_e32 v166, vcc, s95, v150
	global_load_dwordx4 v[214:217], v[164:165], off
	s_nop 0
	v_addc_co_u32_e32 v167, vcc, 0, v151, vcc
	global_load_dwordx4 v[218:221], v[166:167], off
	v_add_co_u32_e32 v168, vcc, s96, v150
	s_lshl_b64 s[6:7], s[62:63], 20
	s_nop 0
	v_addc_co_u32_e32 v169, vcc, 0, v151, vcc
	global_load_dwordx4 v[224:227], v[168:169], off
	s_add_u32 s6, s48, s6
	s_addc_u32 s7, s49, s7
	v_lshl_add_u64 v[142:143], s[6:7], 0, v[142:143]
	v_add_co_u32_e32 v144, vcc, s75, v142
	s_waitcnt vmcnt(0)
	v_fma_f32 v126, v126, v192, v196
	v_fma_f32 v127, v127, v193, v197
	v_addc_co_u32_e32 v145, vcc, 0, v143, vcc
	v_add_co_u32_e32 v146, vcc, s88, v142
	v_fma_f32 v124, v124, v190, v194
	v_fma_f32 v125, v125, v191, v195
	s_nop 0
	v_addc_co_u32_e32 v147, vcc, 0, v143, vcc
	v_add_co_u32_e32 v154, vcc, s89, v142
	v_fma_f32 v122, v122, v192, v200
	v_fma_f32 v123, v123, v193, v201
	s_nop 0
	v_addc_co_u32_e32 v155, vcc, 0, v143, vcc
	v_add_co_u32_e32 v162, vcc, s93, v142
	v_fma_f32 v120, v120, v190, v198
	v_fma_f32 v121, v121, v191, v199
	s_nop 0
	v_addc_co_u32_e32 v163, vcc, 0, v143, vcc
	v_add_co_u32_e32 v170, vcc, s94, v142
	global_store_dwordx4 v[142:143], v[124:127], off
	s_nop 0
	v_addc_co_u32_e32 v171, vcc, 0, v143, vcc
	v_fma_f32 v100, v100, v190, v214
	v_fma_f32 v101, v101, v191, v215
	v_fma_f32 v118, v118, v192, v204
	v_fma_f32 v119, v119, v193, v205
	v_fma_f32 v116, v116, v190, v202
	v_fma_f32 v117, v117, v191, v203
	v_fma_f32 v114, v114, v192, v208
	v_fma_f32 v115, v115, v193, v209
	v_fma_f32 v112, v112, v190, v206
	v_fma_f32 v113, v113, v191, v207
	v_fma_f32 v106, v106, v192, v212
	v_fma_f32 v107, v107, v193, v213
	v_fma_f32 v104, v104, v190, v210
	v_fma_f32 v105, v105, v191, v211
	v_fma_f32 v102, v102, v192, v216
	v_fma_f32 v103, v103, v193, v217
	global_store_dwordx4 v[144:145], v[120:123], off
	global_store_dwordx4 v[146:147], v[116:119], off
	global_store_dwordx4 v[154:155], v[112:115], off
	global_store_dwordx4 v[162:163], v[104:107], off
	global_store_dwordx4 v[170:171], v[100:103], off
	s_nop 1
	v_fma_f32 v100, v92, v190, v218
	v_fma_f32 v101, v93, v191, v219
	v_add_co_u32_e32 v92, vcc, s95, v142
	v_fma_f32 v102, v94, v192, v220
	v_fma_f32 v103, v95, v193, v221
	s_nop 0
	v_addc_co_u32_e32 v93, vcc, 0, v143, vcc
	global_store_dwordx4 v[92:93], v[100:103], off
	s_nop 1
	v_fma_f32 v100, v80, v190, v224
	v_fma_f32 v101, v81, v191, v225
	v_add_co_u32_e32 v80, vcc, s96, v142
	v_fma_f32 v102, v82, v192, v226
	v_fma_f32 v103, v83, v193, v227
	s_nop 0
	v_addc_co_u32_e32 v81, vcc, 0, v143, vcc
	global_store_dwordx4 v[80:81], v[100:103], off
	global_load_dwordx4 v[100:103], v[148:149], off offset:64
	global_load_dwordx4 v[104:107], v[150:151], off offset:64
	global_load_dwordx4 v[112:115], v[152:153], off offset:64
	global_load_dwordx4 v[116:119], v[156:157], off offset:64
	global_load_dwordx4 v[120:123], v[158:159], off offset:64
	global_load_dwordx4 v[124:127], v[160:161], off offset:64
	global_load_dwordx4 v[190:193], v[164:165], off offset:64
	global_load_dwordx4 v[194:197], v[166:167], off offset:64
	global_load_dwordx4 v[198:201], v[168:169], off offset:64
	s_andn2_b64 vcc, exec, s[4:5]
	s_mov_b64 s[4:5], -1
	s_waitcnt vmcnt(7)
	v_fma_f32 v106, v110, v102, v106
	v_fma_f32 v107, v111, v103, v107
	v_fma_f32 v104, v108, v100, v104
	v_fma_f32 v105, v109, v101, v105
	s_waitcnt vmcnt(6)
	v_fma_f32 v98, v98, v102, v114
	v_fma_f32 v99, v99, v103, v115
	v_fma_f32 v96, v96, v100, v112
	v_fma_f32 v97, v97, v101, v113
	s_waitcnt vmcnt(5)
	v_fma_f32 v90, v90, v102, v118
	v_fma_f32 v91, v91, v103, v119
	v_fma_f32 v88, v88, v100, v116
	v_fma_f32 v89, v89, v101, v117
	s_waitcnt vmcnt(4)
	v_fma_f32 v86, v86, v102, v122
	v_fma_f32 v87, v87, v103, v123
	v_fma_f32 v84, v84, v100, v120
	v_fma_f32 v85, v85, v101, v121
	s_waitcnt vmcnt(3)
	v_fma_f32 v78, v78, v102, v126
	v_fma_f32 v79, v79, v103, v127
	v_fma_f32 v76, v76, v100, v124
	v_fma_f32 v77, v77, v101, v125
	s_waitcnt vmcnt(2)
;     __device__ __forceinline__ void operator()(const f32x4 (&acc)[2][2][4][2], const Unit& u, int wr, int wc, int fr, int fq) const {
;     ...
;             for (int n = 0; n < 2; ++n) { const f32x4 gv = *(const f32x4*)(g + col0 + bj * HALF + n * 16); f32x4 bs[2][4];
; #pragma unroll
;                 for (int ai = 0; ai < 2; ++ai)
; #pragma unroll
;                     for (int m = 0; m < 4; ++m) bs[ai][m] = *(const f32x4*)(src + off0 + (size_t)(ai * HALF + m * 16) * 1024 + bj * HALF + n * 16);
; #pragma unroll
;                 for (int ai = 0; ai < 2; ++ai)
; #pragma unroll
;                     for (int m = 0; m < 4; ++m) *(f32x4*)(dst + off0 + (size_t)(ai * HALF + m * 16) * 1024 + bj * HALF + n * 16) = bs[ai][m] + gv * acc[ai][bj][m][n];
;                 asm volatile("" ::: "memory"); }
	v_fma_f32 v74, v74, v102, v192
	v_fma_f32 v75, v75, v103, v193
	v_fma_f32 v72, v72, v100, v190
	v_fma_f32 v73, v73, v101, v191
	s_waitcnt vmcnt(1)
	v_fma_f32 v66, v66, v102, v196
	v_fma_f32 v67, v67, v103, v197
	v_fma_f32 v64, v64, v100, v194
	v_fma_f32 v65, v65, v101, v195
	s_waitcnt vmcnt(0)
	v_fma_f32 v58, v58, v102, v200
	v_fma_f32 v59, v59, v103, v201
	v_fma_f32 v56, v56, v100, v198
	v_fma_f32 v57, v57, v101, v199
	global_store_dwordx4 v[142:143], v[104:107], off offset:64
	global_store_dwordx4 v[144:145], v[96:99], off offset:64
	global_store_dwordx4 v[146:147], v[88:91], off offset:64
	global_store_dwordx4 v[154:155], v[84:87], off offset:64
	global_store_dwordx4 v[162:163], v[76:79], off offset:64
	global_store_dwordx4 v[170:171], v[72:75], off offset:64
	global_store_dwordx4 v[92:93], v[64:67], off offset:64
	global_store_dwordx4 v[80:81], v[56:59], off offset:64
	global_load_dwordx4 v[56:59], v[148:149], off offset:512
	global_load_dwordx4 v[64:67], v[150:151], off offset:512
	global_load_dwordx4 v[72:75], v[152:153], off offset:512
	global_load_dwordx4 v[76:79], v[156:157], off offset:512
	global_load_dwordx4 v[82:85], v[158:159], off offset:512
	global_load_dwordx4 v[86:89], v[160:161], off offset:512
	global_load_dwordx4 v[94:97], v[164:165], off offset:512
	global_load_dwordx4 v[98:101], v[166:167], off offset:512
	global_load_dwordx4 v[102:105], v[168:169], off offset:512
	s_waitcnt vmcnt(7)
	v_fma_f32 v66, v70, v58, v66
	v_fma_f32 v67, v71, v59, v67
	v_fma_f32 v64, v68, v56, v64
	v_fma_f32 v65, v69, v57, v65
	s_waitcnt vmcnt(6)
	v_fma_f32 v62, v62, v58, v74
	v_fma_f32 v63, v63, v59, v75
	v_fma_f32 v60, v60, v56, v72
	v_fma_f32 v61, v61, v57, v73
	s_waitcnt vmcnt(5)
	v_fma_f32 v54, v54, v58, v78
	v_fma_f32 v55, v55, v59, v79
	v_fma_f32 v52, v52, v56, v76
	v_fma_f32 v53, v53, v57, v77
	s_waitcnt vmcnt(4)
	v_fma_f32 v50, v50, v58, v84
	v_fma_f32 v51, v51, v59, v85
	v_fma_f32 v48, v48, v56, v82
	v_fma_f32 v49, v49, v57, v83
	s_waitcnt vmcnt(3)
	v_fma_f32 v46, v46, v58, v88
	v_fma_f32 v47, v47, v59, v89
	v_fma_f32 v44, v44, v56, v86
	v_fma_f32 v45, v45, v57, v87
	s_waitcnt vmcnt(2)
	v_fma_f32 v38, v38, v58, v96
	v_fma_f32 v39, v39, v59, v97
	v_fma_f32 v36, v36, v56, v94
	v_fma_f32 v37, v37, v57, v95
	s_waitcnt vmcnt(1)
	v_fma_f32 v30, v30, v58, v100
	v_fma_f32 v31, v31, v59, v101
	v_fma_f32 v28, v28, v56, v98
	v_fma_f32 v29, v29, v57, v99
	s_waitcnt vmcnt(0)
	v_fma_f32 v22, v22, v58, v104
	v_fma_f32 v23, v23, v59, v105
	v_fma_f32 v20, v20, v56, v102
	v_fma_f32 v21, v21, v57, v103
	global_store_dwordx4 v[142:143], v[64:67], off offset:512
	global_store_dwordx4 v[144:145], v[60:63], off offset:512
	global_store_dwordx4 v[146:147], v[52:55], off offset:512
	global_store_dwordx4 v[154:155], v[48:51], off offset:512
	global_store_dwordx4 v[162:163], v[44:47], off offset:512
	global_store_dwordx4 v[170:171], v[36:39], off offset:512
	global_store_dwordx4 v[92:93], v[28:31], off offset:512
	global_store_dwordx4 v[80:81], v[20:23], off offset:512
	global_load_dwordx4 v[20:23], v[148:149], off offset:576
	global_load_dwordx4 v[28:31], v[150:151], off offset:576
	global_load_dwordx4 v[36:39], v[152:153], off offset:576
	global_load_dwordx4 v[44:47], v[156:157], off offset:576
	global_load_dwordx4 v[48:51], v[158:159], off offset:576
	global_load_dwordx4 v[52:55], v[160:161], off offset:576
	global_load_dwordx4 v[56:59], v[164:165], off offset:576
	global_load_dwordx4 v[60:63], v[166:167], off offset:576
	global_load_dwordx4 v[64:67], v[168:169], off offset:576
	s_waitcnt vmcnt(7)
	v_fma_f32 v30, v42, v22, v30
	v_fma_f32 v31, v43, v23, v31
	v_fma_f32 v28, v40, v20, v28
	v_fma_f32 v29, v41, v21, v29
	s_waitcnt vmcnt(6)
	v_fma_f32 v34, v34, v22, v38
	v_fma_f32 v35, v35, v23, v39
	v_fma_f32 v32, v32, v20, v36
	v_fma_f32 v33, v33, v21, v37
	s_waitcnt vmcnt(5)
	v_fma_f32 v26, v26, v22, v46
	v_fma_f32 v27, v27, v23, v47
	v_fma_f32 v24, v24, v20, v44
	v_fma_f32 v25, v25, v21, v45
	s_waitcnt vmcnt(4)
	v_fma_f32 v18, v18, v22, v50
	v_fma_f32 v19, v19, v23, v51
	v_fma_f32 v16, v16, v20, v48
	v_fma_f32 v17, v17, v21, v49
	s_waitcnt vmcnt(3)
	v_fma_f32 v14, v14, v22, v54
	v_fma_f32 v15, v15, v23, v55
	v_fma_f32 v12, v12, v20, v52
	v_fma_f32 v13, v13, v21, v53
	s_waitcnt vmcnt(2)
	v_fma_f32 v10, v10, v22, v58
	v_fma_f32 v11, v11, v23, v59
	v_fma_f32 v8, v8, v20, v56
	v_fma_f32 v9, v9, v21, v57
	s_waitcnt vmcnt(1)
	v_fma_f32 v6, v6, v22, v62
	v_fma_f32 v7, v7, v23, v63
	v_fma_f32 v4, v4, v20, v60
	v_fma_f32 v5, v5, v21, v61
	s_waitcnt vmcnt(0)
	v_fma_f32 v2, v2, v22, v66
	v_fma_f32 v3, v3, v23, v67
	v_fma_f32 v0, v0, v20, v64
	v_fma_f32 v1, v1, v21, v65
	global_store_dwordx4 v[142:143], v[28:31], off offset:576
	global_store_dwordx4 v[144:145], v[32:35], off offset:576
	global_store_dwordx4 v[146:147], v[24:27], off offset:576
	global_store_dwordx4 v[154:155], v[16:19], off offset:576
	global_store_dwordx4 v[162:163], v[12:15], off offset:576
	global_store_dwordx4 v[170:171], v[8:11], off offset:576
	global_store_dwordx4 v[92:93], v[4:7], off offset:576
	global_store_dwordx4 v[80:81], v[0:3], off offset:576
	s_cbranch_vccnz .LBB0_626
	s_andn2_b64 vcc, exec, s[8:9]
	s_cbranch_vccnz .LBB0_625
	s_barrier
	s_branch .LBB0_625

; __device__ __forceinline__ unsigned pk2(float lo, float hi) { return f2bf(lo) | (f2bf(hi) << 16); }
; __device__ __forceinline__ void norm_mod_phase(const float* lat, long lat_bs, const float* cx, long ctx_bs, const float* modl, int shoff, int scoff, bf16* XN, int skip_ctx, int gw, int NGW, float* xcopy, const float* part, int nkc, const float* pgate) {
;     ...
;         const float rstd = 1.0f / sqrtf(wave_sum(ss) * (1.0f / DMODEL) + EPS);
;         const f32x4* sh = (const f32x4*)(modl + s * NMOD6 + shoff) + lane; const f32x4* sc = (const f32x4*)(modl + s * NMOD6 + scoff) + lane;
;         v2u* o8 = (v2u*)(XN + (size_t)row * DMODEL) + lane;
; #pragma unroll
;         for (int j = 0; j < 4; ++j) { const f32x4 a = sh[64 * j], m = sc[64 * j]; const f32x4 y = v[j] * rstd * (m + 1.0f) + a; v2u w; w.x = pk2(y.x, y.y); w.y = pk2(y.z, y.w); o8[64 * j] = w; }
.LBB0_721:
	s_add_u32 s54, s54, s42
	s_mulk_i32 s4, 0x1800
	s_addc_u32 s55, s55, s43
	s_ashr_i32 s5, s4, 31
	s_lshl_b64 s[4:5], s[4:5], 2
	s_add_u32 s4, s68, s4
	s_addc_u32 s5, s69, s5
	v_lshl_add_u64 v[60:61], s[4:5], 0, v[32:33]
	v_add_co_u32_e32 v56, vcc, s12, v60
	ds_bpermute_b32 v51, v44, v50
	s_nop 0
	v_addc_co_u32_e32 v57, vcc, 0, v61, vcc
	global_load_dwordx4 v[52:55], v[56:57], off
	s_nop 0
	global_load_dwordx4 v[56:59], v[56:57], off offset:-4096
	s_lshl_b64 s[4:5], s[60:61], 11
	s_waitcnt lgkmcnt(0)
	v_add_f32_e32 v50, v50, v51
	ds_bpermute_b32 v51, v45, v50
	v_lshl_add_u64 v[62:63], v[36:37], 0, s[4:5]
	v_lshl_add_u64 v[40:41], v[40:41], 0, s[56:57]
	s_cmp_lt_i32 s54, 0x8400
	s_waitcnt lgkmcnt(0)
	v_add_f32_e32 v50, v50, v51
	ds_bpermute_b32 v51, v46, v50
	s_waitcnt lgkmcnt(0)
	v_add_f32_e32 v50, v50, v51
	ds_bpermute_b32 v51, v47, v50
	s_waitcnt lgkmcnt(0)
	v_add_f32_e32 v50, v50, v51
	ds_bpermute_b32 v51, v48, v50
	s_waitcnt lgkmcnt(0)
	v_add_f32_e32 v50, v50, v51
	ds_bpermute_b32 v51, v49, v50
	s_waitcnt lgkmcnt(0)
	v_add_f32_e32 v50, v50, v51
	v_fmamk_f32 v50, v50, 0x3a800000, v42
	v_mul_f32_e32 v51, 0x4f800000, v50
	v_cmp_gt_f32_e32 vcc, s7, v50
	s_waitcnt vmcnt(1)
	v_add_f32_e32 v52, 1.0, v52
	v_add_f32_e32 v53, 1.0, v53
	v_cndmask_b32_e32 v50, v50, v51, vcc
	v_sqrt_f32_e32 v51, v50
	s_nop 0
	v_add_u32_e32 v64, -1, v51
	v_add_u32_e32 v65, 1, v51
	v_fma_f32 v66, -v64, v51, v50
	v_fma_f32 v67, -v65, v51, v50
	v_cmp_ge_f32_e64 s[4:5], 0, v66
	s_nop 1
	v_cndmask_b32_e64 v51, v51, v64, s[4:5]
	v_cmp_lt_f32_e64 s[4:5], 0, v67
	s_nop 1
	v_cndmask_b32_e64 v51, v51, v65, s[4:5]
	v_mul_f32_e32 v64, 0x37800000, v51
	v_cndmask_b32_e32 v51, v51, v64, vcc
	v_cmp_class_f32_e32 vcc, v50, v43
	v_lshl_add_u64 v[64:65], v[60:61], 0, s[52:53]
	s_nop 0
	v_cndmask_b32_e32 v50, v51, v50, vcc
	v_div_scale_f32 v51, s[4:5], v50, v50, 1.0
	v_rcp_f32_e32 v66, v51
	v_div_scale_f32 v67, vcc, 1.0, v50, 1.0
	s_mov_b32 s4, s58
	v_fma_f32 v68, -v51, v66, 1.0
	v_fmac_f32_e32 v66, v68, v66
	v_mul_f32_e32 v68, v67, v66
	v_fma_f32 v69, -v51, v68, v67
	v_fmac_f32_e32 v68, v69, v66
	v_fma_f32 v51, -v51, v68, v67
	v_div_fmas_f32 v51, v51, v66, v68
	v_div_fixup_f32 v66, v51, v50, 1.0
	v_mul_f32_e32 v12, v12, v66
	v_mul_f32_e32 v13, v13, v66
	v_mul_f32_e32 v14, v14, v66
	v_mul_f32_e32 v15, v15, v66
	v_add_f32_e32 v50, 1.0, v54
	v_add_f32_e32 v51, 1.0, v55
	s_waitcnt vmcnt(0)
	v_fma_f32 v12, v52, v12, v56
	v_fma_f32 v13, v53, v13, v57
	v_fma_f32 v14, v50, v14, v58
	v_fma_f32 v15, v51, v15, v59
	v_bfe_u32 v50, v12, 16, 1
	v_bfe_u32 v52, v14, 16, 1
	v_bfe_u32 v51, v13, 16, 1
	v_bfe_u32 v53, v15, 16, 1
	v_add3_u32 v12, v12, v50, s13
	v_add3_u32 v14, v14, v52, s13
	v_add3_u32 v13, v13, v51, s13
	v_add3_u32 v15, v15, v53, s13
	v_lshrrev_b32_e32 v12, 16, v12
	v_lshrrev_b32_e32 v14, 16, v14
	v_and_or_b32 v12, v13, s14, v12
	v_and_or_b32 v13, v15, s14, v14
	global_store_dwordx2 v[62:63], v[12:13], off
	global_load_dwordx4 v[12:15], v[64:65], off offset:1024
	v_lshl_add_u64 v[54:55], v[60:61], 0, s[36:37]
	global_load_dwordx4 v[50:53], v[54:55], off offset:1024
	global_load_dwordx4 v[100:103], v[64:65], off offset:2048
	global_load_dwordx4 v[104:107], v[54:55], off offset:2048
	global_load_dwordx4 v[108:111], v[64:65], off offset:3072
	global_load_dwordx4 v[112:115], v[54:55], off offset:3072
	v_mul_f32_e32 v8, v8, v66
	v_mul_f32_e32 v9, v9, v66
	v_mul_f32_e32 v10, v10, v66
	v_mul_f32_e32 v11, v11, v66
	v_mul_f32_e32 v4, v4, v66
	v_mul_f32_e32 v5, v5, v66
	v_mul_f32_e32 v6, v6, v66
	v_mul_f32_e32 v7, v7, v66
	v_mul_f32_e32 v58, v0, v66
	v_mul_f32_e32 v59, v1, v66
	v_mul_f32_e32 v60, v2, v66
	v_mul_f32_e32 v61, v3, v66
	v_mov_b64_e32 v[0:1], v[28:29]
	v_mov_b64_e32 v[2:3], v[30:31]
	s_waitcnt vmcnt(5)
	v_add_f32_e32 v14, 1.0, v14
	v_add_f32_e32 v15, 1.0, v15
	v_add_f32_e32 v12, 1.0, v12
	v_add_f32_e32 v13, 1.0, v13
	s_waitcnt vmcnt(4)
	v_fma_f32 v10, v14, v10, v52
	v_fma_f32 v11, v15, v11, v53
	v_fma_f32 v8, v12, v8, v50
	v_fma_f32 v9, v13, v9, v51
	v_bfe_u32 v14, v10, 16, 1
	v_bfe_u32 v12, v8, 16, 1
	v_bfe_u32 v13, v9, 16, 1
	v_bfe_u32 v15, v11, 16, 1
	v_add3_u32 v8, v8, v12, s13
	v_add3_u32 v10, v10, v14, s13
	v_add3_u32 v9, v9, v13, s13
	v_add3_u32 v11, v11, v15, s13
	v_lshrrev_b32_e32 v8, 16, v8
	v_lshrrev_b32_e32 v10, 16, v10
	v_and_or_b32 v8, v9, s14, v8
	v_and_or_b32 v9, v11, s14, v10
	global_store_dwordx2 v[62:63], v[8:9], off offset:512
	s_nop 0
	s_waitcnt vmcnt(4)
	v_add_f32_e32 v10, 1.0, v102
	v_add_f32_e32 v11, 1.0, v103
	v_add_f32_e32 v8, 1.0, v100
	v_add_f32_e32 v9, 1.0, v101
	s_waitcnt vmcnt(3)
	v_fma_f32 v6, v6, v10, v106
	v_fma_f32 v7, v7, v11, v107
	v_fma_f32 v4, v4, v8, v104
	v_fma_f32 v5, v5, v9, v105
	v_bfe_u32 v10, v6, 16, 1
	v_bfe_u32 v8, v4, 16, 1
	v_bfe_u32 v9, v5, 16, 1
	v_bfe_u32 v11, v7, 16, 1
	v_add3_u32 v4, v4, v8, s13
	v_add3_u32 v6, v6, v10, s13
	v_add3_u32 v5, v5, v9, s13
	v_add3_u32 v7, v7, v11, s13
	v_lshrrev_b32_e32 v4, 16, v4
	v_lshrrev_b32_e32 v6, 16, v6
	v_and_or_b32 v4, v5, s14, v4
	v_and_or_b32 v5, v7, s14, v6
	global_store_dwordx2 v[62:63], v[4:5], off offset:1024
	s_nop 0
	v_mov_b64_e32 v[4:5], v[24:25]
	v_mov_b64_e32 v[8:9], v[20:21]
	v_mov_b64_e32 v[12:13], v[16:17]
	v_mov_b64_e32 v[6:7], v[26:27]
	v_mov_b64_e32 v[10:11], v[22:23]
	v_mov_b64_e32 v[14:15], v[18:19]
	s_waitcnt vmcnt(3)
	v_add_f32_e32 v52, 1.0, v110
	v_add_f32_e32 v53, 1.0, v111
	v_add_f32_e32 v50, 1.0, v108
	v_add_f32_e32 v51, 1.0, v109
	s_waitcnt vmcnt(2)
	v_fma_f32 v52, v60, v52, v114
	v_fma_f32 v53, v61, v53, v115
	v_fma_f32 v50, v58, v50, v112
	v_fma_f32 v51, v59, v51, v113
	v_bfe_u32 v56, v52, 16, 1
	v_bfe_u32 v54, v50, 16, 1
	v_bfe_u32 v55, v51, 16, 1
	v_bfe_u32 v57, v53, 16, 1
	v_add3_u32 v50, v50, v54, s13
	v_add3_u32 v52, v52, v56, s13
	v_add3_u32 v51, v51, v55, s13
	v_add3_u32 v53, v53, v57, s13
	v_lshrrev_b32_e32 v50, 16, v50
	v_lshrrev_b32_e32 v52, 16, v52
	v_and_or_b32 v50, v51, s14, v50
	v_and_or_b32 v51, v53, s14, v52
	global_store_dwordx2 v[62:63], v[50:51], off offset:1536
	s_cbranch_scc0 .LBB0_732

; __device__ __forceinline__ void norm_mod_phase(const float* lat, long lat_bs, const float* cx, long ctx_bs, const float* modl, int shoff, int scoff, bf16* XN, int skip_ctx, int gw, int NGW, float* xcopy, const float* part, int nkc, const float* pgate) {
;     ...
;         if (skip_ctx && s == 4) continue;
; #pragma unroll
;         for (int j = 0; j < 4; ++j) ss += (v[j].x * v[j].x + v[j].y * v[j].y) + (v[j].z * v[j].z + v[j].w * v[j].w);
.LBB0_728:
	s_cmp_eq_u32 s4, 4
	s_mov_b64 s[62:63], -1
	s_cbranch_scc1 .LBB0_730
	v_mul_f32_e32 v50, v14, v14
	v_mul_f32_e32 v51, v15, v15
	v_mul_f32_e32 v52, v12, v12
	v_mul_f32_e32 v53, v13, v13
	v_mov_b32_e32 v55, v51
	v_mov_b32_e32 v54, v52
	v_pk_mov_b32 v[50:51], v[52:53], v[50:51] op_sel:[1,0]
	v_mul_f32_e32 v52, v10, v10
	v_mul_f32_e32 v53, v11, v11
	v_add_f32_e32 v50, v50, v54
	v_add_f32_e32 v51, v51, v55
	v_mul_f32_e32 v54, v8, v8
	v_mul_f32_e32 v55, v9, v9
	v_add_f32_e32 v51, v50, v51
	v_add_f32_e32 v50, v50, v50
	v_mov_b32_e32 v56, v54
	v_mov_b32_e32 v57, v53
	v_pk_mov_b32 v[52:53], v[54:55], v[52:53] op_sel:[1,0]
	v_mul_f32_e32 v50, v4, v4
	v_add_f32_e32 v52, v52, v56
	v_add_f32_e32 v53, v53, v57
	v_fma_f32 v54, v4, v4, v50
	v_fma_f32 v55, v5, v5, v50
	v_mul_f32_e32 v50, v6, v6
	v_add_f32_e32 v53, v52, v53
	v_add_f32_e32 v52, v52, v52
	v_fma_f32 v56, v6, v6, v50
	v_fma_f32 v57, v7, v7, v50
	v_mul_f32_e32 v54, v0, v0
	v_mul_f32_e32 v56, v1, v1
	v_mul_f32_e32 v52, v2, v2
	v_mul_f32_e32 v50, v3, v3
	v_add_f32_e32 v54, v54, v56
	v_add_f32_e32 v55, v55, v57
	v_add_f32_e32 v50, v52, v50
	v_add_f32_e32 v51, v53, v51
	s_ashr_i32 s61, s54, 31
	v_add_f32_e32 v50, v54, v50
	v_add_f32_e32 v51, v55, v51
	s_mov_b32 s60, s54
	v_add_f32_e32 v50, v50, v51
	s_cbranch_execnz .LBB0_721
	s_branch .LBB0_731

; __device__ __forceinline__ void norm_mod_phase(const float* lat, long lat_bs, const float* cx, long ctx_bs, const float* modl, int shoff, int scoff, bf16* XN, int skip_ctx, int gw, int NGW, float* xcopy, const float* part, int nkc, const float* pgate) {
;     ...
;         if (xcopy && s == 4) {
;             const int b_ = row / TPB, cr = b_ * CTXL + (row - b_ * TPB); const f32x4* gp = (const f32x4*)(pgate + 4 * NMOD6) + lane;
;             f32x4 sm[4];
; #pragma unroll
;             for (int j = 0; j < 4; ++j) sm[j] = (f32x4){0.f, 0.f, 0.f, 0.f};
;             for (int kc = 0; kc < nkc; ++kc) { const f32x4* pp = (const f32x4*)(part + ((size_t)kc * 1024 + cr) * DMODEL) + lane;
; #pragma unroll
;                 for (int j = 0; j < 4; ++j) sm[j] += pp[64 * j]; }
;             f32x4* xc = (f32x4*)(xcopy + (size_t)row * DMODEL) + lane; ss = 0.f;
; #pragma unroll
;             for (int j = 0; j < 4; ++j) { v[j] += gp[64 * j] * sm[j]; xc[64 * j] = v[j]; ss += (v[j].x * v[j].x + v[j].y * v[j].y) + (v[j].z * v[j].z + v[j].w * v[j].w); } }
.LBB0_731:
	s_mul_hi_i32 s5, s54, 0xc1f07c1f
	s_lshr_b32 s8, s5, 31
	s_lshr_b32 s5, s5, 11
	s_add_i32 s5, s5, s8
	s_lshl_b32 s5, s5, 13
	s_add_i32 s60, s54, s5
	s_ashr_i32 s61, s60, 31
	s_lshl_b64 s[60:61], s[60:61], 12
	v_lshl_add_u64 v[86:87], v[34:35], 0, s[60:61]
	v_add_co_u32_e32 v94, vcc, s1, v86
	global_load_dwordx4 v[50:53], v[86:87], off
	s_nop 0
	v_addc_co_u32_e32 v95, vcc, 0, v87, vcc
	v_add_co_u32_e32 v102, vcc, s3, v86
	global_load_dwordx4 v[54:57], v[94:95], off
	s_nop 0
	v_addc_co_u32_e32 v103, vcc, 0, v87, vcc
	global_load_dwordx4 v[58:61], v[102:103], off
	v_add_co_u32_e32 v114, vcc, s6, v86
	s_mov_b64 s[60:61], s[54:55]
	s_nop 0
	v_addc_co_u32_e32 v115, vcc, 0, v87, vcc
	global_load_dwordx4 v[62:65], v[114:115], off
	global_load_dwordx4 v[66:69], v[38:39], off
	global_load_dwordx4 v[70:73], v[86:87], off offset:3072
	global_load_dwordx4 v[74:77], v[94:95], off offset:3072
	global_load_dwordx4 v[78:81], v[102:103], off offset:3072
	global_load_dwordx4 v[82:85], v[86:87], off offset:1024
	s_nop 0
	global_load_dwordx4 v[86:89], v[86:87], off offset:2048
	s_nop 0
	global_load_dwordx4 v[90:93], v[94:95], off offset:1024
	s_nop 0
	global_load_dwordx4 v[94:97], v[94:95], off offset:2048
	s_nop 0
	global_load_dwordx4 v[98:101], v[102:103], off offset:1024
	s_nop 0
	global_load_dwordx4 v[102:105], v[102:103], off offset:2048
	s_nop 0
	global_load_dwordx4 v[106:109], v[114:115], off offset:1024
	global_load_dwordx4 v[110:113], v[114:115], off offset:2048
	s_nop 0
	global_load_dwordx4 v[114:117], v[114:115], off offset:3072
	s_waitcnt vmcnt(16)
	v_add_f32_e32 v52, 0, v52
	v_add_f32_e32 v53, 0, v53
	v_add_f32_e32 v50, 0, v50
	v_add_f32_e32 v51, 0, v51
	s_waitcnt vmcnt(15)
	v_add_f32_e32 v52, v52, v56
	v_add_f32_e32 v53, v53, v57
	v_add_f32_e32 v50, v50, v54
	v_add_f32_e32 v51, v51, v55
	s_waitcnt vmcnt(8)
	v_add_f32_e32 v54, 0, v84
	v_add_f32_e32 v55, 0, v85
	v_add_f32_e32 v52, v52, v60
	v_add_f32_e32 v53, v53, v61
	v_add_f32_e32 v50, v50, v58
	v_add_f32_e32 v51, v51, v59
	v_add_f32_e32 v52, v52, v64
	v_add_f32_e32 v53, v53, v65
	v_add_f32_e32 v50, v50, v62
	v_add_f32_e32 v51, v51, v63
	v_fma_f32 v14, v52, v68, v14
	v_fma_f32 v15, v53, v69, v15
	v_fma_f32 v12, v50, v66, v12
	v_fma_f32 v13, v51, v67, v13
	global_store_dwordx4 v[40:41], v[12:15], off
	global_load_dwordx4 v[50:53], v[38:39], off offset:1024
	v_add_f32_e32 v56, 0, v82
	v_add_f32_e32 v57, 0, v83
	s_waitcnt vmcnt(8)
	v_add_f32_e32 v54, v54, v92
	v_add_f32_e32 v55, v55, v93
	v_add_f32_e32 v56, v56, v90
	v_add_f32_e32 v57, v57, v91
	s_waitcnt vmcnt(6)
	v_add_f32_e32 v54, v54, v100
	v_add_f32_e32 v55, v55, v101
	v_add_f32_e32 v56, v56, v98
	v_add_f32_e32 v57, v57, v99
	s_waitcnt vmcnt(4)
	v_add_f32_e32 v54, v54, v108
	v_add_f32_e32 v55, v55, v109
	v_add_f32_e32 v56, v56, v106
	v_add_f32_e32 v57, v57, v107
	v_mul_f32_e32 v58, v14, v14
	v_mul_f32_e32 v59, v15, v15
	v_mul_f32_e32 v60, v12, v12
	v_mul_f32_e32 v61, v13, v13
	s_waitcnt vmcnt(0)
	v_fma_f32 v10, v54, v52, v10
	v_fma_f32 v11, v55, v53, v11
	v_fma_f32 v8, v56, v50, v8
	v_fma_f32 v9, v57, v51, v9
	global_store_dwordx4 v[40:41], v[8:11], off offset:1024
	global_load_dwordx4 v[50:53], v[38:39], off offset:2048
	v_add_f32_e32 v54, 0, v88
	v_add_f32_e32 v55, 0, v89
	v_add_f32_e32 v56, 0, v86
	v_add_f32_e32 v57, 0, v87
	v_add_f32_e32 v54, v54, v96
	v_add_f32_e32 v55, v55, v97
	v_add_f32_e32 v56, v56, v94
	v_add_f32_e32 v57, v57, v95
	v_add_f32_e32 v54, v54, v104
	v_add_f32_e32 v55, v55, v105
	v_add_f32_e32 v56, v56, v102
	v_add_f32_e32 v57, v57, v103
	v_add_f32_e32 v54, v54, v112
	v_add_f32_e32 v55, v55, v113
	v_add_f32_e32 v56, v56, v110
	v_add_f32_e32 v57, v57, v111
	v_pk_mov_b32 v[62:63], v[60:61], v[58:59] op_sel:[1,0]
	v_mov_b32_e32 v61, v59
	v_add_f32_e32 v58, v62, v60
	v_add_f32_e32 v59, v63, v61
	v_mul_f32_e32 v60, v10, v10
	v_mul_f32_e32 v61, v11, v11
	v_mul_f32_e32 v62, v8, v8
	v_mul_f32_e32 v63, v9, v9
	v_pk_add_f32 v[58:59], v[58:59], v[58:59] op_sel:[0,1] op_sel_hi:[1,0]
	v_pk_mov_b32 v[64:65], v[62:63], v[60:61] op_sel:[1,0]
	v_mov_b32_e32 v63, v61
	v_add_f32_e32 v60, v64, v62
	v_add_f32_e32 v61, v65, v63
	s_waitcnt vmcnt(0)
	v_fma_f32 v6, v54, v52, v6
	v_fma_f32 v7, v55, v53, v7
	v_fma_f32 v4, v56, v50, v4
	v_fma_f32 v5, v57, v51, v5
	global_store_dwordx4 v[40:41], v[4:7], off offset:2048
	global_load_dwordx4 v[50:53], v[38:39], off offset:3072
	v_add_f32_e32 v54, 0, v72
	v_add_f32_e32 v55, 0, v73
	v_add_f32_e32 v56, 0, v70
	v_add_f32_e32 v57, 0, v71
	v_add_f32_e32 v54, v54, v76
	v_add_f32_e32 v55, v55, v77
	v_add_f32_e32 v56, v56, v74
	v_add_f32_e32 v57, v57, v75
	v_add_f32_e32 v54, v54, v80
	v_add_f32_e32 v55, v55, v81
	v_add_f32_e32 v56, v56, v78
	v_add_f32_e32 v57, v57, v79
	v_add_f32_e32 v54, v54, v116
	v_add_f32_e32 v55, v55, v117
	v_add_f32_e32 v56, v56, v114
	v_add_f32_e32 v57, v57, v115
	v_mul_f32_e32 v62, v5, v5
	v_mul_f32_e32 v64, v7, v7
	v_pk_add_f32 v[60:61], v[60:61], v[60:61] op_sel:[0,1] op_sel_hi:[1,0]
	v_fma_f32 v63, v5, v5, v62
	v_fma_f32 v62, v4, v4, v62
	v_fma_f32 v65, v7, v7, v64
	v_fma_f32 v64, v6, v6, v64
	s_waitcnt vmcnt(0)
	v_fma_f32 v2, v54, v52, v2
	v_fma_f32 v3, v55, v53, v3
	v_fma_f32 v0, v56, v50, v0
	v_fma_f32 v1, v57, v51, v1
	v_mul_f32_e32 v63, v2, v2
	v_mul_f32_e32 v59, v0, v0
	v_mul_f32_e32 v61, v1, v1
	v_mul_f32_e32 v65, v3, v3
	v_add_f32_e32 v50, v58, v60
	v_add_f32_e32 v51, v59, v61
	v_add_f32_e32 v52, v62, v64
	v_add_f32_e32 v53, v63, v65
	global_store_dwordx4 v[40:41], v[0:3], off offset:3072
	v_add_f32_e32 v50, v50, v52
	v_add_f32_e32 v51, v51, v53
	s_nop 0
	v_add_f32_e32 v50, v50, v51
	s_branch .LBB0_721

;     __device__ __forceinline__ void operator()(const f32x4 (&acc)[2][2][4][2], const Unit& u, int wr, int wc, int fr, int fq) const {
;     ...
;             for (int n = 0; n < 2; ++n) { const f32x4 gv = *(const f32x4*)(g + col0 + bj * HALF + n * 16); f32x4 bs[2][4];
; #pragma unroll
;                 for (int ai = 0; ai < 2; ++ai)
; #pragma unroll
;                     for (int m = 0; m < 4; ++m) bs[ai][m] = *(const f32x4*)(src + off0 + (size_t)(ai * HALF + m * 16) * 1024 + bj * HALF + n * 16);
; #pragma unroll
;                 for (int ai = 0; ai < 2; ++ai)
; #pragma unroll
;                     for (int m = 0; m < 4; ++m) *(f32x4*)(dst + off0 + (size_t)(ai * HALF + m * 16) * 1024 + bj * HALF + n * 16) = bs[ai][m] + gv * acc[ai][bj][m][n];
;                 asm volatile("" ::: "memory"); }
.LBB0_879:
	s_lshl_b64 s[60:61], s[60:61], 2
	v_lshl_or_b32 v142, s33, 8, v173
	s_add_u32 s60, s68, s60
	v_ashrrev_i32_e32 v143, 31, v142
	s_addc_u32 s61, s69, s61
	v_lshl_add_u64 v[144:145], v[132:133], 0, v[142:143]
	v_lshl_add_u64 v[148:149], v[142:143], 2, s[60:61]
	v_lshlrev_b64 v[142:143], 2, v[144:145]
	v_lshl_add_u64 v[150:151], s[58:59], 0, v[142:143]
	v_add_co_u32_e32 v152, vcc, s67, v150
	global_load_dwordx4 v[190:193], v[148:149], off
	s_nop 0
	v_addc_co_u32_e32 v153, vcc, 0, v151, vcc
	v_add_co_u32_e32 v156, vcc, s80, v150
	global_load_dwordx4 v[194:197], v[150:151], off
	global_load_dwordx4 v[198:201], v[152:153], off
	v_addc_co_u32_e32 v157, vcc, 0, v151, vcc
	v_add_co_u32_e32 v158, vcc, s81, v150
	s_ashr_i32 s57, s56, 31
	s_nop 0
	v_addc_co_u32_e32 v159, vcc, 0, v151, vcc
	v_add_co_u32_e32 v160, vcc, s82, v150
	global_load_dwordx4 v[202:205], v[156:157], off
	global_load_dwordx4 v[206:209], v[158:159], off
	v_addc_co_u32_e32 v161, vcc, 0, v151, vcc
	v_add_co_u32_e32 v164, vcc, s83, v150
	global_load_dwordx4 v[210:213], v[160:161], off
	s_nop 0
	v_addc_co_u32_e32 v165, vcc, 0, v151, vcc
	v_add_co_u32_e32 v166, vcc, s84, v150
	global_load_dwordx4 v[214:217], v[164:165], off
	s_nop 0
	v_addc_co_u32_e32 v167, vcc, 0, v151, vcc
	global_load_dwordx4 v[218:221], v[166:167], off
	v_add_co_u32_e32 v168, vcc, s85, v150
	s_lshl_b64 s[56:57], s[56:57], 20
	s_nop 0
	v_addc_co_u32_e32 v169, vcc, 0, v151, vcc
	global_load_dwordx4 v[224:227], v[168:169], off
	s_add_u32 s56, s48, s56
	s_addc_u32 s57, s49, s57
	v_lshl_add_u64 v[142:143], s[56:57], 0, v[142:143]
	v_add_co_u32_e32 v144, vcc, s67, v142
	s_waitcnt vmcnt(0)
	v_fma_f32 v126, v126, v192, v196
	v_fma_f32 v127, v127, v193, v197
	v_addc_co_u32_e32 v145, vcc, 0, v143, vcc
	v_add_co_u32_e32 v146, vcc, s80, v142
	v_fma_f32 v124, v124, v190, v194
	v_fma_f32 v125, v125, v191, v195
	s_nop 0
	v_addc_co_u32_e32 v147, vcc, 0, v143, vcc
	v_add_co_u32_e32 v154, vcc, s81, v142
	v_fma_f32 v122, v122, v192, v200
	v_fma_f32 v123, v123, v193, v201
	s_nop 0
	v_addc_co_u32_e32 v155, vcc, 0, v143, vcc
	v_add_co_u32_e32 v162, vcc, s82, v142
	v_fma_f32 v120, v120, v190, v198
	v_fma_f32 v121, v121, v191, v199
	s_nop 0
	v_addc_co_u32_e32 v163, vcc, 0, v143, vcc
	v_add_co_u32_e32 v170, vcc, s83, v142
	global_store_dwordx4 v[142:143], v[124:127], off
	s_nop 0
	v_addc_co_u32_e32 v171, vcc, 0, v143, vcc
	v_fma_f32 v100, v100, v190, v214
	v_fma_f32 v101, v101, v191, v215
	v_fma_f32 v118, v118, v192, v204
	v_fma_f32 v119, v119, v193, v205
	v_fma_f32 v116, v116, v190, v202
	v_fma_f32 v117, v117, v191, v203
	v_fma_f32 v114, v114, v192, v208
	v_fma_f32 v115, v115, v193, v209
	v_fma_f32 v112, v112, v190, v206
	v_fma_f32 v113, v113, v191, v207
	v_fma_f32 v106, v106, v192, v212
	v_fma_f32 v107, v107, v193, v213
	v_fma_f32 v104, v104, v190, v210
	v_fma_f32 v105, v105, v191, v211
	v_fma_f32 v102, v102, v192, v216
	v_fma_f32 v103, v103, v193, v217
	global_store_dwordx4 v[144:145], v[120:123], off
	global_store_dwordx4 v[146:147], v[116:119], off
	global_store_dwordx4 v[154:155], v[112:115], off
	global_store_dwordx4 v[162:163], v[104:107], off
	global_store_dwordx4 v[170:171], v[100:103], off
	s_nop 1
	v_fma_f32 v100, v92, v190, v218
	v_fma_f32 v101, v93, v191, v219
	v_add_co_u32_e32 v92, vcc, s84, v142
	v_fma_f32 v102, v94, v192, v220
	v_fma_f32 v103, v95, v193, v221
	s_nop 0
	v_addc_co_u32_e32 v93, vcc, 0, v143, vcc
	global_store_dwordx4 v[92:93], v[100:103], off
	s_nop 1
	v_fma_f32 v100, v80, v190, v224
	v_fma_f32 v101, v81, v191, v225
	v_add_co_u32_e32 v80, vcc, s85, v142
	v_fma_f32 v102, v82, v192, v226
	v_fma_f32 v103, v83, v193, v227
	s_nop 0
	v_addc_co_u32_e32 v81, vcc, 0, v143, vcc
	global_store_dwordx4 v[80:81], v[100:103], off
	global_load_dwordx4 v[100:103], v[148:149], off offset:64
	global_load_dwordx4 v[104:107], v[150:151], off offset:64
	global_load_dwordx4 v[112:115], v[152:153], off offset:64
	global_load_dwordx4 v[116:119], v[156:157], off offset:64
	global_load_dwordx4 v[120:123], v[158:159], off offset:64
	global_load_dwordx4 v[124:127], v[160:161], off offset:64
	global_load_dwordx4 v[190:193], v[164:165], off offset:64
	global_load_dwordx4 v[194:197], v[166:167], off offset:64
	global_load_dwordx4 v[198:201], v[168:169], off offset:64
	s_and_b64 vcc, exec, s[6:7]
	s_mov_b64 s[6:7], -1
	s_waitcnt vmcnt(7)
	v_fma_f32 v106, v110, v102, v106
	v_fma_f32 v107, v111, v103, v107
	v_fma_f32 v104, v108, v100, v104
	v_fma_f32 v105, v109, v101, v105
	s_waitcnt vmcnt(6)
	v_fma_f32 v98, v98, v102, v114
	v_fma_f32 v99, v99, v103, v115
	v_fma_f32 v96, v96, v100, v112
	v_fma_f32 v97, v97, v101, v113
	s_waitcnt vmcnt(5)
	v_fma_f32 v90, v90, v102, v118
	v_fma_f32 v91, v91, v103, v119
	v_fma_f32 v88, v88, v100, v116
	v_fma_f32 v89, v89, v101, v117
	s_waitcnt vmcnt(4)
	v_fma_f32 v86, v86, v102, v122
	v_fma_f32 v87, v87, v103, v123
	v_fma_f32 v84, v84, v100, v120
	v_fma_f32 v85, v85, v101, v121
	s_waitcnt vmcnt(3)
	v_fma_f32 v78, v78, v102, v126
	v_fma_f32 v79, v79, v103, v127
	v_fma_f32 v76, v76, v100, v124
	v_fma_f32 v77, v77, v101, v125
	s_waitcnt vmcnt(2)
;     __device__ __forceinline__ void operator()(const f32x4 (&acc)[2][2][4][2], const Unit& u, int wr, int wc, int fr, int fq) const {
;     ...
;             for (int n = 0; n < 2; ++n) { const f32x4 gv = *(const f32x4*)(g + col0 + bj * HALF + n * 16); f32x4 bs[2][4];
; #pragma unroll
;                 for (int ai = 0; ai < 2; ++ai)
; #pragma unroll
;                     for (int m = 0; m < 4; ++m) bs[ai][m] = *(const f32x4*)(src + off0 + (size_t)(ai * HALF + m * 16) * 1024 + bj * HALF + n * 16);
; #pragma unroll
;                 for (int ai = 0; ai < 2; ++ai)
; #pragma unroll
;                     for (int m = 0; m < 4; ++m) *(f32x4*)(dst + off0 + (size_t)(ai * HALF + m * 16) * 1024 + bj * HALF + n * 16) = bs[ai][m] + gv * acc[ai][bj][m][n];
;                 asm volatile("" ::: "memory"); }
	v_fma_f32 v74, v74, v102, v192
	v_fma_f32 v75, v75, v103, v193
	v_fma_f32 v72, v72, v100, v190
	v_fma_f32 v73, v73, v101, v191
	s_waitcnt vmcnt(1)
	v_fma_f32 v66, v66, v102, v196
	v_fma_f32 v67, v67, v103, v197
	v_fma_f32 v64, v64, v100, v194
	v_fma_f32 v65, v65, v101, v195
	s_waitcnt vmcnt(0)
	v_fma_f32 v58, v58, v102, v200
	v_fma_f32 v59, v59, v103, v201
	v_fma_f32 v56, v56, v100, v198
	v_fma_f32 v57, v57, v101, v199
	global_store_dwordx4 v[142:143], v[104:107], off offset:64
	global_store_dwordx4 v[144:145], v[96:99], off offset:64
	global_store_dwordx4 v[146:147], v[88:91], off offset:64
	global_store_dwordx4 v[154:155], v[84:87], off offset:64
	global_store_dwordx4 v[162:163], v[76:79], off offset:64
	global_store_dwordx4 v[170:171], v[72:75], off offset:64
	global_store_dwordx4 v[92:93], v[64:67], off offset:64
	global_store_dwordx4 v[80:81], v[56:59], off offset:64
	global_load_dwordx4 v[56:59], v[148:149], off offset:512
	global_load_dwordx4 v[64:67], v[150:151], off offset:512
	global_load_dwordx4 v[72:75], v[152:153], off offset:512
	global_load_dwordx4 v[76:79], v[156:157], off offset:512
	global_load_dwordx4 v[82:85], v[158:159], off offset:512
	global_load_dwordx4 v[86:89], v[160:161], off offset:512
	global_load_dwordx4 v[94:97], v[164:165], off offset:512
	global_load_dwordx4 v[98:101], v[166:167], off offset:512
	global_load_dwordx4 v[102:105], v[168:169], off offset:512
	s_waitcnt vmcnt(7)
	v_fma_f32 v66, v70, v58, v66
	v_fma_f32 v67, v71, v59, v67
	v_fma_f32 v64, v68, v56, v64
	v_fma_f32 v65, v69, v57, v65
	s_waitcnt vmcnt(6)
	v_fma_f32 v62, v62, v58, v74
	v_fma_f32 v63, v63, v59, v75
	v_fma_f32 v60, v60, v56, v72
	v_fma_f32 v61, v61, v57, v73
	s_waitcnt vmcnt(5)
	v_fma_f32 v54, v54, v58, v78
	v_fma_f32 v55, v55, v59, v79
	v_fma_f32 v52, v52, v56, v76
	v_fma_f32 v53, v53, v57, v77
	s_waitcnt vmcnt(4)
	v_fma_f32 v50, v50, v58, v84
	v_fma_f32 v51, v51, v59, v85
	v_fma_f32 v48, v48, v56, v82
	v_fma_f32 v49, v49, v57, v83
	s_waitcnt vmcnt(3)
	v_fma_f32 v46, v46, v58, v88
	v_fma_f32 v47, v47, v59, v89
	v_fma_f32 v44, v44, v56, v86
	v_fma_f32 v45, v45, v57, v87
	s_waitcnt vmcnt(2)
	v_fma_f32 v38, v38, v58, v96
	v_fma_f32 v39, v39, v59, v97
	v_fma_f32 v36, v36, v56, v94
	v_fma_f32 v37, v37, v57, v95
	s_waitcnt vmcnt(1)
	v_fma_f32 v30, v30, v58, v100
	v_fma_f32 v31, v31, v59, v101
	v_fma_f32 v28, v28, v56, v98
	v_fma_f32 v29, v29, v57, v99
	s_waitcnt vmcnt(0)
	v_fma_f32 v22, v22, v58, v104
	v_fma_f32 v23, v23, v59, v105
	v_fma_f32 v20, v20, v56, v102
	v_fma_f32 v21, v21, v57, v103
	global_store_dwordx4 v[142:143], v[64:67], off offset:512
	global_store_dwordx4 v[144:145], v[60:63], off offset:512
	global_store_dwordx4 v[146:147], v[52:55], off offset:512
	global_store_dwordx4 v[154:155], v[48:51], off offset:512
	global_store_dwordx4 v[162:163], v[44:47], off offset:512
	global_store_dwordx4 v[170:171], v[36:39], off offset:512
	global_store_dwordx4 v[92:93], v[28:31], off offset:512
	global_store_dwordx4 v[80:81], v[20:23], off offset:512
	global_load_dwordx4 v[20:23], v[148:149], off offset:576
	global_load_dwordx4 v[28:31], v[150:151], off offset:576
	global_load_dwordx4 v[36:39], v[152:153], off offset:576
	global_load_dwordx4 v[44:47], v[156:157], off offset:576
	global_load_dwordx4 v[48:51], v[158:159], off offset:576
	global_load_dwordx4 v[52:55], v[160:161], off offset:576
	global_load_dwordx4 v[56:59], v[164:165], off offset:576
	global_load_dwordx4 v[60:63], v[166:167], off offset:576
	global_load_dwordx4 v[64:67], v[168:169], off offset:576
	s_waitcnt vmcnt(7)
	v_fma_f32 v30, v42, v22, v30
	v_fma_f32 v31, v43, v23, v31
	v_fma_f32 v28, v40, v20, v28
	v_fma_f32 v29, v41, v21, v29
	s_waitcnt vmcnt(6)
	v_fma_f32 v34, v34, v22, v38
	v_fma_f32 v35, v35, v23, v39
	v_fma_f32 v32, v32, v20, v36
	v_fma_f32 v33, v33, v21, v37
	s_waitcnt vmcnt(5)
	v_fma_f32 v26, v26, v22, v46
	v_fma_f32 v27, v27, v23, v47
	v_fma_f32 v24, v24, v20, v44
	v_fma_f32 v25, v25, v21, v45
	s_waitcnt vmcnt(4)
	v_fma_f32 v18, v18, v22, v50
	v_fma_f32 v19, v19, v23, v51
	v_fma_f32 v16, v16, v20, v48
	v_fma_f32 v17, v17, v21, v49
	s_waitcnt vmcnt(3)
	v_fma_f32 v14, v14, v22, v54
	v_fma_f32 v15, v15, v23, v55
	v_fma_f32 v12, v12, v20, v52
	v_fma_f32 v13, v13, v21, v53
	s_waitcnt vmcnt(2)
	v_fma_f32 v10, v10, v22, v58
	v_fma_f32 v11, v11, v23, v59
	v_fma_f32 v8, v8, v20, v56
	v_fma_f32 v9, v9, v21, v57
	s_waitcnt vmcnt(1)
	v_fma_f32 v6, v6, v22, v62
	v_fma_f32 v7, v7, v23, v63
	v_fma_f32 v4, v4, v20, v60
	v_fma_f32 v5, v5, v21, v61
	s_waitcnt vmcnt(0)
	v_fma_f32 v2, v2, v22, v66
	v_fma_f32 v3, v3, v23, v67
	v_fma_f32 v0, v0, v20, v64
	v_fma_f32 v1, v1, v21, v65
	global_store_dwordx4 v[142:143], v[28:31], off offset:576
	global_store_dwordx4 v[144:145], v[32:35], off offset:576
	global_store_dwordx4 v[146:147], v[24:27], off offset:576
	global_store_dwordx4 v[154:155], v[16:19], off offset:576
	global_store_dwordx4 v[162:163], v[12:15], off offset:576
	global_store_dwordx4 v[170:171], v[8:11], off offset:576
	global_store_dwordx4 v[92:93], v[4:7], off offset:576
	global_store_dwordx4 v[80:81], v[0:3], off offset:576
	s_cbranch_vccnz .LBB0_861
	s_andn2_b64 vcc, exec, s[36:37]
	s_cbranch_vccnz .LBB0_860
	s_barrier
	s_branch .LBB0_860

; __device__ __forceinline__ unsigned pk2(float lo, float hi) { return f2bf(lo) | (f2bf(hi) << 16); }
; __device__ __forceinline__ void norm_mod_phase(const float* lat, long lat_bs, const float* cx, long ctx_bs, const float* modl, int shoff, int scoff, bf16* XN, int skip_ctx, int gw, int NGW, float* xcopy, const float* part, int nkc, const float* pgate) {
;     ...
;         const float rstd = 1.0f / sqrtf(wave_sum(ss) * (1.0f / DMODEL) + EPS);
;         const f32x4* sh = (const f32x4*)(modl + s * NMOD6 + shoff) + lane; const f32x4* sc = (const f32x4*)(modl + s * NMOD6 + scoff) + lane;
;         v2u* o8 = (v2u*)(XN + (size_t)row * DMODEL) + lane;
; #pragma unroll
;         for (int j = 0; j < 4; ++j) { const f32x4 a = sh[64 * j], m = sc[64 * j]; const f32x4 y = v[j] * rstd * (m + 1.0f) + a; v2u w; w.x = pk2(y.x, y.y); w.y = pk2(y.z, y.w); o8[64 * j] = w; }
.LBB0_960:
	s_add_u32 s36, s36, s42
	s_mul_i32 s40, s57, 0x1800
	s_addc_u32 s37, s37, s43
	s_ashr_i32 s41, s40, 31
	s_lshl_b64 s[40:41], s[40:41], 2
	s_add_u32 s40, s86, s40
	s_addc_u32 s41, s38, s41
	v_lshl_add_u64 v[38:39], s[40:41], 0, v[40:41]
	v_add_co_u32_e32 v34, vcc, s54, v38
	ds_bpermute_b32 v33, v52, v32
	s_nop 0
	v_addc_co_u32_e32 v35, vcc, 0, v39, vcc
	global_load_dwordx4 v[34:37], v[34:35], off
	s_nop 0
	global_load_dwordx4 v[60:63], v40, s[40:41]
	s_lshl_b64 s[6:7], s[6:7], 11
	s_waitcnt lgkmcnt(0)
	v_add_f32_e32 v32, v32, v33
	ds_bpermute_b32 v33, v53, v32
	v_lshl_add_u64 v[50:51], v[46:47], 0, s[6:7]
	v_lshl_add_u64 v[38:39], v[38:39], 0, s[10:11]
	v_lshl_add_u64 v[48:49], v[48:49], 0, s[8:9]
	s_cmp_lt_i32 s36, 0x8400
	s_waitcnt lgkmcnt(0)
	v_add_f32_e32 v32, v32, v33
	ds_bpermute_b32 v33, v54, v32
	s_mov_b32 s57, s39
	s_waitcnt lgkmcnt(0)
	v_add_f32_e32 v32, v32, v33
	ds_bpermute_b32 v33, v55, v32
	s_waitcnt lgkmcnt(0)
	v_add_f32_e32 v32, v32, v33
	ds_bpermute_b32 v33, v56, v32
	s_waitcnt lgkmcnt(0)
	v_add_f32_e32 v32, v32, v33
	ds_bpermute_b32 v33, v57, v32
	s_waitcnt lgkmcnt(0)
	v_add_f32_e32 v32, v32, v33
	v_fmamk_f32 v32, v32, 0x3a800000, v58
	v_mul_f32_e32 v33, 0x4f800000, v32
	v_cmp_gt_f32_e32 vcc, s53, v32
	s_waitcnt vmcnt(1)
	v_add_f32_e32 v34, 1.0, v34
	v_add_f32_e32 v35, 1.0, v35
	v_cndmask_b32_e32 v32, v32, v33, vcc
	v_sqrt_f32_e32 v33, v32
	s_nop 0
	v_add_u32_e32 v64, -1, v33
	v_add_u32_e32 v65, 1, v33
	v_fma_f32 v66, -v64, v33, v32
	v_fma_f32 v67, -v65, v33, v32
	v_cmp_ge_f32_e64 s[6:7], 0, v66
	s_nop 1
	v_cndmask_b32_e64 v33, v33, v64, s[6:7]
	v_cmp_lt_f32_e64 s[6:7], 0, v67
	s_nop 1
	v_cndmask_b32_e64 v33, v33, v65, s[6:7]
	v_mul_f32_e32 v64, 0x37800000, v33
	v_cndmask_b32_e32 v33, v33, v64, vcc
	v_cmp_class_f32_e32 vcc, v32, v59
	s_nop 1
	v_cndmask_b32_e32 v32, v33, v32, vcc
	v_div_scale_f32 v33, s[6:7], v32, v32, 1.0
	v_rcp_f32_e32 v64, v33
	v_div_scale_f32 v65, vcc, 1.0, v32, 1.0
	v_fma_f32 v66, -v33, v64, 1.0
	v_fmac_f32_e32 v64, v66, v64
	v_mul_f32_e32 v66, v65, v64
	v_fma_f32 v67, -v33, v66, v65
	v_fmac_f32_e32 v66, v67, v64
	v_fma_f32 v33, -v33, v66, v65
	v_div_fmas_f32 v33, v33, v64, v66
	v_div_fixup_f32 v64, v33, v32, 1.0
	v_mul_f32_e32 v28, v28, v64
	v_mul_f32_e32 v29, v29, v64
	v_mul_f32_e32 v30, v30, v64
	v_mul_f32_e32 v31, v31, v64
	v_add_f32_e32 v32, 1.0, v36
	v_add_f32_e32 v33, 1.0, v37
	s_waitcnt vmcnt(0)
	v_fma_f32 v28, v34, v28, v60
	v_fma_f32 v29, v35, v29, v61
	v_fma_f32 v30, v32, v30, v62
	v_fma_f32 v31, v33, v31, v63
	v_bfe_u32 v32, v28, 16, 1
	v_bfe_u32 v34, v30, 16, 1
	v_bfe_u32 v33, v29, 16, 1
	v_bfe_u32 v35, v31, 16, 1
	v_add3_u32 v28, v28, v32, s55
	v_add3_u32 v30, v30, v34, s55
	v_add3_u32 v29, v29, v33, s55
	v_add3_u32 v31, v31, v35, s55
	v_lshrrev_b32_e32 v28, 16, v28
	v_lshrrev_b32_e32 v30, 16, v30
	v_and_or_b32 v28, v29, s56, v28
	v_and_or_b32 v29, v31, s56, v30
	global_store_dwordx2 v[50:51], v[28:29], off
	global_load_dwordx4 v[28:31], v[38:39], off offset:1024
	s_nop 0
	global_load_dwordx4 v[32:35], v40, s[40:41] offset:1024
	global_load_dwordx4 v[100:103], v[38:39], off offset:2048
	global_load_dwordx4 v[104:107], v40, s[40:41] offset:2048
	global_load_dwordx4 v[108:111], v[38:39], off offset:3072
	global_load_dwordx4 v[112:115], v40, s[40:41] offset:3072
	v_mul_f32_e32 v8, v8, v64
	v_mul_f32_e32 v9, v9, v64
	v_mul_f32_e32 v10, v10, v64
	v_mul_f32_e32 v11, v11, v64
	v_mul_f32_e32 v4, v4, v64
	v_mul_f32_e32 v5, v5, v64
	v_mul_f32_e32 v6, v6, v64
	v_mul_f32_e32 v7, v7, v64
	v_mul_f32_e32 v60, v0, v64
	v_mul_f32_e32 v61, v1, v64
	v_mul_f32_e32 v62, v2, v64
	v_mul_f32_e32 v63, v3, v64
	v_mov_b64_e32 v[0:1], v[12:13]
	v_mov_b64_e32 v[2:3], v[14:15]
	s_waitcnt vmcnt(5)
	v_add_f32_e32 v30, 1.0, v30
	v_add_f32_e32 v31, 1.0, v31
	v_add_f32_e32 v28, 1.0, v28
	v_add_f32_e32 v29, 1.0, v29
	s_waitcnt vmcnt(4)
	v_fma_f32 v10, v30, v10, v34
	v_fma_f32 v11, v31, v11, v35
	v_fma_f32 v8, v28, v8, v32
	v_fma_f32 v9, v29, v9, v33
	v_bfe_u32 v30, v10, 16, 1
	v_bfe_u32 v28, v8, 16, 1
	v_bfe_u32 v29, v9, 16, 1
	v_bfe_u32 v31, v11, 16, 1
	v_add3_u32 v8, v8, v28, s55
	v_add3_u32 v10, v10, v30, s55
	v_add3_u32 v9, v9, v29, s55
	v_add3_u32 v11, v11, v31, s55
	v_lshrrev_b32_e32 v8, 16, v8
	v_lshrrev_b32_e32 v10, 16, v10
	v_and_or_b32 v8, v9, s56, v8
	v_and_or_b32 v9, v11, s56, v10
	global_store_dwordx2 v[50:51], v[8:9], off offset:512
	s_nop 0
	s_waitcnt vmcnt(4)
	v_add_f32_e32 v10, 1.0, v102
	v_add_f32_e32 v11, 1.0, v103
	v_add_f32_e32 v8, 1.0, v100
	v_add_f32_e32 v9, 1.0, v101
	s_waitcnt vmcnt(3)
	v_fma_f32 v6, v6, v10, v106
	v_fma_f32 v7, v7, v11, v107
	v_fma_f32 v4, v4, v8, v104
	v_fma_f32 v5, v5, v9, v105
	v_bfe_u32 v10, v6, 16, 1
	v_bfe_u32 v8, v4, 16, 1
	v_bfe_u32 v9, v5, 16, 1
	v_bfe_u32 v11, v7, 16, 1
	v_add3_u32 v4, v4, v8, s55
	v_add3_u32 v6, v6, v10, s55
	v_add3_u32 v5, v5, v9, s55
	v_add3_u32 v7, v7, v11, s55
	v_lshrrev_b32_e32 v4, 16, v4
	v_lshrrev_b32_e32 v6, 16, v6
	v_and_or_b32 v4, v5, s56, v4
	v_and_or_b32 v5, v7, s56, v6
	global_store_dwordx2 v[50:51], v[4:5], off offset:1024
	s_nop 0
	v_mov_b64_e32 v[4:5], v[16:17]
	v_mov_b64_e32 v[8:9], v[20:21]
	v_mov_b64_e32 v[30:31], v[26:27]
	v_mov_b64_e32 v[6:7], v[18:19]
	v_mov_b64_e32 v[10:11], v[22:23]
	v_mov_b64_e32 v[28:29], v[24:25]
	s_waitcnt vmcnt(3)
	v_add_f32_e32 v34, 1.0, v110
	v_add_f32_e32 v35, 1.0, v111
	v_add_f32_e32 v32, 1.0, v108
	v_add_f32_e32 v33, 1.0, v109
	s_waitcnt vmcnt(2)
	v_fma_f32 v34, v62, v34, v114
	v_fma_f32 v35, v63, v35, v115
	v_fma_f32 v32, v60, v32, v112
	v_fma_f32 v33, v61, v33, v113
	v_bfe_u32 v38, v34, 16, 1
	v_bfe_u32 v36, v32, 16, 1
	v_bfe_u32 v37, v33, 16, 1
	v_bfe_u32 v39, v35, 16, 1
	v_add3_u32 v32, v32, v36, s55
	v_add3_u32 v34, v34, v38, s55
	v_add3_u32 v33, v33, v37, s55
	v_add3_u32 v35, v35, v39, s55
	v_lshrrev_b32_e32 v32, 16, v32
	v_lshrrev_b32_e32 v34, 16, v34
	v_and_or_b32 v32, v33, s56, v32
	v_and_or_b32 v33, v35, s56, v34
	global_store_dwordx2 v[50:51], v[32:33], off offset:1536
	s_cbranch_scc0 .LBB0_967

; __device__ __forceinline__ void norm_mod_phase(const float* lat, long lat_bs, const float* cx, long ctx_bs, const float* modl, int shoff, int scoff, bf16* XN, int skip_ctx, int gw, int NGW, float* xcopy, const float* part, int nkc, const float* pgate) {
;     ...
;         if (skip_ctx && s == 4) continue;
; #pragma unroll
;         for (int j = 0; j < 4; ++j) ss += (v[j].x * v[j].x + v[j].y * v[j].y) + (v[j].z * v[j].z + v[j].w * v[j].w);
.LBB0_963:
	s_cmp_eq_u32 s57, 4
	s_mov_b64 s[40:41], -1
	s_cbranch_scc1 .LBB0_965
	v_mul_f32_e32 v32, v30, v30
	v_mul_f32_e32 v33, v31, v31
	v_mul_f32_e32 v34, v28, v28
	v_mul_f32_e32 v35, v29, v29
	v_mov_b32_e32 v37, v33
	v_mov_b32_e32 v36, v34
	v_pk_mov_b32 v[32:33], v[34:35], v[32:33] op_sel:[1,0]
	v_mul_f32_e32 v34, v10, v10
	v_mul_f32_e32 v35, v11, v11
	v_add_f32_e32 v32, v32, v36
	v_add_f32_e32 v33, v33, v37
	v_mul_f32_e32 v36, v8, v8
	v_mul_f32_e32 v37, v9, v9
	v_add_f32_e32 v33, v32, v33
	v_add_f32_e32 v32, v32, v32
	v_mov_b32_e32 v38, v36
	v_mov_b32_e32 v39, v35
	v_pk_mov_b32 v[34:35], v[36:37], v[34:35] op_sel:[1,0]
	v_mul_f32_e32 v32, v4, v4
	v_add_f32_e32 v34, v34, v38
	v_add_f32_e32 v35, v35, v39
	v_fma_f32 v36, v4, v4, v32
	v_fma_f32 v37, v5, v5, v32
	v_mul_f32_e32 v32, v6, v6
	v_add_f32_e32 v35, v34, v35
	v_add_f32_e32 v34, v34, v34
	v_fma_f32 v38, v6, v6, v32
	v_fma_f32 v39, v7, v7, v32
	v_mul_f32_e32 v36, v0, v0
	v_mul_f32_e32 v38, v1, v1
	v_mul_f32_e32 v34, v2, v2
	v_mul_f32_e32 v32, v3, v3
	v_add_f32_e32 v36, v36, v38
	v_add_f32_e32 v37, v37, v39
	v_add_f32_e32 v32, v34, v32
	v_add_f32_e32 v33, v35, v33
	s_ashr_i32 s7, s36, 31
	v_add_f32_e32 v32, v36, v32
	v_add_f32_e32 v33, v37, v33
	s_mov_b32 s6, s36
	v_add_f32_e32 v32, v32, v33
	s_cbranch_execnz .LBB0_960
	s_branch .LBB0_966

; __device__ __forceinline__ void norm_mod_phase(const float* lat, long lat_bs, const float* cx, long ctx_bs, const float* modl, int shoff, int scoff, bf16* XN, int skip_ctx, int gw, int NGW, float* xcopy, const float* part, int nkc, const float* pgate) {
;     ...
;         if (xcopy && s == 4) {
;             const int b_ = row / TPB, cr = b_ * CTXL + (row - b_ * TPB); const f32x4* gp = (const f32x4*)(pgate + 4 * NMOD6) + lane;
;             f32x4 sm[4];
; #pragma unroll
;             for (int j = 0; j < 4; ++j) sm[j] = (f32x4){0.f, 0.f, 0.f, 0.f};
;             for (int kc = 0; kc < nkc; ++kc) { const f32x4* pp = (const f32x4*)(part + ((size_t)kc * 1024 + cr) * DMODEL) + lane;
; #pragma unroll
;                 for (int j = 0; j < 4; ++j) sm[j] += pp[64 * j]; }
;             f32x4* xc = (f32x4*)(xcopy + (size_t)row * DMODEL) + lane; ss = 0.f;
; #pragma unroll
;             for (int j = 0; j < 4; ++j) { v[j] += gp[64 * j] * sm[j]; xc[64 * j] = v[j]; ss += (v[j].x * v[j].x + v[j].y * v[j].y) + (v[j].z * v[j].z + v[j].w * v[j].w); } }
.LBB0_966:
	s_mul_hi_i32 s6, s36, 0xc1f07c1f
	s_lshr_b32 s7, s6, 31
	s_lshr_b32 s6, s6, 11
	s_add_i32 s6, s6, s7
	s_lshl_b32 s6, s6, 13
	s_add_i32 s6, s36, s6
	s_ashr_i32 s7, s6, 31
	s_lshl_b64 s[6:7], s[6:7], 12
	v_lshl_add_u64 v[50:51], v[44:45], 0, s[6:7]
	v_add_co_u32_e32 v152, vcc, s1, v50
	global_load_dwordx4 v[32:35], v[50:51], off
	s_nop 0
	v_addc_co_u32_e32 v153, vcc, 0, v51, vcc
	v_add_co_u32_e32 v160, vcc, s3, v50
	global_load_dwordx4 v[36:39], v[152:153], off
	s_nop 0
	v_addc_co_u32_e32 v161, vcc, 0, v51, vcc
	v_add_co_u32_e32 v168, vcc, s4, v50
	global_load_dwordx4 v[60:63], v[160:161], off
	s_nop 0
	v_addc_co_u32_e32 v169, vcc, 0, v51, vcc
	v_add_co_u32_e32 v176, vcc, s5, v50
	global_load_dwordx4 v[64:67], v[168:169], off
	s_nop 0
	v_addc_co_u32_e32 v177, vcc, 0, v51, vcc
	v_add_co_u32_e32 v180, vcc, s12, v50
	global_load_dwordx4 v[68:71], v[176:177], off
	s_nop 0
	v_addc_co_u32_e32 v181, vcc, 0, v51, vcc
	v_add_co_u32_e32 v182, vcc, s13, v50
	global_load_dwordx4 v[72:75], v[180:181], off
	s_nop 0
	v_addc_co_u32_e32 v183, vcc, 0, v51, vcc
	v_add_co_u32_e32 v184, vcc, s14, v50
	global_load_dwordx4 v[76:79], v[182:183], off
	s_nop 0
	v_addc_co_u32_e32 v185, vcc, 0, v51, vcc
	v_add_co_u32_e32 v186, vcc, s15, v50
	global_load_dwordx4 v[80:83], v[184:185], off
	s_nop 0
	v_addc_co_u32_e32 v187, vcc, 0, v51, vcc
	v_add_co_u32_e32 v188, vcc, s33, v50
	global_load_dwordx4 v[84:87], v[186:187], off
	s_nop 0
	v_addc_co_u32_e32 v189, vcc, 0, v51, vcc
	global_load_dwordx4 v[88:91], v[188:189], off
	v_add_co_u32_e32 v190, vcc, s52, v50
	s_mov_b64 s[6:7], s[36:37]
	s_nop 0
	v_addc_co_u32_e32 v191, vcc, 0, v51, vcc
	global_load_dwordx4 v[92:95], v[190:191], off
	global_load_dwordx4 v[96:99], v[42:43], off
	global_load_dwordx4 v[100:103], v[50:51], off offset:3072
	global_load_dwordx4 v[104:107], v[152:153], off offset:3072
	global_load_dwordx4 v[108:111], v[160:161], off offset:3072
	global_load_dwordx4 v[112:115], v[168:169], off offset:3072
	global_load_dwordx4 v[116:119], v[176:177], off offset:3072
	global_load_dwordx4 v[120:123], v[180:181], off offset:3072
	global_load_dwordx4 v[124:127], v[182:183], off offset:3072
	global_load_dwordx4 v[128:131], v[184:185], off offset:3072
	global_load_dwordx4 v[132:135], v[186:187], off offset:3072
	global_load_dwordx4 v[136:139], v[188:189], off offset:3072
	global_load_dwordx4 v[140:143], v[50:51], off offset:1024
	global_load_dwordx4 v[144:147], v[50:51], off offset:2048
	global_load_dwordx4 v[148:151], v[152:153], off offset:1024
	s_nop 0
	global_load_dwordx4 v[152:155], v[152:153], off offset:2048
	s_nop 0
	global_load_dwordx4 v[156:159], v[160:161], off offset:1024
	s_nop 0
	global_load_dwordx4 v[160:163], v[160:161], off offset:2048
	s_nop 0
	global_load_dwordx4 v[164:167], v[168:169], off offset:1024
	s_nop 0
	global_load_dwordx4 v[168:171], v[168:169], off offset:2048
	s_nop 0
	global_load_dwordx4 v[172:175], v[176:177], off offset:1024
	s_nop 0
	global_load_dwordx4 v[176:179], v[176:177], off offset:2048
	s_waitcnt vmcnt(31)
	v_add_f32_e32 v34, 0, v34
	v_add_f32_e32 v35, 0, v35
	v_add_f32_e32 v32, 0, v32
	v_add_f32_e32 v33, 0, v33
	s_waitcnt vmcnt(30)
	v_add_f32_e32 v34, v34, v38
	v_add_f32_e32 v35, v35, v39
	v_add_f32_e32 v32, v32, v36
	v_add_f32_e32 v33, v33, v37
	s_waitcnt vmcnt(29)
	v_add_f32_e32 v34, v34, v62
	v_add_f32_e32 v35, v35, v63
	v_add_f32_e32 v32, v32, v60
	v_add_f32_e32 v33, v33, v61
	s_waitcnt vmcnt(28)
	v_add_f32_e32 v34, v34, v66
	v_add_f32_e32 v35, v35, v67
	v_add_f32_e32 v32, v32, v64
	v_add_f32_e32 v33, v33, v65
	s_waitcnt vmcnt(27)
	v_add_f32_e32 v34, v34, v70
	v_add_f32_e32 v35, v35, v71
	v_add_f32_e32 v32, v32, v68
	v_add_f32_e32 v33, v33, v69
	s_waitcnt vmcnt(26)
	v_add_f32_e32 v50, v34, v74
	v_add_f32_e32 v51, v35, v75
	v_add_f32_e32 v60, v32, v72
	v_add_f32_e32 v61, v33, v73
	global_load_dwordx4 v[32:35], v[180:181], off offset:1024
	global_load_dwordx4 v[36:39], v[180:181], off offset:2048
	s_waitcnt vmcnt(27)
	v_add_f32_e32 v50, v50, v78
	v_add_f32_e32 v51, v51, v79
	v_add_f32_e32 v68, v60, v76
	v_add_f32_e32 v69, v61, v77
	global_load_dwordx4 v[60:63], v[182:183], off offset:1024
	global_load_dwordx4 v[64:67], v[182:183], off offset:2048
	s_waitcnt vmcnt(28)
	v_add_f32_e32 v50, v50, v82
	v_add_f32_e32 v51, v51, v83
	v_add_f32_e32 v76, v68, v80
	v_add_f32_e32 v77, v69, v81
	global_load_dwordx4 v[68:71], v[184:185], off offset:1024
	global_load_dwordx4 v[72:75], v[184:185], off offset:2048
	s_waitcnt vmcnt(29)
	v_add_f32_e32 v50, v50, v86
	v_add_f32_e32 v51, v51, v87
	v_add_f32_e32 v84, v76, v84
	v_add_f32_e32 v85, v77, v85
	global_load_dwordx4 v[76:79], v[186:187], off offset:1024
	global_load_dwordx4 v[80:83], v[186:187], off offset:2048
	s_waitcnt vmcnt(30)
	v_add_f32_e32 v50, v50, v90
	v_add_f32_e32 v51, v51, v91
	v_add_f32_e32 v180, v84, v88
	v_add_f32_e32 v181, v85, v89
	global_load_dwordx4 v[84:87], v[188:189], off offset:1024
	global_load_dwordx4 v[88:91], v[188:189], off offset:2048
	s_waitcnt vmcnt(31)
	v_add_f32_e32 v50, v50, v94
	v_add_f32_e32 v51, v51, v95
	v_add_f32_e32 v188, v180, v92
	v_add_f32_e32 v189, v181, v93
	s_waitcnt vmcnt(30)
	v_fma_f32 v30, v50, v98, v30
	v_fma_f32 v31, v51, v99, v31
	v_fma_f32 v28, v188, v96, v28
	v_fma_f32 v29, v189, v97, v29
	global_load_dwordx4 v[92:95], v[190:191], off offset:1024
	global_load_dwordx4 v[180:183], v[190:191], off offset:2048
	global_load_dwordx4 v[184:187], v[190:191], off offset:3072
	s_waitcnt vmcnt(22)
	v_add_f32_e32 v50, 0, v142
	v_add_f32_e32 v51, 0, v143
	global_store_dwordx4 v[48:49], v[28:31], off
	global_load_dwordx4 v[96:99], v[42:43], off offset:1024
	v_add_f32_e32 v140, 0, v140
	v_add_f32_e32 v141, 0, v141
	s_waitcnt vmcnt(22)
; __device__ __forceinline__ void norm_mod_phase(const float* lat, long lat_bs, const float* cx, long ctx_bs, const float* modl, int shoff, int scoff, bf16* XN, int skip_ctx, int gw, int NGW, float* xcopy, const float* part, int nkc, const float* pgate) {
;     ...
;         if (xcopy && s == 4) {
;             const int b_ = row / TPB, cr = b_ * CTXL + (row - b_ * TPB); const f32x4* gp = (const f32x4*)(pgate + 4 * NMOD6) + lane;
;             f32x4 sm[4];
; #pragma unroll
;             for (int j = 0; j < 4; ++j) sm[j] = (f32x4){0.f, 0.f, 0.f, 0.f};
;             for (int kc = 0; kc < nkc; ++kc) { const f32x4* pp = (const f32x4*)(part + ((size_t)kc * 1024 + cr) * DMODEL) + lane;
; #pragma unroll
;                 for (int j = 0; j < 4; ++j) sm[j] += pp[64 * j]; }
;             f32x4* xc = (f32x4*)(xcopy + (size_t)row * DMODEL) + lane; ss = 0.f;
; #pragma unroll
;             for (int j = 0; j < 4; ++j) { v[j] += gp[64 * j] * sm[j]; xc[64 * j] = v[j]; ss += (v[j].x * v[j].x + v[j].y * v[j].y) + (v[j].z * v[j].z + v[j].w * v[j].w); } }
	v_add_f32_e32 v50, v50, v150
	v_add_f32_e32 v51, v51, v151
	v_add_f32_e32 v140, v140, v148
	v_add_f32_e32 v141, v141, v149
	s_waitcnt vmcnt(20)
	v_add_f32_e32 v50, v50, v158
	v_add_f32_e32 v51, v51, v159
	v_add_f32_e32 v140, v140, v156
	v_add_f32_e32 v141, v141, v157
	s_waitcnt vmcnt(18)
	v_add_f32_e32 v50, v50, v166
	v_add_f32_e32 v51, v51, v167
	v_add_f32_e32 v140, v140, v164
	v_add_f32_e32 v141, v141, v165
	s_waitcnt vmcnt(16)
	v_add_f32_e32 v50, v50, v174
	v_add_f32_e32 v51, v51, v175
	v_add_f32_e32 v140, v140, v172
	v_add_f32_e32 v141, v141, v173
	s_waitcnt vmcnt(14)
	v_add_f32_e32 v34, v50, v34
	v_add_f32_e32 v35, v51, v35
	v_add_f32_e32 v32, v140, v32
	v_add_f32_e32 v33, v141, v33
	v_add_f32_e32 v50, 0, v146
	v_add_f32_e32 v51, 0, v147
	s_waitcnt vmcnt(12)
	v_add_f32_e32 v34, v34, v62
	v_add_f32_e32 v35, v35, v63
	v_add_f32_e32 v32, v32, v60
	v_add_f32_e32 v33, v33, v61
	v_add_f32_e32 v60, 0, v144
	v_add_f32_e32 v61, 0, v145
	v_add_f32_e32 v50, v50, v154
	v_add_f32_e32 v51, v51, v155
	v_add_f32_e32 v60, v60, v152
	v_add_f32_e32 v61, v61, v153
	s_waitcnt vmcnt(10)
	v_add_f32_e32 v34, v34, v70
	v_add_f32_e32 v35, v35, v71
	v_add_f32_e32 v32, v32, v68
	v_add_f32_e32 v33, v33, v69
	v_add_f32_e32 v50, v50, v162
	v_add_f32_e32 v51, v51, v163
	v_add_f32_e32 v60, v60, v160
	v_add_f32_e32 v61, v61, v161
	v_add_f32_e32 v50, v50, v170
	v_add_f32_e32 v51, v51, v171
	s_waitcnt vmcnt(8)
	v_add_f32_e32 v34, v34, v78
	v_add_f32_e32 v35, v35, v79
	v_add_f32_e32 v32, v32, v76
	v_add_f32_e32 v33, v33, v77
	v_add_f32_e32 v60, v60, v168
	v_add_f32_e32 v61, v61, v169
	s_waitcnt vmcnt(6)
	v_add_f32_e32 v34, v34, v86
	v_add_f32_e32 v35, v35, v87
	v_add_f32_e32 v32, v32, v84
	v_add_f32_e32 v33, v33, v85
	v_add_f32_e32 v50, v50, v178
	v_add_f32_e32 v51, v51, v179
	v_add_f32_e32 v60, v60, v176
	v_add_f32_e32 v61, v61, v177
	s_waitcnt vmcnt(4)
	v_add_f32_e32 v34, v34, v94
	v_add_f32_e32 v35, v35, v95
	v_add_f32_e32 v32, v32, v92
	v_add_f32_e32 v33, v33, v93
	v_add_f32_e32 v38, v50, v38
	v_add_f32_e32 v39, v51, v39
	v_add_f32_e32 v36, v60, v36
	v_add_f32_e32 v37, v61, v37
	v_add_f32_e32 v38, v38, v66
	v_add_f32_e32 v39, v39, v67
	s_waitcnt vmcnt(0)
	v_fma_f32 v10, v34, v98, v10
	v_fma_f32 v11, v35, v99, v11
	v_fma_f32 v8, v32, v96, v8
	v_fma_f32 v9, v33, v97, v9
	global_store_dwordx4 v[48:49], v[8:11], off offset:1024
	global_load_dwordx4 v[32:35], v[42:43], off offset:2048
	v_add_f32_e32 v36, v36, v64
	v_add_f32_e32 v37, v37, v65
	v_add_f32_e32 v38, v38, v74
	v_add_f32_e32 v39, v39, v75
	v_add_f32_e32 v36, v36, v72
	v_add_f32_e32 v37, v37, v73
	v_add_f32_e32 v38, v38, v82
	v_add_f32_e32 v39, v39, v83
	v_add_f32_e32 v36, v36, v80
	v_add_f32_e32 v37, v37, v81
	v_add_f32_e32 v38, v38, v90
	v_add_f32_e32 v39, v39, v91
	v_add_f32_e32 v36, v36, v88
	v_add_f32_e32 v37, v37, v89
	v_add_f32_e32 v38, v38, v182
	v_add_f32_e32 v39, v39, v183
	v_add_f32_e32 v36, v36, v180
	v_add_f32_e32 v37, v37, v181
	v_mul_f32_e32 v50, v30, v30
	v_mul_f32_e32 v51, v31, v31
	v_mul_f32_e32 v60, v28, v28
	v_mul_f32_e32 v61, v29, v29
	s_waitcnt vmcnt(0)
	v_fma_f32 v6, v38, v34, v6
	v_fma_f32 v7, v39, v35, v7
	v_fma_f32 v4, v36, v32, v4
	v_fma_f32 v5, v37, v33, v5
	global_store_dwordx4 v[48:49], v[4:7], off offset:2048
	global_load_dwordx4 v[32:35], v[42:43], off offset:3072
	v_add_f32_e32 v36, 0, v102
	v_add_f32_e32 v37, 0, v103
	v_add_f32_e32 v38, 0, v100
	v_add_f32_e32 v39, 0, v101
	v_add_f32_e32 v36, v36, v106
	v_add_f32_e32 v37, v37, v107
	v_add_f32_e32 v38, v38, v104
	v_add_f32_e32 v39, v39, v105
	v_add_f32_e32 v36, v36, v110
	v_add_f32_e32 v37, v37, v111
	v_add_f32_e32 v38, v38, v108
	v_add_f32_e32 v39, v39, v109
	v_add_f32_e32 v36, v36, v114
	v_add_f32_e32 v37, v37, v115
	v_add_f32_e32 v38, v38, v112
	v_add_f32_e32 v39, v39, v113
	v_add_f32_e32 v36, v36, v118
	v_add_f32_e32 v37, v37, v119
	v_add_f32_e32 v38, v38, v116
	v_add_f32_e32 v39, v39, v117
	v_add_f32_e32 v36, v36, v122
	v_add_f32_e32 v37, v37, v123
	v_add_f32_e32 v38, v38, v120
	v_add_f32_e32 v39, v39, v121
	v_add_f32_e32 v36, v36, v126
	v_add_f32_e32 v37, v37, v127
	v_add_f32_e32 v38, v38, v124
	v_add_f32_e32 v39, v39, v125
	v_add_f32_e32 v36, v36, v130
	v_add_f32_e32 v37, v37, v131
	v_add_f32_e32 v38, v38, v128
	v_add_f32_e32 v39, v39, v129
	v_pk_mov_b32 v[62:63], v[60:61], v[50:51] op_sel:[1,0]
	v_mov_b32_e32 v61, v51
	v_add_f32_e32 v36, v36, v134
	v_add_f32_e32 v37, v37, v135
	v_add_f32_e32 v38, v38, v132
	v_add_f32_e32 v39, v39, v133
	v_add_f32_e32 v50, v62, v60
	v_add_f32_e32 v51, v63, v61
	v_mul_f32_e32 v60, v10, v10
	v_mul_f32_e32 v61, v11, v11
	v_mul_f32_e32 v62, v8, v8
	v_mul_f32_e32 v63, v9, v9
	v_add_f32_e32 v36, v36, v138
	v_add_f32_e32 v37, v37, v139
	v_add_f32_e32 v38, v38, v136
	v_add_f32_e32 v39, v39, v137
	v_pk_mov_b32 v[64:65], v[62:63], v[60:61] op_sel:[1,0]
	v_mov_b32_e32 v63, v61
	v_add_f32_e32 v36, v36, v186
	v_add_f32_e32 v37, v37, v187
	v_add_f32_e32 v38, v38, v184
	v_add_f32_e32 v39, v39, v185
	v_add_f32_e32 v60, v64, v62
	v_add_f32_e32 v61, v65, v63
	v_mul_f32_e32 v62, v5, v5
	v_mul_f32_e32 v64, v7, v7
	v_pk_add_f32 v[50:51], v[50:51], v[50:51] op_sel:[0,1] op_sel_hi:[1,0]
	v_pk_add_f32 v[60:61], v[60:61], v[60:61] op_sel:[0,1] op_sel_hi:[1,0]
	v_fma_f32 v63, v5, v5, v62
	v_fma_f32 v62, v4, v4, v62
	v_fma_f32 v65, v7, v7, v64
	v_fma_f32 v64, v6, v6, v64
	s_waitcnt vmcnt(0)
	v_fma_f32 v2, v36, v34, v2
	v_fma_f32 v3, v37, v35, v3
	v_fma_f32 v0, v38, v32, v0
	v_fma_f32 v1, v39, v33, v1
	v_mul_f32_e32 v63, v2, v2
	v_mul_f32_e32 v51, v0, v0
	v_mul_f32_e32 v61, v1, v1
	v_mul_f32_e32 v65, v3, v3
	v_add_f32_e32 v32, v50, v60
	v_add_f32_e32 v33, v51, v61
	v_add_f32_e32 v34, v62, v64
	v_add_f32_e32 v35, v63, v65
	global_store_dwordx4 v[48:49], v[0:3], off offset:3072
	v_add_f32_e32 v32, v32, v34
	v_add_f32_e32 v33, v33, v35
	s_nop 0
	v_add_f32_e32 v32, v32, v33
	s_branch .LBB0_960

.LBB0_1127:
	v_add_u32_e32 v178, s84, v248
	ds_read_b128 v[82:85], v178
	ds_read_b128 v[198:201], v178 offset:512
	s_waitcnt lgkmcnt(14)
	v_mfma_f32_32x32x16_bf16 v[34:49], v[154:157], v[106:109], v[34:49]
	v_exp_f32_e32 v130, v130
	v_exp_f32_e32 v131, v131
	v_exp_f32_e32 v132, v132
	ds_read_b64_tr_b16 v[106:107], v216 offset:37888
	ds_read_b64_tr_b16 v[108:109], v216 offset:38400
	ds_read_b128 v[202:205], v178 offset:2048
	ds_read_b128 v[190:193], v178 offset:2560
	v_mfma_f32_32x32x16_bf16 v[50:65], v[150:153], v[102:105], v[50:65]
	v_exp_f32_e32 v133, v133
	v_exp_f32_e32 v134, v134
	v_exp_f32_e32 v135, v135
	ds_read_b64_tr_b16 v[102:103], v216 offset:34816
	ds_read_b64_tr_b16 v[104:105], v216 offset:35328
	ds_read_b128 v[194:197], v178 offset:4096
	ds_read_b128 v[182:185], v178 offset:4608
	s_waitcnt lgkmcnt(14)
	v_mfma_f32_32x32x16_bf16 v[34:49], v[150:153], v[98:101], v[34:49]
	v_exp_f32_e32 v136, v136
	v_exp_f32_e32 v137, v137
	v_exp_f32_e32 v138, v138
	ds_read_b64_tr_b16 v[98:99], v216 offset:38912
	ds_read_b64_tr_b16 v[100:101], v216 offset:39424
	ds_read_b128 v[186:189], v178 offset:6144
	ds_read_b128 v[178:181], v178 offset:6656
	v_mfma_f32_32x32x16_bf16 v[50:65], v[146:149], v[86:89], v[50:65]
	v_exp_f32_e32 v139, v139
	v_exp_f32_e32 v140, v140
	v_exp_f32_e32 v141, v141
	ds_read_b64_tr_b16 v[86:87], v216 offset:35840
	ds_read_b64_tr_b16 v[88:89], v216 offset:36352
	v_mfma_f32_32x32x16_bf16 v[34:49], v[146:149], v[90:93], v[34:49]
	v_exp_f32_e32 v142, v142
	v_exp_f32_e32 v143, v143
	v_exp_f32_e32 v144, v144
	ds_read_b64_tr_b16 v[90:91], v216 offset:39936
	ds_read_b64_tr_b16 v[92:93], v216 offset:40448
	v_mfma_f32_32x32x16_bf16 v[18:33], v[158:161], v[206:209], v[18:33]
	v_exp_f32_e32 v145, v145
	v_exp_f32_e32 v114, v114
	v_exp_f32_e32 v115, v115
	s_waitcnt lgkmcnt(14)
	v_mfma_f32_32x32x16_bf16 v[2:17], v[158:161], v[110:113], v[2:17]
	v_exp_f32_e32 v116, v116
	v_exp_f32_e32 v117, v117
	v_mfma_f32_32x32x16_bf16 v[18:33], v[154:157], v[94:97], v[18:33]
	v_exp_f32_e32 v118, v118
	v_exp_f32_e32 v119, v119
	v_mfma_f32_32x32x16_bf16 v[2:17], v[154:157], v[106:109], v[2:17]
	v_exp_f32_e32 v120, v120
	v_exp_f32_e32 v121, v121
	s_waitcnt lgkmcnt(10)
	v_mfma_f32_32x32x16_bf16 v[18:33], v[150:153], v[102:105], v[18:33]
	v_exp_f32_e32 v122, v122
	v_exp_f32_e32 v123, v123
	s_waitcnt lgkmcnt(6)
	v_mfma_f32_32x32x16_bf16 v[2:17], v[150:153], v[98:101], v[2:17]
	v_exp_f32_e32 v124, v124
	v_exp_f32_e32 v125, v125
	s_waitcnt lgkmcnt(2)
	v_mfma_f32_32x32x16_bf16 v[18:33], v[146:149], v[86:89], v[18:33]
	v_exp_f32_e32 v126, v126
	v_exp_f32_e32 v127, v127
	s_waitcnt lgkmcnt(0)
	v_mfma_f32_32x32x16_bf16 v[2:17], v[146:149], v[90:93], v[2:17]
	v_exp_f32_e32 v128, v128
	v_exp_f32_e32 v129, v129
	s_waitcnt vmcnt(3) lgkmcnt(0)
	s_barrier
	s_andn2_b64 vcc, exec, s[86:87]
	s_cbranch_vccnz .LBB0_1129
	s_waitcnt lgkmcnt(0)
	v_add_u32_e32 v98, s3, v245
	ds_read_b128 v[86:89], v98 offset:96
	ds_read_b128 v[90:93], v98 offset:64
	ds_read_b128 v[94:97], v98 offset:32
	ds_read_b128 v[98:101], v98
	s_waitcnt lgkmcnt(3)
	v_mul_f32_e32 v62, v62, v86
	v_mul_f32_e32 v63, v63, v87
	s_waitcnt lgkmcnt(2)
	v_mul_f32_e32 v58, v58, v90
	v_mul_f32_e32 v59, v59, v91
	s_waitcnt lgkmcnt(1)
	v_mul_f32_e32 v54, v54, v94
	v_mul_f32_e32 v55, v55, v95
	v_mul_f32_e32 v64, v64, v88
	v_mul_f32_e32 v65, v65, v89
	v_mul_f32_e32 v60, v60, v92
	v_mul_f32_e32 v61, v61, v93
	v_mul_f32_e32 v56, v56, v96
	v_mul_f32_e32 v57, v57, v97
	s_waitcnt lgkmcnt(0)
	v_mul_f32_e32 v52, v52, v100
	v_mul_f32_e32 v53, v53, v101
	v_mul_f32_e32 v50, v50, v98
	v_mul_f32_e32 v51, v51, v99
	v_mul_f32_e32 v46, v46, v86
	v_mul_f32_e32 v47, v47, v87
	v_mul_f32_e32 v42, v42, v90
	v_mul_f32_e32 v43, v43, v91
	v_mul_f32_e32 v38, v38, v94
	v_mul_f32_e32 v39, v39, v95
	v_mul_f32_e32 v48, v48, v88
	v_mul_f32_e32 v49, v49, v89
	v_mul_f32_e32 v44, v44, v92
	v_mul_f32_e32 v45, v45, v93
	v_mul_f32_e32 v40, v40, v96
	v_mul_f32_e32 v41, v41, v97
	v_mul_f32_e32 v36, v36, v100
	v_mul_f32_e32 v37, v37, v101
	v_mul_f32_e32 v34, v34, v98
	v_mul_f32_e32 v35, v35, v99
	v_mul_f32_e32 v30, v30, v86
	v_mul_f32_e32 v31, v31, v87
	v_mul_f32_e32 v26, v26, v90
	v_mul_f32_e32 v27, v27, v91
	v_mul_f32_e32 v22, v22, v94
	v_mul_f32_e32 v23, v23, v95
	v_mul_f32_e32 v32, v32, v88
	v_mul_f32_e32 v33, v33, v89
	v_mul_f32_e32 v28, v28, v92
	v_mul_f32_e32 v29, v29, v93
	v_mul_f32_e32 v24, v24, v96
	v_mul_f32_e32 v25, v25, v97
	v_mul_f32_e32 v20, v20, v100
	v_mul_f32_e32 v21, v21, v101
	v_mul_f32_e32 v18, v18, v98
	v_mul_f32_e32 v19, v19, v99
	v_mul_f32_e32 v14, v14, v86
	v_mul_f32_e32 v15, v15, v87
	v_mul_f32_e32 v10, v10, v90
	v_mul_f32_e32 v11, v11, v91
	v_mul_f32_e32 v6, v6, v94
	v_mul_f32_e32 v7, v7, v95
	v_mul_f32_e32 v16, v16, v88
	v_mul_f32_e32 v17, v17, v89
	v_mul_f32_e32 v12, v12, v92
	v_mul_f32_e32 v13, v13, v93
	v_mul_f32_e32 v8, v8, v96
	v_mul_f32_e32 v9, v9, v97
	v_mul_f32_e32 v4, v4, v100
	v_mul_f32_e32 v5, v5, v101
	v_mul_f32_e32 v2, v2, v98
	v_mul_f32_e32 v3, v3, v99

.LBB0_1130:
	v_add_u32_e32 v1, s4, v248
	ds_read_b128 v[206:209], v1
	ds_read_b128 v[198:201], v1 offset:512
	s_waitcnt lgkmcnt(14)
	v_mfma_f32_32x32x16_bf16 v[34:49], v[154:157], v[138:141], v[34:49]
	v_exp_f32_e32 v98, v98
	v_exp_f32_e32 v99, v99
	v_exp_f32_e32 v100, v100
	ds_read_b64_tr_b16 v[138:139], v226 offset:37888
	ds_read_b64_tr_b16 v[140:141], v226 offset:38400
	ds_read_b128 v[202:205], v1 offset:2048
	ds_read_b128 v[194:197], v1 offset:2560
	v_mfma_f32_32x32x16_bf16 v[50:65], v[150:153], v[134:137], v[50:65]
	v_exp_f32_e32 v101, v101
	v_exp_f32_e32 v102, v102
	v_exp_f32_e32 v103, v103
	ds_read_b64_tr_b16 v[134:135], v226 offset:34816
	ds_read_b64_tr_b16 v[136:137], v226 offset:35328
	ds_read_b128 v[190:193], v1 offset:4096
	ds_read_b128 v[186:189], v1 offset:4608
	s_waitcnt lgkmcnt(14)
	v_mfma_f32_32x32x16_bf16 v[34:49], v[150:153], v[130:133], v[34:49]
	v_exp_f32_e32 v104, v104
	v_exp_f32_e32 v105, v105
	v_exp_f32_e32 v106, v106
	ds_read_b64_tr_b16 v[130:131], v226 offset:38912
	ds_read_b64_tr_b16 v[132:133], v226 offset:39424
	ds_read_b128 v[182:185], v1 offset:6144
	ds_read_b128 v[178:181], v1 offset:6656
	v_mfma_f32_32x32x16_bf16 v[50:65], v[146:149], v[114:117], v[50:65]
	v_exp_f32_e32 v107, v107
	v_exp_f32_e32 v108, v108
	v_exp_f32_e32 v109, v109
	ds_read_b64_tr_b16 v[114:115], v226 offset:35840
	ds_read_b64_tr_b16 v[116:117], v226 offset:36352
	v_mfma_f32_32x32x16_bf16 v[34:49], v[146:149], v[118:121], v[34:49]
	v_exp_f32_e32 v110, v110
	v_exp_f32_e32 v111, v111
	v_exp_f32_e32 v112, v112
	ds_read_b64_tr_b16 v[118:119], v226 offset:39936
	ds_read_b64_tr_b16 v[120:121], v226 offset:40448
	v_mfma_f32_32x32x16_bf16 v[18:33], v[158:161], v[142:145], v[18:33]
	v_exp_f32_e32 v113, v113
	v_exp_f32_e32 v82, v82
	v_exp_f32_e32 v83, v83
	s_waitcnt lgkmcnt(14)
	v_mfma_f32_32x32x16_bf16 v[2:17], v[158:161], v[126:129], v[2:17]
	v_exp_f32_e32 v84, v84
	v_exp_f32_e32 v85, v85
	v_mfma_f32_32x32x16_bf16 v[18:33], v[154:157], v[122:125], v[18:33]
	v_exp_f32_e32 v86, v86
	v_exp_f32_e32 v87, v87
	v_mfma_f32_32x32x16_bf16 v[2:17], v[154:157], v[138:141], v[2:17]
	v_exp_f32_e32 v88, v88
	v_exp_f32_e32 v89, v89
	s_waitcnt lgkmcnt(10)
	v_mfma_f32_32x32x16_bf16 v[18:33], v[150:153], v[134:137], v[18:33]
	v_exp_f32_e32 v90, v90
	v_exp_f32_e32 v91, v91
	s_waitcnt lgkmcnt(6)
	v_mfma_f32_32x32x16_bf16 v[2:17], v[150:153], v[130:133], v[2:17]
	v_exp_f32_e32 v92, v92
	v_exp_f32_e32 v93, v93
	s_waitcnt lgkmcnt(2)
	v_mfma_f32_32x32x16_bf16 v[18:33], v[146:149], v[114:117], v[18:33]
	v_exp_f32_e32 v94, v94
	v_exp_f32_e32 v95, v95
	s_waitcnt lgkmcnt(0)
	v_mfma_f32_32x32x16_bf16 v[2:17], v[146:149], v[118:121], v[2:17]
	v_exp_f32_e32 v96, v96
	v_exp_f32_e32 v97, v97
	s_waitcnt vmcnt(3) lgkmcnt(0)
	s_barrier
	s_andn2_b64 vcc, exec, s[86:87]
	s_cbranch_vccnz .LBB0_1132
	s_waitcnt lgkmcnt(0)
	v_add_u32_e32 v1, s3, v245
	ds_read_b128 v[114:117], v1 offset:96
	ds_read_b128 v[118:121], v1 offset:64
	ds_read_b128 v[122:125], v1 offset:32
	ds_read_b128 v[126:129], v1
	s_waitcnt lgkmcnt(3)
	v_mul_f32_e32 v62, v62, v114
	v_mul_f32_e32 v63, v63, v115
	s_waitcnt lgkmcnt(2)
	v_mul_f32_e32 v58, v58, v118
	v_mul_f32_e32 v59, v59, v119
	s_waitcnt lgkmcnt(1)
	v_mul_f32_e32 v54, v54, v122
	v_mul_f32_e32 v55, v55, v123
	v_mul_f32_e32 v64, v64, v116
	v_mul_f32_e32 v65, v65, v117
	v_mul_f32_e32 v60, v60, v120
	v_mul_f32_e32 v61, v61, v121
	v_mul_f32_e32 v56, v56, v124
	v_mul_f32_e32 v57, v57, v125
	s_waitcnt lgkmcnt(0)
	v_mul_f32_e32 v52, v52, v128
	v_mul_f32_e32 v53, v53, v129
	v_mul_f32_e32 v50, v50, v126
	v_mul_f32_e32 v51, v51, v127
	v_mul_f32_e32 v46, v46, v114
	v_mul_f32_e32 v47, v47, v115
	v_mul_f32_e32 v42, v42, v118
	v_mul_f32_e32 v43, v43, v119
	v_mul_f32_e32 v38, v38, v122
	v_mul_f32_e32 v39, v39, v123
	v_mul_f32_e32 v48, v48, v116
	v_mul_f32_e32 v49, v49, v117
	v_mul_f32_e32 v44, v44, v120
	v_mul_f32_e32 v45, v45, v121
	v_mul_f32_e32 v40, v40, v124
	v_mul_f32_e32 v41, v41, v125
	v_mul_f32_e32 v36, v36, v128
	v_mul_f32_e32 v37, v37, v129
	v_mul_f32_e32 v34, v34, v126
	v_mul_f32_e32 v35, v35, v127
	v_mul_f32_e32 v30, v30, v114
	v_mul_f32_e32 v31, v31, v115
	v_mul_f32_e32 v26, v26, v118
	v_mul_f32_e32 v27, v27, v119
	v_mul_f32_e32 v22, v22, v122
	v_mul_f32_e32 v23, v23, v123
	v_mul_f32_e32 v32, v32, v116
	v_mul_f32_e32 v33, v33, v117
	v_mul_f32_e32 v28, v28, v120
	v_mul_f32_e32 v29, v29, v121
	v_mul_f32_e32 v24, v24, v124
	v_mul_f32_e32 v25, v25, v125
	v_mul_f32_e32 v20, v20, v128
	v_mul_f32_e32 v21, v21, v129
	v_mul_f32_e32 v18, v18, v126
	v_mul_f32_e32 v19, v19, v127
	v_mul_f32_e32 v14, v14, v114
	v_mul_f32_e32 v15, v15, v115
	v_mul_f32_e32 v10, v10, v118
	v_mul_f32_e32 v11, v11, v119
	v_mul_f32_e32 v6, v6, v122
	v_mul_f32_e32 v7, v7, v123
	v_mul_f32_e32 v16, v16, v116
	v_mul_f32_e32 v17, v17, v117
	v_mul_f32_e32 v12, v12, v120
	v_mul_f32_e32 v13, v13, v121
	v_mul_f32_e32 v8, v8, v124
	v_mul_f32_e32 v9, v9, v125
	v_mul_f32_e32 v4, v4, v128
	v_mul_f32_e32 v5, v5, v129
	v_mul_f32_e32 v2, v2, v126
	v_mul_f32_e32 v3, v3, v127

.LBB0_1147:
	s_waitcnt lgkmcnt(0)
	v_add_u32_e32 v98, s3, v245
	ds_read_b128 v[86:89], v98 offset:96
	ds_read_b128 v[90:93], v98 offset:64
	ds_read_b128 v[94:97], v98 offset:32
	ds_read_b128 v[98:101], v98
	s_waitcnt lgkmcnt(3)
	v_mul_f32_e32 v62, v62, v86
	v_mul_f32_e32 v63, v63, v87
	s_waitcnt lgkmcnt(2)
	v_mul_f32_e32 v58, v58, v90
	v_mul_f32_e32 v59, v59, v91
	s_waitcnt lgkmcnt(1)
	v_mul_f32_e32 v54, v54, v94
	v_mul_f32_e32 v55, v55, v95
	v_mul_f32_e32 v64, v64, v88
	v_mul_f32_e32 v65, v65, v89
	v_mul_f32_e32 v60, v60, v92
	v_mul_f32_e32 v61, v61, v93
	v_mul_f32_e32 v56, v56, v96
	v_mul_f32_e32 v57, v57, v97
	s_waitcnt lgkmcnt(0)
	v_mul_f32_e32 v52, v52, v100
	v_mul_f32_e32 v53, v53, v101
	v_mul_f32_e32 v50, v50, v98
	v_mul_f32_e32 v51, v51, v99
	v_mul_f32_e32 v46, v46, v86
	v_mul_f32_e32 v47, v47, v87
	v_mul_f32_e32 v42, v42, v90
	v_mul_f32_e32 v43, v43, v91
	v_mul_f32_e32 v38, v38, v94
	v_mul_f32_e32 v39, v39, v95
	v_mul_f32_e32 v48, v48, v88
	v_mul_f32_e32 v49, v49, v89
	v_mul_f32_e32 v44, v44, v92
	v_mul_f32_e32 v45, v45, v93
	v_mul_f32_e32 v40, v40, v96
	v_mul_f32_e32 v41, v41, v97
	v_mul_f32_e32 v36, v36, v100
	v_mul_f32_e32 v37, v37, v101
	v_mul_f32_e32 v34, v34, v98
	v_mul_f32_e32 v35, v35, v99
	v_mul_f32_e32 v30, v30, v86
	v_mul_f32_e32 v31, v31, v87
	v_mul_f32_e32 v26, v26, v90
	v_mul_f32_e32 v27, v27, v91
	v_mul_f32_e32 v22, v22, v94
	v_mul_f32_e32 v23, v23, v95
	v_mul_f32_e32 v32, v32, v88
	v_mul_f32_e32 v33, v33, v89
	v_mul_f32_e32 v28, v28, v92
	v_mul_f32_e32 v29, v29, v93
	v_mul_f32_e32 v24, v24, v96
	v_mul_f32_e32 v25, v25, v97
	v_mul_f32_e32 v20, v20, v100
	v_mul_f32_e32 v21, v21, v101
	v_mul_f32_e32 v18, v18, v98
	v_mul_f32_e32 v19, v19, v99
	v_mul_f32_e32 v14, v14, v86
	v_mul_f32_e32 v15, v15, v87
	v_mul_f32_e32 v10, v10, v90
	v_mul_f32_e32 v11, v11, v91
	v_mul_f32_e32 v6, v6, v94
	v_mul_f32_e32 v7, v7, v95
	v_mul_f32_e32 v16, v16, v88
	v_mul_f32_e32 v17, v17, v89
	v_mul_f32_e32 v12, v12, v92
	v_mul_f32_e32 v13, v13, v93
	v_mul_f32_e32 v8, v8, v96
	v_mul_f32_e32 v9, v9, v97
	v_mul_f32_e32 v4, v4, v100
	v_mul_f32_e32 v5, v5, v101
	v_mul_f32_e32 v2, v2, v98
	v_mul_f32_e32 v3, v3, v99

.LBB0_1154:
	s_waitcnt lgkmcnt(0)
	v_add_u32_e32 v1, s3, v245
	ds_read_b128 v[114:117], v1 offset:96
	ds_read_b128 v[118:121], v1 offset:64
	ds_read_b128 v[122:125], v1 offset:32
	ds_read_b128 v[126:129], v1
	s_waitcnt lgkmcnt(3)
	v_mul_f32_e32 v62, v62, v114
	v_mul_f32_e32 v63, v63, v115
	s_waitcnt lgkmcnt(2)
	v_mul_f32_e32 v58, v58, v118
	v_mul_f32_e32 v59, v59, v119
	s_waitcnt lgkmcnt(1)
	v_mul_f32_e32 v54, v54, v122
	v_mul_f32_e32 v55, v55, v123
	v_mul_f32_e32 v64, v64, v116
	v_mul_f32_e32 v65, v65, v117
	v_mul_f32_e32 v60, v60, v120
	v_mul_f32_e32 v61, v61, v121
	v_mul_f32_e32 v56, v56, v124
	v_mul_f32_e32 v57, v57, v125
	s_waitcnt lgkmcnt(0)
	v_mul_f32_e32 v52, v52, v128
	v_mul_f32_e32 v53, v53, v129
	v_mul_f32_e32 v50, v50, v126
	v_mul_f32_e32 v51, v51, v127
	v_mul_f32_e32 v46, v46, v114
	v_mul_f32_e32 v47, v47, v115
	v_mul_f32_e32 v42, v42, v118
	v_mul_f32_e32 v43, v43, v119
	v_mul_f32_e32 v38, v38, v122
	v_mul_f32_e32 v39, v39, v123
	v_mul_f32_e32 v48, v48, v116
	v_mul_f32_e32 v49, v49, v117
	v_mul_f32_e32 v44, v44, v120
	v_mul_f32_e32 v45, v45, v121
	v_mul_f32_e32 v40, v40, v124
	v_mul_f32_e32 v41, v41, v125
	v_mul_f32_e32 v36, v36, v128
	v_mul_f32_e32 v37, v37, v129
	v_mul_f32_e32 v34, v34, v126
	v_mul_f32_e32 v35, v35, v127
	v_mul_f32_e32 v30, v30, v114
	v_mul_f32_e32 v31, v31, v115
	v_mul_f32_e32 v26, v26, v118
	v_mul_f32_e32 v27, v27, v119
	v_mul_f32_e32 v22, v22, v122
	v_mul_f32_e32 v23, v23, v123
	v_mul_f32_e32 v32, v32, v116
	v_mul_f32_e32 v33, v33, v117
	v_mul_f32_e32 v28, v28, v120
	v_mul_f32_e32 v29, v29, v121
	v_mul_f32_e32 v24, v24, v124
	v_mul_f32_e32 v25, v25, v125
	v_mul_f32_e32 v20, v20, v128
	v_mul_f32_e32 v21, v21, v129
	v_mul_f32_e32 v18, v18, v126
	v_mul_f32_e32 v19, v19, v127
	v_mul_f32_e32 v14, v14, v114
	v_mul_f32_e32 v15, v15, v115
	v_mul_f32_e32 v10, v10, v118
	v_mul_f32_e32 v11, v11, v119
	v_mul_f32_e32 v6, v6, v122
	v_mul_f32_e32 v7, v7, v123
	v_mul_f32_e32 v16, v16, v116
	v_mul_f32_e32 v17, v17, v117
	v_mul_f32_e32 v12, v12, v120
	v_mul_f32_e32 v13, v13, v121
	v_mul_f32_e32 v8, v8, v124
	v_mul_f32_e32 v9, v9, v125
	v_mul_f32_e32 v4, v4, v128
	v_mul_f32_e32 v5, v5, v129
	v_mul_f32_e32 v2, v2, v126
	v_mul_f32_e32 v3, v3, v127

.LBB0_1171:
	s_waitcnt lgkmcnt(14)
	v_mfma_f32_32x32x16_bf16 v[34:49], v[154:157], v[98:101], v[34:49]
	v_exp_f32_e32 v114, v114
	v_exp_f32_e32 v115, v115
	v_exp_f32_e32 v116, v116
	ds_read_b64_tr_b16 v[82:83], v210 offset:37888
	ds_read_b64_tr_b16 v[84:85], v210 offset:38400
	s_waitcnt lgkmcnt(14)
	v_mfma_f32_32x32x16_bf16 v[50:65], v[150:153], v[102:105], v[50:65]
	v_exp_f32_e32 v117, v117
	v_exp_f32_e32 v118, v118
	v_exp_f32_e32 v119, v119
	ds_read_b64_tr_b16 v[86:87], v210 offset:34816
	ds_read_b64_tr_b16 v[88:89], v210 offset:35328
	s_waitcnt lgkmcnt(14)
	v_mfma_f32_32x32x16_bf16 v[34:49], v[150:153], v[106:109], v[34:49]
	v_exp_f32_e32 v120, v120
	v_exp_f32_e32 v121, v121
	v_exp_f32_e32 v122, v122
	ds_read_b64_tr_b16 v[90:91], v210 offset:38912
	ds_read_b64_tr_b16 v[92:93], v210 offset:39424
	s_waitcnt lgkmcnt(14)
	v_mfma_f32_32x32x16_bf16 v[50:65], v[146:149], v[110:113], v[50:65]
	v_exp_f32_e32 v123, v123
	v_exp_f32_e32 v124, v124
	v_exp_f32_e32 v125, v125
	ds_read_b64_tr_b16 v[94:95], v210 offset:35840
	ds_read_b64_tr_b16 v[96:97], v210 offset:36352
	s_waitcnt lgkmcnt(14)
	v_mfma_f32_32x32x16_bf16 v[34:49], v[146:149], v[130:133], v[34:49]
	v_exp_f32_e32 v126, v126
	v_exp_f32_e32 v127, v127
	v_exp_f32_e32 v128, v128
	ds_read_b64_tr_b16 v[98:99], v210 offset:39936
	ds_read_b64_tr_b16 v[100:101], v210 offset:40448
	s_waitcnt lgkmcnt(14)
	v_mfma_f32_32x32x16_bf16 v[18:33], v[158:161], v[142:145], v[18:33]
	v_exp_f32_e32 v129, v129
	v_exp_f32_e32 v66, v66
	v_exp_f32_e32 v67, v67
	s_waitcnt lgkmcnt(12)
	v_mfma_f32_32x32x16_bf16 v[2:17], v[158:161], v[138:141], v[2:17]
	v_exp_f32_e32 v68, v68
	v_exp_f32_e32 v69, v69
	s_waitcnt lgkmcnt(10)
	v_mfma_f32_32x32x16_bf16 v[18:33], v[154:157], v[134:137], v[18:33]
	v_exp_f32_e32 v70, v70
	v_exp_f32_e32 v71, v71
	s_waitcnt lgkmcnt(8)
	v_mfma_f32_32x32x16_bf16 v[2:17], v[154:157], v[82:85], v[2:17]
	v_exp_f32_e32 v72, v72
	v_exp_f32_e32 v73, v73
	s_waitcnt lgkmcnt(6)
	v_mfma_f32_32x32x16_bf16 v[18:33], v[150:153], v[86:89], v[18:33]
	v_exp_f32_e32 v74, v74
	v_exp_f32_e32 v75, v75
	s_waitcnt lgkmcnt(4)
	v_mfma_f32_32x32x16_bf16 v[2:17], v[150:153], v[90:93], v[2:17]
	v_exp_f32_e32 v76, v76
	v_exp_f32_e32 v77, v77
	s_waitcnt lgkmcnt(2)
	v_mfma_f32_32x32x16_bf16 v[18:33], v[146:149], v[94:97], v[18:33]
	v_exp_f32_e32 v78, v78
	v_exp_f32_e32 v79, v79
	s_waitcnt lgkmcnt(0)
	v_mfma_f32_32x32x16_bf16 v[2:17], v[146:149], v[98:101], v[2:17]
	v_exp_f32_e32 v80, v80
	v_exp_f32_e32 v81, v81
	s_andn2_b64 vcc, exec, s[80:81]
	v_add_u32_e32 v82, s3, v245
	s_cbranch_vccnz .LBB0_1173
	s_waitcnt lgkmcnt(0)
	ds_read_b128 v[84:87], v82 offset:96
	ds_read_b128 v[88:91], v82 offset:64
	ds_read_b128 v[92:95], v82 offset:32
	ds_read_b128 v[96:99], v82
	s_waitcnt lgkmcnt(3)
	v_mul_f32_e32 v62, v62, v84
	v_mul_f32_e32 v63, v63, v85
	s_waitcnt lgkmcnt(2)
	v_mul_f32_e32 v58, v58, v88
	v_mul_f32_e32 v59, v59, v89
	s_waitcnt lgkmcnt(1)
	v_mul_f32_e32 v54, v54, v92
	v_mul_f32_e32 v55, v55, v93
	v_mul_f32_e32 v64, v64, v86
	v_mul_f32_e32 v65, v65, v87
	v_mul_f32_e32 v60, v60, v90
	v_mul_f32_e32 v61, v61, v91
	v_mul_f32_e32 v56, v56, v94
	v_mul_f32_e32 v57, v57, v95
	s_waitcnt lgkmcnt(0)
	v_mul_f32_e32 v52, v52, v98
	v_mul_f32_e32 v53, v53, v99
	v_mul_f32_e32 v50, v50, v96
	v_mul_f32_e32 v51, v51, v97
	v_mul_f32_e32 v46, v46, v84
	v_mul_f32_e32 v47, v47, v85
	v_mul_f32_e32 v42, v42, v88
	v_mul_f32_e32 v43, v43, v89
	v_mul_f32_e32 v38, v38, v92
	v_mul_f32_e32 v39, v39, v93
	v_mul_f32_e32 v48, v48, v86
	v_mul_f32_e32 v49, v49, v87
	v_mul_f32_e32 v44, v44, v90
	v_mul_f32_e32 v45, v45, v91
	v_mul_f32_e32 v40, v40, v94
	v_mul_f32_e32 v41, v41, v95
	v_mul_f32_e32 v36, v36, v98
	v_mul_f32_e32 v37, v37, v99
	v_mul_f32_e32 v34, v34, v96
	v_mul_f32_e32 v35, v35, v97
	v_mul_f32_e32 v30, v30, v84
	v_mul_f32_e32 v31, v31, v85
	v_mul_f32_e32 v26, v26, v88
	v_mul_f32_e32 v27, v27, v89
	v_mul_f32_e32 v22, v22, v92
	v_mul_f32_e32 v23, v23, v93
	v_mul_f32_e32 v32, v32, v86
	v_mul_f32_e32 v33, v33, v87
	v_mul_f32_e32 v28, v28, v90
	v_mul_f32_e32 v29, v29, v91
	v_mul_f32_e32 v24, v24, v94
	v_mul_f32_e32 v25, v25, v95
	v_mul_f32_e32 v20, v20, v98
	v_mul_f32_e32 v21, v21, v99
	v_mul_f32_e32 v18, v18, v96
	v_mul_f32_e32 v19, v19, v97
	v_mul_f32_e32 v14, v14, v84
	v_mul_f32_e32 v15, v15, v85
	v_mul_f32_e32 v10, v10, v88
	v_mul_f32_e32 v11, v11, v89
	v_mul_f32_e32 v6, v6, v92
	v_mul_f32_e32 v7, v7, v93
	v_mul_f32_e32 v16, v16, v86
	v_mul_f32_e32 v17, v17, v87
	v_mul_f32_e32 v12, v12, v90
	v_mul_f32_e32 v13, v13, v91
	v_mul_f32_e32 v8, v8, v94
	v_mul_f32_e32 v9, v9, v95
	v_mul_f32_e32 v4, v4, v98
	v_mul_f32_e32 v5, v5, v99
	v_mul_f32_e32 v2, v2, v96
	v_mul_f32_e32 v3, v3, v97
; __device__ __forceinline__ int crow(int r,int hi){return (r&3)+8*(r>>2)+4*hi;}
; #define SBAR() __builtin_amdgcn_sched_barrier(0)
;   #define PKW(P,B) cvtpk_s(P[B],P[B+1])
; template<int MODE,int THRL> __device__ __forceinline__ void attn_unit(const bf16*Qw0,int PQ,const bf16*__restrict__ Kh,int PK,const bf16*__restrict__ Vh,int PV,bf16*Ow0,int PO,int NT,int nabase,int nar0,const float*rpbh,char*shm,int&rot,bool pre,bool hasn,long dKn,long dVn){
;     ...
;   { float sacc=pB0[0]+pB0[1]; _Pragma("unroll") for(int r=2;r<16;++r)sacc+=pB0[r]; _Pragma("unroll") for(int r=0;r<16;++r)sacc+=pB1[r]; l_reg+=sacc;
;     pw0=(u32x4){PKW(pB0,0),PKW(pB0,2),PKW(pB0,4),PKW(pB0,6)};pw1=(u32x4){PKW(pB0,8),PKW(pB0,10),PKW(pB0,12),PKW(pB0,14)};pw2=(u32x4){PKW(pB1,0),PKW(pB1,2),PKW(pB1,4),PKW(pB1,6)};pw3=(u32x4){PKW(pB1,8),PKW(pB1,10),PKW(pB1,12),PKW(pB1,14)};
;     SBAR(); pv(o,vb0+2*sl_cur,PAF(0),PAF(1),PAF(2),PAF(3)); if(MODE==2){ SBAR(); pv(o+2,vb0+2*sl_cur+SLOTB,PAF(0),PAF(1),PAF(2),PAF(3)); } }
;     ...
;   {auto rr=__builtin_amdgcn_permlane32_swap(__float_as_uint(l_reg),__float_as_uint(l_reg),false,false);l_reg=__uint_as_float(rr[0])+__uint_as_float(rr[1]);}
;   if(hi==0)wsf[32+r32]=l_reg;asm volatile("s_waitcnt lgkmcnt(0)":::"memory");
;   float rli[16];
;   #pragma unroll
;   for(int r=0;r<16;++r)rli[r]=__builtin_amdgcn_rcpf(wsf[32+crow(r,hi)]);
.LBB0_1173:
	v_add_f32_e32 v84, v114, v115
	v_add_f32_e32 v84, v116, v84
	v_add_f32_e32 v84, v117, v84
	v_add_f32_e32 v84, v118, v84
	v_add_f32_e32 v84, v119, v84
	v_add_f32_e32 v84, v120, v84
	v_add_f32_e32 v84, v121, v84
	v_add_f32_e32 v84, v122, v84
	v_add_f32_e32 v84, v123, v84
	v_add_f32_e32 v84, v124, v84
	v_add_f32_e32 v84, v125, v84
	v_add_f32_e32 v84, v126, v84
	v_add_f32_e32 v84, v127, v84
	v_add_f32_e32 v84, v128, v84
	v_add_f32_e32 v84, v129, v84
	v_add_f32_e32 v84, v84, v66
	v_add_f32_e32 v84, v67, v84
	v_add_f32_e32 v84, v68, v84
	v_add_f32_e32 v84, v69, v84
	v_add_f32_e32 v84, v70, v84
	v_add_f32_e32 v84, v71, v84
	v_add_f32_e32 v84, v72, v84
	v_add_f32_e32 v84, v73, v84
	v_add_f32_e32 v84, v74, v84
	v_add_f32_e32 v84, v75, v84
	v_add_f32_e32 v84, v76, v84
	v_add_f32_e32 v84, v77, v84
	v_add_f32_e32 v84, v78, v84
	v_add_f32_e32 v84, v79, v84
	v_add_f32_e32 v84, v80, v84
	v_add_f32_e32 v84, v81, v84
	v_add_f32_e32 v1, v1, v84
	v_cvt_pk_bf16_f32 v66, v66, v67
	v_add_u32_e32 v83, v244, v241
	v_cvt_pk_bf16_f32 v84, v114, v115
	v_cvt_pk_bf16_f32 v85, v116, v117
	v_cvt_pk_bf16_f32 v86, v118, v119
	v_cvt_pk_bf16_f32 v87, v120, v121
	v_cvt_pk_bf16_f32 v88, v122, v123
	v_cvt_pk_bf16_f32 v89, v124, v125
	v_cvt_pk_bf16_f32 v90, v126, v127
	v_cvt_pk_bf16_f32 v91, v128, v129
	v_cvt_pk_bf16_f32 v67, v68, v69
	v_cvt_pk_bf16_f32 v68, v70, v71
	v_cvt_pk_bf16_f32 v69, v72, v73
	v_cvt_pk_bf16_f32 v70, v74, v75
	v_cvt_pk_bf16_f32 v71, v76, v77
	v_cvt_pk_bf16_f32 v72, v78, v79
	v_cvt_pk_bf16_f32 v73, v80, v81
	v_add3_u32 v83, v242, v83, s84
	v_add_u32_e32 v104, 0x6000, v83
	ds_read_b64_tr_b16 v[74:75],v104 offset:0
	ds_read_b64_tr_b16 v[76:77],v104 offset:512
	ds_read_b64_tr_b16 v[78:79],v104 offset:1024
	ds_read_b64_tr_b16 v[80:81],v104 offset:1536
	ds_read_b64_tr_b16 v[92:93],v104 offset:2048
	ds_read_b64_tr_b16 v[94:95],v104 offset:2560
	ds_read_b64_tr_b16 v[96:97],v104 offset:3072
	ds_read_b64_tr_b16 v[98:99],v104 offset:3584
	s_waitcnt lgkmcnt(0)
	s_nop 0
	v_mfma_f32_32x32x16_bf16 v[50:65], v[84:87], v[74:77], v[50:65]
	ds_read_b64_tr_b16 v[74:75],v104 offset:4096
	ds_read_b64_tr_b16 v[76:77],v104 offset:4608
	v_mfma_f32_32x32x16_bf16 v[50:65], v[88:91], v[78:81], v[50:65]
	ds_read_b64_tr_b16 v[78:79],v104 offset:5120
	ds_read_b64_tr_b16 v[80:81],v104 offset:5632
	v_mfma_f32_32x32x16_bf16 v[50:65], v[66:69], v[92:95], v[50:65]
	ds_read_b64_tr_b16 v[92:93],v104 offset:6144
	ds_read_b64_tr_b16 v[94:95],v104 offset:6656
	ds_read_b64_tr_b16 v[100:101],v104 offset:7168
	ds_read_b64_tr_b16 v[102:103],v104 offset:7680
	s_waitcnt lgkmcnt(0)
	v_mfma_f32_32x32x16_bf16 v[50:65], v[70:73], v[96:99], v[50:65]
	v_mfma_f32_32x32x16_bf16 v[34:49], v[84:87], v[74:77], v[34:49]
	v_mfma_f32_32x32x16_bf16 v[34:49], v[88:91], v[78:81], v[34:49]
	v_mfma_f32_32x32x16_bf16 v[34:49], v[66:69], v[92:95], v[34:49]
	v_mfma_f32_32x32x16_bf16 v[34:49], v[70:73], v[100:103], v[34:49]
	v_add_u32_e32 v83, 0x8000, v83
	ds_read_b64_tr_b16 v[74:75],v83 offset:0
	ds_read_b64_tr_b16 v[76:77],v83 offset:512
	ds_read_b64_tr_b16 v[78:79],v83 offset:1024
	ds_read_b64_tr_b16 v[80:81],v83 offset:1536
	ds_read_b64_tr_b16 v[92:93],v83 offset:2048
	ds_read_b64_tr_b16 v[94:95],v83 offset:2560
	ds_read_b64_tr_b16 v[96:97],v83 offset:3072
	ds_read_b64_tr_b16 v[98:99],v83 offset:3584
	s_waitcnt lgkmcnt(0)
	s_nop 0
	v_mfma_f32_32x32x16_bf16 v[18:33], v[84:87], v[74:77], v[18:33]
	ds_read_b64_tr_b16 v[74:75],v83 offset:4096
	ds_read_b64_tr_b16 v[76:77],v83 offset:4608
	v_mfma_f32_32x32x16_bf16 v[18:33], v[88:91], v[78:81], v[18:33]
	ds_read_b64_tr_b16 v[78:79],v83 offset:5120
	ds_read_b64_tr_b16 v[80:81],v83 offset:5632
	v_mfma_f32_32x32x16_bf16 v[18:33], v[66:69], v[92:95], v[18:33]
	ds_read_b64_tr_b16 v[92:93],v83 offset:6144
	ds_read_b64_tr_b16 v[94:95],v83 offset:6656
	ds_read_b64_tr_b16 v[100:101],v83 offset:7168
	ds_read_b64_tr_b16 v[102:103],v83 offset:7680
	s_waitcnt lgkmcnt(0)
	v_mfma_f32_32x32x16_bf16 v[18:33], v[70:73], v[96:99], v[18:33]
	v_mfma_f32_32x32x16_bf16 v[2:17], v[84:87], v[74:77], v[2:17]
	v_mfma_f32_32x32x16_bf16 v[2:17], v[88:91], v[78:81], v[2:17]
	v_mfma_f32_32x32x16_bf16 v[2:17], v[66:69], v[92:95], v[2:17]
	v_mov_b32_e32 v66, v1
	s_nop 1
	v_permlane32_swap_b32_e32 v1, v66
	v_mfma_f32_32x32x16_bf16 v[2:17], v[70:73], v[100:103], v[2:17]
	s_and_saveexec_b64 s[80:81], s[6:7]
	v_add_f32_e32 v1, v1, v66
	ds_write_b32 v243, v1 offset:128
	s_or_b64 exec, exec, s[80:81]
	s_lshl_b64 s[6:7], s[76:77], 13
	s_waitcnt lgkmcnt(0)
	s_or_b64 s[76:77], s[6:7], s[78:79]
	ds_read_b128 v[66:69], v82 offset:128
	ds_read_b128 v[70:73], v82 offset:160
	s_lshl_b64 s[6:7], s[76:77], 12
	s_add_u32 s1, s28, s6
	s_addc_u32 s3, s29, s7
	s_lshl_b32 s4, s73, 11
	s_add_u32 s1, s1, s4
	s_addc_u32 s3, s3, 0
	s_waitcnt lgkmcnt(1)
	v_rcp_f32_e32 v1, v66
	v_rcp_f32_e32 v74, v67
	v_rcp_f32_e32 v75, v68
	v_rcp_f32_e32 v76, v69
	ds_read_b128 v[66:69], v82 offset:192
	s_add_u32 s1, s1, s72
	s_addc_u32 s3, s3, 0
	s_lshl_b64 s[6:7], s[74:75], 17
	s_add_u32 s6, s1, s6
	s_addc_u32 s7, s3, s7
	s_lshl_b32 s1, s74, 12
	s_waitcnt lgkmcnt(1)
	v_rcp_f32_e32 v77, v70
	v_rcp_f32_e32 v78, v71
	v_rcp_f32_e32 v79, v72
	v_rcp_f32_e32 v80, v73
	ds_read_b128 v[70:73], v82 offset:224
	s_waitcnt lgkmcnt(1)
; __device__ __forceinline__ int crow(int r,int hi){return (r&3)+8*(r>>2)+4*hi;}
; template<int MODE,int THRL> __device__ __forceinline__ void attn_unit(const bf16*Qw0,int PQ,const bf16*__restrict__ Kh,int PK,const bf16*__restrict__ Vh,int PV,bf16*Ow0,int PO,int NT,int nabase,int nar0,const float*rpbh,char*shm,int&rot,bool pre,bool hasn,long dKn,long dVn){
;     ...
;   bf16*Ow=Ow0+(long)wid*QBLK*PO;
;   { bf16*stg=(bf16*)(shm+LDS_OST)+wid*2048;
;     #pragma unroll
;     for(int hf=0;hf<ND/2;++hf){
;     #pragma unroll
;     for(int r=0;r<16;++r){const int orow=crow(r,hi);
;       #pragma unroll
;       for(int d0=0;d0<2;++d0)stg[orow*64+d0*32+r32]=__float2bfloat16(o[2*hf+d0][r]*rli[r]);}
;     asm volatile("s_waitcnt lgkmcnt(0)":::"memory");
;     #pragma unroll
;     for(int i=0;i<4;++i){const int row=i*8+(lane>>3),ch=lane&7; const u32x4 v=*(const u32x4*)(stg+row*64+ch*8); ATTN_STORE16(Ow+(long)row*PO+hf*64+ch*8,v);}
;     asm volatile("s_waitcnt lgkmcnt(0)":::"memory"); } }
	v_rcp_f32_e32 v81, v66
	v_rcp_f32_e32 v82, v67
	s_add_i32 s1, s1, 0x12800
	v_lshlrev_b32_e32 v66, 9, v240
	v_lshlrev_b32_e32 v67, 1, v239
	v_mul_f32_e32 v34, v34, v1
	v_or3_b32 v83, s1, v66, v67
	v_cvt_pk_bf16_f32 v34, v34, s0
	ds_write_b16 v83, v34 offset:64
	v_mul_f32_e32 v34, v51, v74
	v_cvt_pk_bf16_f32 v34, v34, s0
	ds_write_b16 v83, v34 offset:128
	v_mul_f32_e32 v34, v35, v74
	v_cvt_pk_bf16_f32 v34, v34, s0
	ds_write_b16 v83, v34 offset:192
	v_mul_f32_e32 v34, v52, v75
	v_cvt_pk_bf16_f32 v34, v34, s0
	ds_write_b16 v83, v34 offset:256
	v_mul_f32_e32 v34, v36, v75
	v_cvt_pk_bf16_f32 v34, v34, s0
	ds_write_b16 v83, v34 offset:320
	v_mul_f32_e32 v34, v53, v76
	v_cvt_pk_bf16_f32 v34, v34, s0
	ds_write_b16 v83, v34 offset:384
	v_mul_f32_e32 v34, v37, v76
	v_cvt_pk_bf16_f32 v34, v34, s0
	ds_write_b16 v83, v34 offset:448
	v_mul_f32_e32 v34, v54, v77
	v_cvt_pk_bf16_f32 v34, v34, s0
	ds_write_b16 v83, v34 offset:1024
	v_mul_f32_e32 v34, v38, v77
	v_cvt_pk_bf16_f32 v34, v34, s0
	ds_write_b16 v83, v34 offset:1088
	v_mul_f32_e32 v34, v55, v78
	v_cvt_pk_bf16_f32 v34, v34, s0
	ds_write_b16 v83, v34 offset:1152
	v_mul_f32_e32 v34, v39, v78
	v_cvt_pk_bf16_f32 v34, v34, s0
	ds_write_b16 v83, v34 offset:1216
	v_mul_f32_e32 v34, v56, v79
	v_cvt_pk_bf16_f32 v34, v34, s0
	ds_write_b16 v83, v34 offset:1280
	v_mul_f32_e32 v34, v40, v79
	v_cvt_pk_bf16_f32 v34, v34, s0
	ds_write_b16 v83, v34 offset:1344
	v_mul_f32_e32 v34, v57, v80
	v_cvt_pk_bf16_f32 v34, v34, s0
	ds_write_b16 v83, v34 offset:1408
	v_mul_f32_e32 v34, v41, v80
	v_cvt_pk_bf16_f32 v34, v34, s0
	ds_write_b16 v83, v34 offset:1472
	v_mul_f32_e32 v34, v58, v81
	v_cvt_pk_bf16_f32 v34, v34, s0
	ds_write_b16 v83, v34 offset:2048
	v_mul_f32_e32 v34, v42, v81
	v_cvt_pk_bf16_f32 v34, v34, s0
	v_rcp_f32_e32 v68, v68
	ds_write_b16 v83, v34 offset:2112
	v_mul_f32_e32 v34, v59, v82
	v_cvt_pk_bf16_f32 v34, v34, s0
	ds_write_b16 v83, v34 offset:2176
	v_mul_f32_e32 v34, v43, v82
	v_cvt_pk_bf16_f32 v34, v34, s0
	v_rcp_f32_e32 v69, v69
	ds_write_b16 v83, v34 offset:2240
	v_mul_f32_e32 v34, v60, v68
	v_cvt_pk_bf16_f32 v34, v34, s0
	ds_write_b16 v83, v34 offset:2304
	v_mul_f32_e32 v34, v44, v68
	v_cvt_pk_bf16_f32 v34, v34, s0
	s_waitcnt lgkmcnt(14)
	v_rcp_f32_e32 v70, v70
	ds_write_b16 v83, v34 offset:2368
	v_mul_f32_e32 v34, v61, v69
	v_cvt_pk_bf16_f32 v34, v34, s0
	ds_write_b16 v83, v34 offset:2432
	v_mul_f32_e32 v34, v45, v69
	v_cvt_pk_bf16_f32 v34, v34, s0
	v_rcp_f32_e32 v71, v71
	ds_write_b16 v83, v34 offset:2496
	v_mul_f32_e32 v34, v62, v70
	v_cvt_pk_bf16_f32 v34, v34, s0
	ds_write_b16 v83, v34 offset:3072
	v_mul_f32_e32 v34, v46, v70
	v_cvt_pk_bf16_f32 v34, v34, s0
	v_rcp_f32_e32 v72, v72
	ds_write_b16 v83, v34 offset:3136
	v_mul_f32_e32 v34, v63, v71
	v_cvt_pk_bf16_f32 v34, v34, s0
	ds_write_b16 v83, v34 offset:3200
	v_mul_f32_e32 v34, v47, v71
	v_cvt_pk_bf16_f32 v34, v34, s0
	v_rcp_f32_e32 v73, v73
	ds_write_b16 v83, v34 offset:3264
	v_mul_f32_e32 v34, v64, v72
	v_cvt_pk_bf16_f32 v34, v34, s0
	ds_write_b16 v83, v34 offset:3328
	v_mul_f32_e32 v34, v48, v72
	v_cvt_pk_bf16_f32 v34, v34, s0
	ds_write_b16 v83, v34 offset:3392
	v_mul_f32_e32 v34, v65, v73
	v_cvt_pk_bf16_f32 v34, v34, s0
	v_lshlrev_b32_e32 v66, 1, v238
	v_mul_f32_e32 v50, v50, v1
	ds_write_b16 v83, v34 offset:3456
	v_mul_f32_e32 v34, v49, v73
	v_and_b32_e32 v66, 0x70, v66
	v_cvt_pk_bf16_f32 v50, v50, s0
	v_cvt_pk_bf16_f32 v34, v34, s0
	v_lshrrev_b32_e32 v84, 3, v237
	v_or_b32_e32 v85, s1, v66
	ds_write_b16 v83, v50
	ds_write_b16 v83, v34 offset:3520
	v_lshl_or_b32 v86, v84, 7, v85
	s_waitcnt lgkmcnt(0)
	v_mov_b32_e32 v67, v0
	ds_read_b128 v[34:37], v86
	v_or_b32_e32 v44, 8, v84
	v_lshl_add_u64 v[66:67], s[6:7], 0, v[66:67]
	v_lshlrev_b32_e32 v38, 12, v84
	v_mov_b32_e32 v39, v0
	v_lshl_or_b32 v48, v44, 7, v85
	v_lshl_add_u64 v[42:43], v[66:67], 0, v[38:39]
	ds_read_b128 v[38:41], v48
	s_waitcnt lgkmcnt(1)
	global_store_dwordx4 v[42:43], v[34:37], off
	v_or_b32_e32 v50, 24, v84
	v_lshl_add_u32 v51, v50, 7, v85
	v_lshlrev_b32_e32 v34, 12, v44
	v_mov_b32_e32 v35, v0
	v_lshl_add_u64 v[44:45], v[66:67], 0, v[34:35]
	s_waitcnt lgkmcnt(0)
	global_store_dwordx4 v[44:45], v[38:41], off
	v_mul_f32_e32 v18, v18, v1
	v_mul_f32_e32 v1, v2, v1
	v_or_b32_e32 v38, 16, v84
	v_lshl_add_u32 v49, v38, 7, v85
	ds_read_b128 v[34:37], v49
	v_lshlrev_b32_e32 v38, 12, v38
	v_mov_b32_e32 v39, v0
	v_lshl_add_u64 v[46:47], v[66:67], 0, v[38:39]
	ds_read_b128 v[38:41], v51
	s_waitcnt lgkmcnt(1)
	global_store_dwordx4 v[46:47], v[34:37], off
	v_cvt_pk_bf16_f32 v1, v1, s0
	v_cvt_pk_bf16_f32 v18, v18, s0
	v_lshlrev_b32_e32 v34, 12, v50
	v_mov_b32_e32 v35, v0
	v_lshl_add_u64 v[34:35], v[66:67], 0, v[34:35]
	s_waitcnt lgkmcnt(0)
	global_store_dwordx4 v[34:35], v[38:41], off
	s_waitcnt lgkmcnt(0)
; #define FRESH_LANE() ({ int t_ = threadIdx.x; asm volatile("" : "+v"(t_)); t_ & 63; })
; template<int MODE,int THRL> __device__ __forceinline__ void attn_unit(const bf16*Qw0,int PQ,const bf16*__restrict__ Kh,int PK,const bf16*__restrict__ Vh,int PV,bf16*Ow0,int PO,int NT,int nabase,int nar0,const float*rpbh,char*shm,int&rot,bool pre,bool hasn,long dKn,long dVn){
;     ...
;       for(int d0=0;d0<2;++d0)stg[orow*64+d0*32+r32]=__float2bfloat16(o[2*hf+d0][r]*rli[r]);}
;     asm volatile("s_waitcnt lgkmcnt(0)":::"memory");
;     #pragma unroll
;     for(int i=0;i<4;++i){const int row=i*8+(lane>>3),ch=lane&7; const u32x4 v=*(const u32x4*)(stg+row*64+ch*8); ATTN_STORE16(Ow+(long)row*PO+hf*64+ch*8,v);}
;     asm volatile("s_waitcnt lgkmcnt(0)":::"memory"); } }
;   rot=sl_next;
;   asm volatile("s_waitcnt lgkmcnt(0)\n\ts_barrier":::"memory");
; template <int l> __device__ __forceinline__ void layer_body(const Args& a, unsigned char* lds, const XcdBarrier& bar, int G, int bx, int vcu, int gw, int NGW, int lane_, int tid_k, int wave) {
;     ...
;                         if (G == 256 && map == 1) {
;                             asm volatile("s_waitcnt vmcnt(0)" ::: "memory"); __builtin_amdgcn_fence(__ATOMIC_SEQ_CST, "workgroup");
;                             const int lane = FRESH_LANE(), rsub = lane >> 3, ch = lane & 7;
;                             const f32x4* gp = (const f32x4*)(a.subln + ch * 16); const f32x4 g0 = gp[0], g1 = gp[1], g2 = gp[2], g3 = gp[3];
;                             const float gn[16] = {g0.x, g0.y, g0.z, g0.w, g1.x, g1.y, g1.z, g1.w, g2.x, g2.y, g2.z, g2.w, g3.x, g3.y, g3.z, g3.w};
; #pragma unroll
;                             for (int it = 0; it < 4; ++it) { const int r = wave * 32 + it * 8 + rsub; const size_t lr = (size_t)b * SEQ + (size_t)qb * 256 + r;
;                                 const v4u* p1 = (const v4u*)(OP + lr * 2048 + h * 128) + ch * 2; const v4u* p2 = (const v4u*)(OP + lr * 2048 + 1024 + h * 128) + ch * 2;
;                                 const v4u a0 = p1[0], a1 = p1[1], b0 = p2[0], b1 = p2[1];
	ds_write_b16 v83, v1 offset:64
	v_mul_f32_e32 v1, v19, v74
	v_cvt_pk_bf16_f32 v1, v1, s0
	ds_write_b16 v83, v1 offset:128
	v_mul_f32_e32 v1, v3, v74
	v_cvt_pk_bf16_f32 v1, v1, s0
	ds_write_b16 v83, v1 offset:192
	v_mul_f32_e32 v1, v20, v75
	v_cvt_pk_bf16_f32 v1, v1, s0
	ds_write_b16 v83, v1 offset:256
	v_mul_f32_e32 v1, v4, v75
	v_cvt_pk_bf16_f32 v1, v1, s0
	ds_write_b16 v83, v1 offset:320
	v_mul_f32_e32 v1, v21, v76
	v_cvt_pk_bf16_f32 v1, v1, s0
	ds_write_b16 v83, v1 offset:384
	v_mul_f32_e32 v1, v5, v76
	v_cvt_pk_bf16_f32 v1, v1, s0
	ds_write_b16 v83, v1 offset:448
	v_mul_f32_e32 v1, v22, v77
	v_cvt_pk_bf16_f32 v1, v1, s0
	ds_write_b16 v83, v1 offset:1024
	v_mul_f32_e32 v1, v6, v77
	v_cvt_pk_bf16_f32 v1, v1, s0
	ds_write_b16 v83, v1 offset:1088
	v_mul_f32_e32 v1, v23, v78
	v_cvt_pk_bf16_f32 v1, v1, s0
	ds_write_b16 v83, v1 offset:1152
	v_mul_f32_e32 v1, v7, v78
	v_cvt_pk_bf16_f32 v1, v1, s0
	ds_write_b16 v83, v1 offset:1216
	v_mul_f32_e32 v1, v24, v79
	v_cvt_pk_bf16_f32 v1, v1, s0
	ds_write_b16 v83, v1 offset:1280
	v_mul_f32_e32 v1, v8, v79
	v_cvt_pk_bf16_f32 v1, v1, s0
	ds_write_b16 v83, v1 offset:1344
	v_mul_f32_e32 v1, v25, v80
	v_cvt_pk_bf16_f32 v1, v1, s0
	ds_write_b16 v83, v1 offset:1408
	v_mul_f32_e32 v1, v9, v80
	v_cvt_pk_bf16_f32 v1, v1, s0
	ds_write_b16 v83, v1 offset:1472
	v_mul_f32_e32 v1, v26, v81
	v_cvt_pk_bf16_f32 v1, v1, s0
	ds_write_b16 v83, v1 offset:2048
	v_mul_f32_e32 v1, v10, v81
	v_cvt_pk_bf16_f32 v1, v1, s0
	ds_write_b16 v83, v1 offset:2112
	v_mul_f32_e32 v1, v27, v82
	v_cvt_pk_bf16_f32 v1, v1, s0
	ds_write_b16 v83, v1 offset:2176
	v_mul_f32_e32 v1, v11, v82
	v_cvt_pk_bf16_f32 v1, v1, s0
	ds_write_b16 v83, v1 offset:2240
	v_mul_f32_e32 v1, v28, v68
	v_cvt_pk_bf16_f32 v1, v1, s0
	ds_write_b16 v83, v1 offset:2304
	v_mul_f32_e32 v1, v12, v68
	v_cvt_pk_bf16_f32 v1, v1, s0
	ds_write_b16 v83, v1 offset:2368
	v_mul_f32_e32 v1, v29, v69
	v_cvt_pk_bf16_f32 v1, v1, s0
	ds_write_b16 v83, v1 offset:2432
	v_mul_f32_e32 v1, v13, v69
	v_cvt_pk_bf16_f32 v1, v1, s0
	ds_write_b16 v83, v1 offset:2496
	v_mul_f32_e32 v1, v30, v70
	v_cvt_pk_bf16_f32 v1, v1, s0
	ds_write_b16 v83, v1 offset:3072
	v_mul_f32_e32 v1, v14, v70
	v_cvt_pk_bf16_f32 v1, v1, s0
	ds_write_b16 v83, v1 offset:3136
	v_mul_f32_e32 v1, v31, v71
	v_cvt_pk_bf16_f32 v1, v1, s0
	ds_write_b16 v83, v1 offset:3200
	v_mul_f32_e32 v1, v15, v71
	v_cvt_pk_bf16_f32 v1, v1, s0
	ds_write_b16 v83, v1 offset:3264
	v_mul_f32_e32 v1, v32, v72
	v_cvt_pk_bf16_f32 v1, v1, s0
	ds_write_b16 v83, v1 offset:3328
	v_mul_f32_e32 v1, v16, v72
	v_cvt_pk_bf16_f32 v1, v1, s0
	ds_write_b16 v83, v1 offset:3392
	v_mul_f32_e32 v1, v33, v73
	v_cvt_pk_bf16_f32 v1, v1, s0
	ds_write_b16 v83, v1 offset:3456
	v_mul_f32_e32 v1, v17, v73
	v_cvt_pk_bf16_f32 v1, v1, s0
	ds_write_b16 v83, v18
	ds_write_b16 v83, v1 offset:3520
	s_waitcnt lgkmcnt(0)
	ds_read_b128 v[2:5], v86
	ds_read_b128 v[6:9], v48
	ds_read_b128 v[10:13], v49
	ds_read_b128 v[14:17], v51
	s_waitcnt lgkmcnt(3)
	global_store_dwordx4 v[42:43], v[2:5], off offset:128
	s_waitcnt lgkmcnt(2)
	global_store_dwordx4 v[44:45], v[6:9], off offset:128
	s_waitcnt lgkmcnt(1)
	global_store_dwordx4 v[46:47], v[10:13], off offset:128
	s_waitcnt lgkmcnt(0)
	global_store_dwordx4 v[34:35], v[14:17], off offset:128
	s_waitcnt lgkmcnt(0)
	s_cmp_lg_u32 s73, 0
	v_readlane_b32 s0, v254, 12
	s_cselect_b64 s[6:7], -1, 0
	v_readlane_b32 s1, v254, 13
	s_waitcnt lgkmcnt(0)
	s_barrier
	s_and_b64 s[6:7], s[0:1], s[6:7]
	s_andn2_b64 vcc, exec, s[6:7]
	s_cbranch_vccnz .LBB0_1177
	v_mov_b32_e32 v1, v222
	s_waitcnt vmcnt(0)
	v_readlane_b32 s0, v254, 14
	v_lshrrev_b32_e32 v2, 3, v1
	v_mov_b32_e32 v23, v0
	v_and_or_b32 v22, v2, 7, s0
	v_lshl_add_u64 v[2:3], s[76:77], 0, v[22:23]
	v_lshlrev_b64 v[2:3], 12, v[2:3]
	v_and_b32_e32 v1, 7, v1
	s_mov_b32 s73, s85
	v_lshl_add_u64 v[2:3], s[28:29], 0, v[2:3]
	v_lshlrev_b32_e32 v24, 5, v1
	v_mov_b32_e32 v25, v0
	v_lshl_add_u64 v[2:3], v[2:3], 0, s[72:73]
	v_lshl_add_u64 v[2:3], v[2:3], 0, v[24:25]
	global_load_dwordx4 v[18:21], v[2:3], off offset:16
	global_load_dwordx4 v[26:29], v[2:3], off offset:2064
	global_load_dwordx4 v[30:33], v[2:3], off
	global_load_dwordx4 v[34:37], v[2:3], off offset:2048
	v_lshlrev_b32_e32 v1, 6, v1
	global_load_dwordx4 v[14:17], v1, s[24:25]
	global_load_dwordx4 v[10:13], v1, s[24:25] offset:16
	global_load_dwordx4 v[6:9], v1, s[24:25] offset:32
	global_load_dwordx4 v[2:5], v1, s[24:25] offset:48
	s_mov_b32 s0, 0xf800000
	s_add_u32 s6, s46, s72
	s_addc_u32 s7, s47, 0
	s_waitcnt vmcnt(7)
	v_lshlrev_b32_e32 v39, 16, v19
	v_lshlrev_b32_e32 v38, 16, v18
	s_waitcnt vmcnt(5)
	v_lshlrev_b32_e32 v47, 16, v31
	v_lshlrev_b32_e32 v46, 16, v30
	s_waitcnt vmcnt(4)
; __device__ __forceinline__ unsigned pk2(float lo, float hi) { return f2bf(lo) | (f2bf(hi) << 16); }
; template <int l> __device__ __forceinline__ void layer_body(const Args& a, unsigned char* lds, const XcdBarrier& bar, int G, int bx, int vcu, int gw, int NGW, int lane_, int tid_k, int wave) {
;     ...
;                             for (int it = 0; it < 4; ++it) { const int r = wave * 32 + it * 8 + rsub; const size_t lr = (size_t)b * SEQ + (size_t)qb * 256 + r;
;                                 const v4u* p1 = (const v4u*)(OP + lr * 2048 + h * 128) + ch * 2; const v4u* p2 = (const v4u*)(OP + lr * 2048 + 1024 + h * 128) + ch * 2;
;                                 const v4u a0 = p1[0], a1 = p1[1], b0 = p2[0], b1 = p2[1];
;                                 const unsigned wa[8] = {a0.x, a0.y, a0.z, a0.w, a1.x, a1.y, a1.z, a1.w}, wb[8] = {b0.x, b0.y, b0.z, b0.w, b1.x, b1.y, b1.z, b1.w};
;                                 float o[16]; float ss = 0.f;
; #pragma unroll
;                                 for (int e = 0; e < 8; ++e) { o[2 * e] = bflo(wa[e]) - lam * bflo(wb[e]); o[2 * e + 1] = bfhi(wa[e]) - lam * bfhi(wb[e]); ss += o[2 * e] * o[2 * e] + o[2 * e + 1] * o[2 * e + 1]; }
;                                 ss += __shfl_xor(ss, 1); ss += __shfl_xor(ss, 2); ss += __shfl_xor(ss, 4);
;                                 const float rs = (1.0f - LAMBDA_INIT) / sqrtf(ss * (1.0f / 128.0f) + EPS);
;                                 unsigned w[8];
; #pragma unroll
;                                 for (int e = 0; e < 8; ++e) w[e] = pk2(o[2 * e] * rs * gn[2 * e], o[2 * e + 1] * rs * gn[2 * e + 1]);
;                                 v4u* op = (v4u*)(AO + (rq + r) * DMODEL + h * 128) + ch * 2; op[0] = (v4u){w[0], w[1], w[2], w[3]}; op[1] = (v4u){w[4], w[5], w[6], w[7]}; }
	v_lshlrev_b32_e32 v49, 16, v35
	v_lshlrev_b32_e32 v48, 16, v34
	v_and_b32_e32 v31, 0xffff0000, v31
	v_and_b32_e32 v30, 0xffff0000, v30
	v_and_b32_e32 v35, 0xffff0000, v35
	v_and_b32_e32 v34, 0xffff0000, v34
	v_lshlrev_b32_e32 v41, 16, v27
	v_lshlrev_b32_e32 v40, 16, v26
	v_lshlrev_b32_e32 v43, 16, v21
	v_lshlrev_b32_e32 v42, 16, v20
	v_lshlrev_b32_e32 v45, 16, v29
	v_lshlrev_b32_e32 v44, 16, v28
	v_lshlrev_b32_e32 v51, 16, v33
	v_lshlrev_b32_e32 v50, 16, v32
	v_lshlrev_b32_e32 v53, 16, v37
	v_lshlrev_b32_e32 v52, 16, v36
	v_and_b32_e32 v33, 0xffff0000, v33
	v_and_b32_e32 v32, 0xffff0000, v32
	v_and_b32_e32 v37, 0xffff0000, v37
	v_and_b32_e32 v36, 0xffff0000, v36
	v_fma_f32 v30, -v218, v34, v30
	v_fma_f32 v31, -v219, v35, v31
	v_fma_f32 v38, -v218, v40, v38
	v_fma_f32 v39, -v219, v41, v39
	v_fma_f32 v40, -v218, v44, v42
	v_fma_f32 v41, -v219, v45, v43
	v_fma_f32 v42, -v218, v48, v46
	v_fma_f32 v43, -v219, v49, v47
	v_fma_f32 v32, -v218, v36, v32
	v_fma_f32 v33, -v219, v37, v33
	v_mul_f32_e32 v36, v30, v30
	v_mul_f32_e32 v37, v31, v31
	v_and_b32_e32 v19, 0xffff0000, v19
	v_and_b32_e32 v18, 0xffff0000, v18
	v_and_b32_e32 v27, 0xffff0000, v27
	v_and_b32_e32 v26, 0xffff0000, v26
	v_fma_f32 v34, -v218, v52, v50
	v_fma_f32 v35, -v219, v53, v51
	v_mul_f32_e32 v44, v32, v32
	v_mul_f32_e32 v45, v33, v33
	v_fma_f32 v36, v42, v42, v36
	v_fma_f32 v37, v43, v43, v37
	v_fma_f32 v26, -v218, v26, v18
	v_fma_f32 v27, -v219, v27, v19
	v_fma_f32 v44, v34, v34, v44
	v_fma_f32 v45, v35, v35, v45
	v_add_f32_e32 v1, v36, v37
	v_and_b32_e32 v21, 0xffff0000, v21
	v_and_b32_e32 v20, 0xffff0000, v20
	v_and_b32_e32 v29, 0xffff0000, v29
	v_and_b32_e32 v28, 0xffff0000, v28
	v_mul_f32_e32 v18, v26, v26
	v_mul_f32_e32 v19, v27, v27
	v_add_f32_e32 v1, v44, v1
	v_fma_f32 v28, -v218, v28, v20
	v_fma_f32 v29, -v219, v29, v21
	v_fma_f32 v18, v38, v38, v18
	v_fma_f32 v19, v39, v39, v19
	v_add_f32_e32 v1, v45, v1
	v_mul_f32_e32 v20, v28, v28
	v_mul_f32_e32 v21, v29, v29
	v_add_f32_e32 v1, v18, v1
	v_fma_f32 v20, v40, v40, v20
	v_fma_f32 v21, v41, v41, v21
	v_add_f32_e32 v1, v19, v1
	v_add_f32_e32 v1, v20, v1
	v_add_f32_e32 v1, v21, v1
	ds_bpermute_b32 v20, v223, v1
	s_waitcnt vmcnt(3)
	v_mov_b32_e32 v21, v16
	v_mov_b32_e32 v16, v15
	s_waitcnt vmcnt(2)
	v_mov_b32_e32 v15, v12
	v_mov_b32_e32 v12, v11
	s_waitcnt lgkmcnt(0)
	v_add_f32_e32 v1, v1, v20
	ds_bpermute_b32 v36, v230, v1
	v_mov_b32_e32 v20, v14
	v_mov_b32_e32 v14, v10
	s_waitcnt vmcnt(1)
	v_mov_b32_e32 v10, v6
	v_mov_b32_e32 v11, v8
	s_waitcnt lgkmcnt(0)
	v_add_f32_e32 v1, v1, v36
	ds_bpermute_b32 v36, v231, v1
	v_mov_b32_e32 v8, v7
	s_waitcnt vmcnt(0)
	v_mov_b32_e32 v7, v4
	v_lshl_add_u64 v[18:19], s[6:7], 0, v[24:25]
	s_waitcnt lgkmcnt(0)
	v_add_f32_e32 v1, v1, v36
	v_fmamk_f32 v1, v1, 0x3c000000, v235
	v_mul_f32_e32 v6, 0x4f800000, v1
	v_cmp_gt_f32_e32 vcc, s0, v1
	s_nop 1
	v_cndmask_b32_e32 v1, v1, v6, vcc
	v_sqrt_f32_e32 v36, v1
	v_mov_b32_e32 v6, v2
	v_add_u32_e32 v2, -1, v36
	v_add_u32_e32 v4, 1, v36
	v_fma_f32 v37, -v2, v36, v1
	v_fma_f32 v44, -v4, v36, v1
	v_cmp_ge_f32_e64 s[6:7], 0, v37
	s_nop 1
	v_cndmask_b32_e64 v2, v36, v2, s[6:7]
	v_cmp_lt_f32_e64 s[6:7], 0, v44
	s_nop 1
	v_cndmask_b32_e64 v2, v2, v4, s[6:7]
	v_mul_f32_e32 v4, 0x37800000, v2
	v_cndmask_b32_e32 v2, v2, v4, vcc
	v_cmp_class_f32_e32 vcc, v1, v236
	v_mov_b32_e32 v4, v3
	s_nop 0
	v_cndmask_b32_e32 v1, v2, v1, vcc
	v_div_scale_f32 v2, s[6:7], v1, v1, s56
	v_rcp_f32_e32 v36, v2
	v_div_scale_f32 v3, vcc, s56, v1, s56
	v_fma_f32 v37, -v2, v36, 1.0
	v_fmac_f32_e32 v36, v37, v36
	v_mul_f32_e32 v37, v3, v36
	v_fma_f32 v44, -v2, v37, v3
	v_fmac_f32_e32 v37, v44, v36
	v_fma_f32 v2, -v2, v37, v3
	v_div_fmas_f32 v2, v2, v36, v37
	v_div_fixup_f32 v2, v2, v1, s56
	v_mul_f32_e32 v36, v42, v2
	v_mul_f32_e32 v37, v43, v2
	v_mul_f32_e32 v38, v38, v2
	v_mul_f32_e32 v39, v39, v2
	v_mul_f32_e32 v26, v26, v2
	v_mul_f32_e32 v27, v27, v2
	v_mul_f32_e32 v30, v30, v2
	v_mul_f32_e32 v31, v31, v2
	v_mul_f32_e32 v34, v34, v2
	v_mul_f32_e32 v35, v35, v2
	v_mul_f32_e32 v32, v32, v2
	v_mul_f32_e32 v33, v33, v2
	v_mul_f32_e32 v40, v40, v2
	v_mul_f32_e32 v41, v41, v2
	v_mul_f32_e32 v3, v29, v2
	v_mul_f32_e32 v2, v28, v2
	v_mul_f32_e32 v28, v20, v36
	v_mul_f32_e32 v29, v21, v37
	v_mul_f32_e32 v36, v10, v38
	v_mul_f32_e32 v37, v11, v39
	v_mul_f32_e32 v38, v8, v26
	v_mul_f32_e32 v39, v9, v27
	v_lshl_add_u64 v[26:27], s[70:71], 0, v[22:23]
	v_mul_f32_e32 v30, v16, v30
	v_mul_f32_e32 v31, v17, v31
	v_mul_f32_e32 v32, v12, v32
	v_mul_f32_e32 v33, v13, v33
	v_lshlrev_b64 v[26:27], 11, v[26:27]
	v_mul_f32_e32 v34, v14, v34
	v_mul_f32_e32 v35, v15, v35
	v_lshl_add_u64 v[42:43], v[18:19], 0, v[26:27]
	v_bfe_u32 v1, v33, 16, 1
	v_bfe_u32 v23, v32, 16, 1
	v_bfe_u32 v26, v31, 16, 1
	v_bfe_u32 v27, v30, 16, 1
	v_add3_u32 v30, v30, v27, s57
	v_add3_u32 v26, v31, v26, s57
	v_add3_u32 v23, v32, v23, s57
	v_add3_u32 v1, v33, v1, s57
	v_bfe_u32 v27, v28, 16, 1
	v_bfe_u32 v31, v29, 16, 1
	v_bfe_u32 v32, v34, 16, 1
	v_bfe_u32 v33, v35, 16, 1
	v_add3_u32 v33, v35, v33, s57
	v_add3_u32 v32, v34, v32, s57
	v_add3_u32 v29, v29, v31, s57
	v_add3_u32 v27, v28, v27, s57
	v_lshrrev_b32_e32 v31, 16, v27
	v_lshrrev_b32_e32 v27, 16, v29
	v_lshrrev_b32_e32 v28, 16, v32
	v_lshrrev_b32_e32 v29, 16, v33
	v_mul_f32_e32 v2, v4, v2
	v_mul_f32_e32 v3, v5, v3
	v_and_or_b32 v29, v1, s14, v29
	v_and_or_b32 v28, v23, s14, v28
	v_and_or_b32 v27, v26, s14, v27
	v_and_or_b32 v26, v30, s14, v31
	v_mul_f32_e32 v40, v6, v40
	v_mul_f32_e32 v41, v7, v41
	global_store_dwordx4 v[42:43], v[26:29], off
	v_bfe_u32 v1, v3, 16, 1
	v_bfe_u32 v23, v2, 16, 1
	v_bfe_u32 v27, v38, 16, 1
	v_add3_u32 v30, v38, v27, s57
	v_add3_u32 v2, v2, v23, s57
	v_add3_u32 v1, v3, v1, s57
	v_bfe_u32 v3, v36, 16, 1
	v_bfe_u32 v23, v37, 16, 1
	v_bfe_u32 v27, v40, 16, 1
	v_bfe_u32 v28, v41, 16, 1
	v_bfe_u32 v26, v39, 16, 1
	v_add3_u32 v28, v41, v28, s57
	v_add3_u32 v27, v40, v27, s57
	v_add3_u32 v23, v37, v23, s57
	v_add3_u32 v3, v36, v3, s57
	v_add3_u32 v26, v39, v26, s57
	v_lshrrev_b32_e32 v3, 16, v3
	v_lshrrev_b32_e32 v23, 16, v23
	v_lshrrev_b32_e32 v27, 16, v27
	v_lshrrev_b32_e32 v28, 16, v28
	v_and_or_b32 v29, v1, s14, v28
	v_and_or_b32 v28, v2, s14, v27
	v_and_or_b32 v27, v26, s14, v23
	v_and_or_b32 v26, v30, s14, v3
	v_or_b32_e32 v2, 8, v22
	v_mov_b32_e32 v3, v0
	global_store_dwordx4 v[42:43], v[26:29], off offset:16
	s_nop 1
	v_lshl_add_u64 v[26:27], s[76:77], 0, v[2:3]
	v_lshlrev_b64 v[26:27], 12, v[26:27]
	v_lshl_add_u64 v[26:27], s[28:29], 0, v[26:27]
	v_lshl_add_u64 v[26:27], v[26:27], 0, s[72:73]
	v_lshl_add_u64 v[38:39], v[26:27], 0, v[24:25]
	global_load_dwordx4 v[26:29], v[38:39], off offset:16
	global_load_dwordx4 v[30:33], v[38:39], off offset:2064
	global_load_dwordx4 v[34:37], v[38:39], off
	s_nop 0
	global_load_dwordx4 v[38:41], v[38:39], off offset:2048
	v_lshl_add_u64 v[2:3], s[70:71], 0, v[2:3]
	v_lshlrev_b64 v[2:3], 11, v[2:3]
	v_lshl_add_u64 v[2:3], v[18:19], 0, v[2:3]
	s_waitcnt vmcnt(3)
; __device__ __forceinline__ unsigned pk2(float lo, float hi) { return f2bf(lo) | (f2bf(hi) << 16); }
; template <int l> __device__ __forceinline__ void layer_body(const Args& a, unsigned char* lds, const XcdBarrier& bar, int G, int bx, int vcu, int gw, int NGW, int lane_, int tid_k, int wave) {
;     ...
;                             for (int it = 0; it < 4; ++it) { const int r = wave * 32 + it * 8 + rsub; const size_t lr = (size_t)b * SEQ + (size_t)qb * 256 + r;
;                                 const v4u* p1 = (const v4u*)(OP + lr * 2048 + h * 128) + ch * 2; const v4u* p2 = (const v4u*)(OP + lr * 2048 + 1024 + h * 128) + ch * 2;
;                                 const v4u a0 = p1[0], a1 = p1[1], b0 = p2[0], b1 = p2[1];
;                                 const unsigned wa[8] = {a0.x, a0.y, a0.z, a0.w, a1.x, a1.y, a1.z, a1.w}, wb[8] = {b0.x, b0.y, b0.z, b0.w, b1.x, b1.y, b1.z, b1.w};
;                                 float o[16]; float ss = 0.f;
; #pragma unroll
;                                 for (int e = 0; e < 8; ++e) { o[2 * e] = bflo(wa[e]) - lam * bflo(wb[e]); o[2 * e + 1] = bfhi(wa[e]) - lam * bfhi(wb[e]); ss += o[2 * e] * o[2 * e] + o[2 * e + 1] * o[2 * e + 1]; }
;                                 ss += __shfl_xor(ss, 1); ss += __shfl_xor(ss, 2); ss += __shfl_xor(ss, 4);
;                                 const float rs = (1.0f - LAMBDA_INIT) / sqrtf(ss * (1.0f / 128.0f) + EPS);
;                                 unsigned w[8];
; #pragma unroll
;                                 for (int e = 0; e < 8; ++e) w[e] = pk2(o[2 * e] * rs * gn[2 * e], o[2 * e + 1] * rs * gn[2 * e + 1]);
;                                 v4u* op = (v4u*)(AO + (rq + r) * DMODEL + h * 128) + ch * 2; op[0] = (v4u){w[0], w[1], w[2], w[3]}; op[1] = (v4u){w[4], w[5], w[6], w[7]}; }
	v_lshlrev_b32_e32 v43, 16, v27
	v_lshlrev_b32_e32 v42, 16, v26
	s_waitcnt vmcnt(2)
	v_lshlrev_b32_e32 v45, 16, v31
	v_lshlrev_b32_e32 v44, 16, v30
	v_and_b32_e32 v27, 0xffff0000, v27
	v_and_b32_e32 v26, 0xffff0000, v26
	v_and_b32_e32 v31, 0xffff0000, v31
	v_and_b32_e32 v30, 0xffff0000, v30
	v_lshlrev_b32_e32 v47, 16, v29
	v_lshlrev_b32_e32 v46, 16, v28
	v_lshlrev_b32_e32 v49, 16, v33
	v_lshlrev_b32_e32 v48, 16, v32
	v_fma_f32 v26, -v218, v30, v26
	v_fma_f32 v27, -v219, v31, v27
	v_fma_f32 v30, -v218, v48, v46
	v_fma_f32 v31, -v219, v49, v47
	s_waitcnt vmcnt(1)
	v_lshlrev_b32_e32 v47, 16, v35
	v_lshlrev_b32_e32 v46, 16, v34
	s_waitcnt vmcnt(0)
	v_lshlrev_b32_e32 v49, 16, v39
	v_lshlrev_b32_e32 v48, 16, v38
	v_and_b32_e32 v35, 0xffff0000, v35
	v_and_b32_e32 v34, 0xffff0000, v34
	v_and_b32_e32 v39, 0xffff0000, v39
	v_and_b32_e32 v38, 0xffff0000, v38
	v_fma_f32 v46, -v218, v48, v46
	v_fma_f32 v47, -v219, v49, v47
	v_fma_f32 v34, -v218, v38, v34
	v_fma_f32 v35, -v219, v39, v35
	v_lshlrev_b32_e32 v49, 16, v37
	v_lshlrev_b32_e32 v48, 16, v36
	v_lshlrev_b32_e32 v51, 16, v41
	v_lshlrev_b32_e32 v50, 16, v40
	v_and_b32_e32 v37, 0xffff0000, v37
	v_and_b32_e32 v36, 0xffff0000, v36
	v_and_b32_e32 v41, 0xffff0000, v41
	v_and_b32_e32 v40, 0xffff0000, v40
	v_mul_f32_e32 v38, v34, v34
	v_mul_f32_e32 v39, v35, v35
	v_fma_f32 v36, -v218, v40, v36
	v_fma_f32 v37, -v219, v41, v37
	v_fma_f32 v38, v46, v46, v38
	v_fma_f32 v39, v47, v47, v39
	v_fma_f32 v48, -v218, v50, v48
	v_fma_f32 v49, -v219, v51, v49
	v_mul_f32_e32 v40, v36, v36
	v_mul_f32_e32 v41, v37, v37
	v_and_b32_e32 v29, 0xffff0000, v29
	v_and_b32_e32 v28, 0xffff0000, v28
	v_and_b32_e32 v33, 0xffff0000, v33
	v_and_b32_e32 v32, 0xffff0000, v32
	v_fma_f32 v40, v48, v48, v40
	v_fma_f32 v41, v49, v49, v41
	v_add_f32_e32 v1, v38, v39
	v_fma_f32 v42, -v218, v44, v42
	v_fma_f32 v43, -v219, v45, v43
	v_fma_f32 v28, -v218, v32, v28
	v_fma_f32 v29, -v219, v33, v29
	v_mul_f32_e32 v32, v26, v26
	v_mul_f32_e32 v33, v27, v27
	v_add_f32_e32 v1, v40, v1
	v_fma_f32 v32, v42, v42, v32
	v_fma_f32 v33, v43, v43, v33
	v_add_f32_e32 v1, v41, v1
	v_mul_f32_e32 v44, v28, v28
	v_mul_f32_e32 v45, v29, v29
	v_add_f32_e32 v1, v32, v1
	v_fma_f32 v44, v30, v30, v44
	v_fma_f32 v45, v31, v31, v45
	v_add_f32_e32 v1, v33, v1
	v_add_f32_e32 v1, v44, v1
	v_add_f32_e32 v1, v45, v1
	ds_bpermute_b32 v23, v223, v1
	s_waitcnt lgkmcnt(0)
	v_add_f32_e32 v1, v1, v23
	ds_bpermute_b32 v23, v230, v1
	s_waitcnt lgkmcnt(0)
	v_add_f32_e32 v1, v1, v23
	ds_bpermute_b32 v23, v231, v1
	s_waitcnt lgkmcnt(0)
	v_add_f32_e32 v1, v1, v23
	v_fmamk_f32 v1, v1, 0x3c000000, v235
	v_mul_f32_e32 v23, 0x4f800000, v1
	v_cmp_gt_f32_e32 vcc, s0, v1
	s_nop 1
	v_cndmask_b32_e32 v1, v1, v23, vcc
	v_sqrt_f32_e32 v23, v1
	s_nop 0
	v_add_u32_e32 v32, -1, v23
	v_fma_f32 v33, -v32, v23, v1
	v_cmp_ge_f32_e64 s[6:7], 0, v33
	v_add_u32_e32 v33, 1, v23
	s_nop 0
	v_cndmask_b32_e64 v32, v23, v32, s[6:7]
	v_fma_f32 v23, -v33, v23, v1
	v_cmp_lt_f32_e64 s[6:7], 0, v23
	s_nop 1
	v_cndmask_b32_e64 v23, v32, v33, s[6:7]
	v_mul_f32_e32 v32, 0x37800000, v23
	v_cndmask_b32_e32 v23, v23, v32, vcc
	v_cmp_class_f32_e32 vcc, v1, v236
	s_nop 1
	v_cndmask_b32_e32 v1, v23, v1, vcc
	v_div_scale_f32 v23, s[6:7], v1, v1, s56
	v_rcp_f32_e32 v32, v23
	s_nop 0
	v_fma_f32 v33, -v23, v32, 1.0
	v_fmac_f32_e32 v32, v33, v32
	v_div_scale_f32 v33, vcc, s56, v1, s56
	v_mul_f32_e32 v38, v33, v32
	v_fma_f32 v39, -v23, v38, v33
	v_fmac_f32_e32 v38, v39, v32
	v_fma_f32 v23, -v23, v38, v33
	v_div_fmas_f32 v23, v23, v32, v38
	v_div_fixup_f32 v32, v23, v1, s56
	v_mul_f32_e32 v26, v26, v32
	v_mul_f32_e32 v27, v27, v32
	v_mul_f32_e32 v34, v34, v32
	v_mul_f32_e32 v35, v35, v32
	v_mul_f32_e32 v44, v8, v26
	v_mul_f32_e32 v45, v9, v27
	v_mul_f32_e32 v26, v30, v32
	v_mul_f32_e32 v27, v31, v32
	v_mul_f32_e32 v38, v46, v32
	v_mul_f32_e32 v39, v47, v32
	v_mul_f32_e32 v34, v16, v34
	v_mul_f32_e32 v35, v17, v35
	v_mul_f32_e32 v40, v48, v32
	v_mul_f32_e32 v41, v49, v32
	v_mul_f32_e32 v30, v6, v26
	v_mul_f32_e32 v31, v7, v27
	v_mul_f32_e32 v26, v28, v32
	v_mul_f32_e32 v27, v29, v32
	v_mul_f32_e32 v38, v20, v38
	v_mul_f32_e32 v39, v21, v39
	v_mul_f32_e32 v40, v14, v40
	v_mul_f32_e32 v41, v15, v41
	v_mul_f32_e32 v36, v36, v32
	v_mul_f32_e32 v37, v37, v32
	v_mul_f32_e32 v42, v42, v32
	v_mul_f32_e32 v43, v43, v32
	v_mul_f32_e32 v32, v4, v26
	v_mul_f32_e32 v33, v5, v27
	v_bfe_u32 v26, v35, 16, 1
	v_bfe_u32 v27, v34, 16, 1
	v_mul_f32_e32 v36, v12, v36
	v_mul_f32_e32 v37, v13, v37
	v_add3_u32 v34, v34, v27, s57
	v_add3_u32 v26, v35, v26, s57
	v_bfe_u32 v27, v38, 16, 1
	v_bfe_u32 v28, v39, 16, 1
	v_bfe_u32 v29, v40, 16, 1
	v_bfe_u32 v35, v41, 16, 1
	v_bfe_u32 v1, v37, 16, 1
	v_bfe_u32 v23, v36, 16, 1
	v_add3_u32 v35, v41, v35, s57
	v_add3_u32 v29, v40, v29, s57
	v_add3_u32 v28, v39, v28, s57
	v_add3_u32 v27, v38, v27, s57
	v_add3_u32 v23, v36, v23, s57
	v_add3_u32 v1, v37, v1, s57
	v_lshrrev_b32_e32 v36, 16, v27
	v_lshrrev_b32_e32 v27, 16, v28
	v_lshrrev_b32_e32 v28, 16, v29
	v_lshrrev_b32_e32 v29, 16, v35
	v_and_or_b32 v29, v1, s14, v29
	v_and_or_b32 v28, v23, s14, v28
	v_and_or_b32 v27, v26, s14, v27
	v_and_or_b32 v26, v34, s14, v36
	v_mul_f32_e32 v42, v10, v42
	v_mul_f32_e32 v43, v11, v43
	global_store_dwordx4 v[2:3], v[26:29], off
	v_bfe_u32 v23, v32, 16, 1
	v_add3_u32 v23, v32, v23, s57
	v_bfe_u32 v27, v44, 16, 1
	v_add3_u32 v34, v44, v27, s57
	v_bfe_u32 v27, v42, 16, 1
	v_bfe_u32 v28, v43, 16, 1
	v_bfe_u32 v29, v30, 16, 1
	v_bfe_u32 v32, v31, 16, 1
	v_bfe_u32 v1, v33, 16, 1
	v_bfe_u32 v26, v45, 16, 1
	v_add3_u32 v31, v31, v32, s57
	v_add3_u32 v29, v30, v29, s57
	v_add3_u32 v28, v43, v28, s57
	v_add3_u32 v27, v42, v27, s57
	v_add3_u32 v26, v45, v26, s57
	v_add3_u32 v1, v33, v1, s57
	v_lshrrev_b32_e32 v30, 16, v27
	v_lshrrev_b32_e32 v27, 16, v28
	v_lshrrev_b32_e32 v28, 16, v29
	v_lshrrev_b32_e32 v29, 16, v31
	v_and_or_b32 v29, v1, s14, v29
	v_and_or_b32 v28, v23, s14, v28
	v_and_or_b32 v27, v26, s14, v27
	v_and_or_b32 v26, v34, s14, v30
	global_store_dwordx4 v[2:3], v[26:29], off offset:16
	v_or_b32_e32 v2, 16, v22
	v_mov_b32_e32 v3, v0
	v_lshl_add_u64 v[26:27], s[76:77], 0, v[2:3]
	v_lshlrev_b64 v[26:27], 12, v[26:27]
	v_lshl_add_u64 v[26:27], s[28:29], 0, v[26:27]
	v_lshl_add_u64 v[26:27], v[26:27], 0, s[72:73]
	v_lshl_add_u64 v[38:39], v[26:27], 0, v[24:25]
	global_load_dwordx4 v[26:29], v[38:39], off offset:16
	global_load_dwordx4 v[30:33], v[38:39], off offset:2064
	global_load_dwordx4 v[34:37], v[38:39], off
	s_nop 0
	global_load_dwordx4 v[38:41], v[38:39], off offset:2048
	v_lshl_add_u64 v[2:3], s[70:71], 0, v[2:3]
	v_lshlrev_b64 v[2:3], 11, v[2:3]
	v_lshl_add_u64 v[2:3], v[18:19], 0, v[2:3]
	s_waitcnt vmcnt(3)
; __device__ __forceinline__ unsigned pk2(float lo, float hi) { return f2bf(lo) | (f2bf(hi) << 16); }
; template <int l> __device__ __forceinline__ void layer_body(const Args& a, unsigned char* lds, const XcdBarrier& bar, int G, int bx, int vcu, int gw, int NGW, int lane_, int tid_k, int wave) {
;     ...
;                             for (int it = 0; it < 4; ++it) { const int r = wave * 32 + it * 8 + rsub; const size_t lr = (size_t)b * SEQ + (size_t)qb * 256 + r;
;                                 const v4u* p1 = (const v4u*)(OP + lr * 2048 + h * 128) + ch * 2; const v4u* p2 = (const v4u*)(OP + lr * 2048 + 1024 + h * 128) + ch * 2;
;                                 const v4u a0 = p1[0], a1 = p1[1], b0 = p2[0], b1 = p2[1];
;                                 const unsigned wa[8] = {a0.x, a0.y, a0.z, a0.w, a1.x, a1.y, a1.z, a1.w}, wb[8] = {b0.x, b0.y, b0.z, b0.w, b1.x, b1.y, b1.z, b1.w};
;                                 float o[16]; float ss = 0.f;
; #pragma unroll
;                                 for (int e = 0; e < 8; ++e) { o[2 * e] = bflo(wa[e]) - lam * bflo(wb[e]); o[2 * e + 1] = bfhi(wa[e]) - lam * bfhi(wb[e]); ss += o[2 * e] * o[2 * e] + o[2 * e + 1] * o[2 * e + 1]; }
;                                 ss += __shfl_xor(ss, 1); ss += __shfl_xor(ss, 2); ss += __shfl_xor(ss, 4);
;                                 const float rs = (1.0f - LAMBDA_INIT) / sqrtf(ss * (1.0f / 128.0f) + EPS);
;                                 unsigned w[8];
; #pragma unroll
;                                 for (int e = 0; e < 8; ++e) w[e] = pk2(o[2 * e] * rs * gn[2 * e], o[2 * e + 1] * rs * gn[2 * e + 1]);
;                                 v4u* op = (v4u*)(AO + (rq + r) * DMODEL + h * 128) + ch * 2; op[0] = (v4u){w[0], w[1], w[2], w[3]}; op[1] = (v4u){w[4], w[5], w[6], w[7]}; }
	v_lshlrev_b32_e32 v43, 16, v27
	v_lshlrev_b32_e32 v42, 16, v26
	s_waitcnt vmcnt(2)
	v_lshlrev_b32_e32 v45, 16, v31
	v_lshlrev_b32_e32 v44, 16, v30
	v_fma_f32 v42, -v218, v44, v42
	v_fma_f32 v43, -v219, v45, v43
	v_lshlrev_b32_e32 v45, 16, v29
	v_lshlrev_b32_e32 v44, 16, v28
	v_lshlrev_b32_e32 v47, 16, v33
	v_lshlrev_b32_e32 v46, 16, v32
	v_fma_f32 v44, -v218, v46, v44
	v_fma_f32 v45, -v219, v47, v45
	s_waitcnt vmcnt(1)
	v_lshlrev_b32_e32 v47, 16, v35
	v_lshlrev_b32_e32 v46, 16, v34
	s_waitcnt vmcnt(0)
	v_lshlrev_b32_e32 v49, 16, v39
	v_lshlrev_b32_e32 v48, 16, v38
	v_and_b32_e32 v35, 0xffff0000, v35
	v_and_b32_e32 v34, 0xffff0000, v34
	v_and_b32_e32 v39, 0xffff0000, v39
	v_and_b32_e32 v38, 0xffff0000, v38
	v_fma_f32 v46, -v218, v48, v46
	v_fma_f32 v47, -v219, v49, v47
	v_fma_f32 v34, -v218, v38, v34
	v_fma_f32 v35, -v219, v39, v35
	v_lshlrev_b32_e32 v49, 16, v37
	v_lshlrev_b32_e32 v48, 16, v36
	v_lshlrev_b32_e32 v51, 16, v41
	v_lshlrev_b32_e32 v50, 16, v40
	v_and_b32_e32 v37, 0xffff0000, v37
	v_and_b32_e32 v36, 0xffff0000, v36
	v_and_b32_e32 v41, 0xffff0000, v41
	v_and_b32_e32 v40, 0xffff0000, v40
	v_mul_f32_e32 v38, v34, v34
	v_mul_f32_e32 v39, v35, v35
	v_fma_f32 v36, -v218, v40, v36
	v_fma_f32 v37, -v219, v41, v37
	v_and_b32_e32 v27, 0xffff0000, v27
	v_and_b32_e32 v26, 0xffff0000, v26
	v_and_b32_e32 v31, 0xffff0000, v31
	v_and_b32_e32 v30, 0xffff0000, v30
	v_fma_f32 v38, v46, v46, v38
	v_fma_f32 v39, v47, v47, v39
	v_fma_f32 v48, -v218, v50, v48
	v_fma_f32 v49, -v219, v51, v49
	v_mul_f32_e32 v40, v36, v36
	v_mul_f32_e32 v41, v37, v37
	v_fma_f32 v26, -v218, v30, v26
	v_fma_f32 v27, -v219, v31, v27
	v_fma_f32 v40, v48, v48, v40
	v_fma_f32 v41, v49, v49, v41
	v_add_f32_e32 v1, v38, v39
	v_mul_f32_e32 v30, v26, v26
	v_mul_f32_e32 v31, v27, v27
	v_and_b32_e32 v29, 0xffff0000, v29
	v_and_b32_e32 v28, 0xffff0000, v28
	v_and_b32_e32 v33, 0xffff0000, v33
	v_and_b32_e32 v32, 0xffff0000, v32
	v_add_f32_e32 v1, v40, v1
	v_fma_f32 v30, v42, v42, v30
	v_fma_f32 v31, v43, v43, v31
	v_fma_f32 v28, -v218, v32, v28
	v_fma_f32 v29, -v219, v33, v29
	v_add_f32_e32 v1, v41, v1
	v_mul_f32_e32 v32, v28, v28
	v_mul_f32_e32 v33, v29, v29
	v_add_f32_e32 v1, v30, v1
	v_fma_f32 v32, v44, v44, v32
	v_fma_f32 v33, v45, v45, v33
	v_add_f32_e32 v1, v31, v1
	v_add_f32_e32 v1, v32, v1
	v_add_f32_e32 v1, v33, v1
	ds_bpermute_b32 v23, v223, v1
	s_waitcnt lgkmcnt(0)
	v_add_f32_e32 v1, v1, v23
	ds_bpermute_b32 v23, v230, v1
	s_waitcnt lgkmcnt(0)
	v_add_f32_e32 v1, v1, v23
	ds_bpermute_b32 v23, v231, v1
	s_waitcnt lgkmcnt(0)
	v_add_f32_e32 v1, v1, v23
	v_fmamk_f32 v1, v1, 0x3c000000, v235
	v_mul_f32_e32 v23, 0x4f800000, v1
	v_cmp_gt_f32_e32 vcc, s0, v1
	s_nop 1
	v_cndmask_b32_e32 v1, v1, v23, vcc
	v_sqrt_f32_e32 v23, v1
	s_nop 0
	v_add_u32_e32 v30, -1, v23
	v_fma_f32 v31, -v30, v23, v1
	v_cmp_ge_f32_e64 s[6:7], 0, v31
	v_add_u32_e32 v31, 1, v23
	s_nop 0
	v_cndmask_b32_e64 v30, v23, v30, s[6:7]
	v_fma_f32 v23, -v31, v23, v1
	v_cmp_lt_f32_e64 s[6:7], 0, v23
	s_nop 1
	v_cndmask_b32_e64 v23, v30, v31, s[6:7]
	v_mul_f32_e32 v30, 0x37800000, v23
	v_cndmask_b32_e32 v23, v23, v30, vcc
	v_cmp_class_f32_e32 vcc, v1, v236
	s_nop 1
	v_cndmask_b32_e32 v1, v23, v1, vcc
	v_div_scale_f32 v23, s[6:7], v1, v1, s56
	v_rcp_f32_e32 v30, v23
	s_nop 0
	v_fma_f32 v31, -v23, v30, 1.0
	v_fmac_f32_e32 v30, v31, v30
	v_div_scale_f32 v31, vcc, s56, v1, s56
	v_mul_f32_e32 v32, v31, v30
	v_fma_f32 v33, -v23, v32, v31
	v_fmac_f32_e32 v32, v33, v30
	v_fma_f32 v23, -v23, v32, v31
	v_div_fmas_f32 v23, v23, v30, v32
	v_div_fixup_f32 v30, v23, v1, s56
	v_mul_f32_e32 v26, v26, v30
	v_mul_f32_e32 v27, v27, v30
	v_mul_f32_e32 v34, v34, v30
	v_mul_f32_e32 v35, v35, v30
	v_mul_f32_e32 v40, v42, v30
	v_mul_f32_e32 v41, v43, v30
	v_mul_f32_e32 v42, v8, v26
	v_mul_f32_e32 v43, v9, v27
	v_mul_f32_e32 v26, v44, v30
	v_mul_f32_e32 v27, v45, v30
	v_mul_f32_e32 v32, v46, v30
	v_mul_f32_e32 v33, v47, v30
	v_mul_f32_e32 v34, v16, v34
	v_mul_f32_e32 v35, v17, v35
	v_mul_f32_e32 v38, v48, v30
	v_mul_f32_e32 v39, v49, v30
	v_mul_f32_e32 v44, v6, v26
	v_mul_f32_e32 v45, v7, v27
	v_mul_f32_e32 v26, v28, v30
	v_mul_f32_e32 v27, v29, v30
	v_mul_f32_e32 v32, v20, v32
	v_mul_f32_e32 v33, v21, v33
	v_mul_f32_e32 v38, v14, v38
	v_mul_f32_e32 v39, v15, v39
	v_mul_f32_e32 v36, v36, v30
	v_mul_f32_e32 v37, v37, v30
	v_mul_f32_e32 v30, v4, v26
	v_mul_f32_e32 v31, v5, v27
	v_bfe_u32 v26, v35, 16, 1
	v_bfe_u32 v27, v34, 16, 1
	v_mul_f32_e32 v36, v12, v36
	v_mul_f32_e32 v37, v13, v37
	v_add3_u32 v34, v34, v27, s57
	v_add3_u32 v26, v35, v26, s57
	v_bfe_u32 v27, v32, 16, 1
	v_bfe_u32 v28, v33, 16, 1
	v_bfe_u32 v29, v38, 16, 1
	v_bfe_u32 v35, v39, 16, 1
	v_bfe_u32 v1, v37, 16, 1
	v_bfe_u32 v23, v36, 16, 1
	v_add3_u32 v35, v39, v35, s57
	v_add3_u32 v29, v38, v29, s57
	v_add3_u32 v28, v33, v28, s57
	v_add3_u32 v27, v32, v27, s57
	v_add3_u32 v23, v36, v23, s57
	v_add3_u32 v1, v37, v1, s57
	v_lshrrev_b32_e32 v32, 16, v27
	v_lshrrev_b32_e32 v27, 16, v28
	v_lshrrev_b32_e32 v28, 16, v29
	v_lshrrev_b32_e32 v29, 16, v35
	v_and_or_b32 v29, v1, s14, v29
	v_and_or_b32 v28, v23, s14, v28
	v_and_or_b32 v27, v26, s14, v27
	v_and_or_b32 v26, v34, s14, v32
	v_mul_f32_e32 v40, v10, v40
	v_mul_f32_e32 v41, v11, v41
	global_store_dwordx4 v[2:3], v[26:29], off
	v_bfe_u32 v23, v30, 16, 1
	v_add3_u32 v23, v30, v23, s57
	v_bfe_u32 v27, v42, 16, 1
	v_add3_u32 v32, v42, v27, s57
	v_bfe_u32 v27, v40, 16, 1
	v_bfe_u32 v28, v41, 16, 1
	v_bfe_u32 v29, v44, 16, 1
	v_bfe_u32 v30, v45, 16, 1
	v_bfe_u32 v1, v31, 16, 1
	v_bfe_u32 v26, v43, 16, 1
	v_add3_u32 v30, v45, v30, s57
	v_add3_u32 v29, v44, v29, s57
	v_add3_u32 v28, v41, v28, s57
	v_add3_u32 v27, v40, v27, s57
	v_add3_u32 v26, v43, v26, s57
	v_add3_u32 v1, v31, v1, s57
	v_lshrrev_b32_e32 v31, 16, v27
	v_lshrrev_b32_e32 v27, 16, v28
	v_lshrrev_b32_e32 v28, 16, v29
	v_lshrrev_b32_e32 v29, 16, v30
	v_and_or_b32 v29, v1, s14, v29
	v_and_or_b32 v28, v23, s14, v28
	v_and_or_b32 v27, v26, s14, v27
	v_and_or_b32 v26, v32, s14, v31
	global_store_dwordx4 v[2:3], v[26:29], off offset:16
	v_or_b32_e32 v2, 24, v22
	v_mov_b32_e32 v3, v0
	v_lshl_add_u64 v[22:23], s[76:77], 0, v[2:3]
	v_lshlrev_b64 v[22:23], 12, v[22:23]
	v_lshl_add_u64 v[22:23], s[28:29], 0, v[22:23]
	v_lshl_add_u64 v[22:23], v[22:23], 0, s[72:73]
	v_lshl_add_u64 v[34:35], v[22:23], 0, v[24:25]
	global_load_dwordx4 v[22:25], v[34:35], off offset:16
	global_load_dwordx4 v[26:29], v[34:35], off offset:2064
	global_load_dwordx4 v[30:33], v[34:35], off
	s_nop 0
	global_load_dwordx4 v[34:37], v[34:35], off offset:2048
	v_lshl_add_u64 v[2:3], s[70:71], 0, v[2:3]
	v_lshlrev_b64 v[2:3], 11, v[2:3]
	v_lshl_add_u64 v[18:19], v[18:19], 0, v[2:3]
	s_waitcnt vmcnt(3)
; __device__ __forceinline__ unsigned pk2(float lo, float hi) { return f2bf(lo) | (f2bf(hi) << 16); }
; template <int l> __device__ __forceinline__ void layer_body(const Args& a, unsigned char* lds, const XcdBarrier& bar, int G, int bx, int vcu, int gw, int NGW, int lane_, int tid_k, int wave) {
;     ...
;                             for (int it = 0; it < 4; ++it) { const int r = wave * 32 + it * 8 + rsub; const size_t lr = (size_t)b * SEQ + (size_t)qb * 256 + r;
;                                 const v4u* p1 = (const v4u*)(OP + lr * 2048 + h * 128) + ch * 2; const v4u* p2 = (const v4u*)(OP + lr * 2048 + 1024 + h * 128) + ch * 2;
;                                 const v4u a0 = p1[0], a1 = p1[1], b0 = p2[0], b1 = p2[1];
;                                 const unsigned wa[8] = {a0.x, a0.y, a0.z, a0.w, a1.x, a1.y, a1.z, a1.w}, wb[8] = {b0.x, b0.y, b0.z, b0.w, b1.x, b1.y, b1.z, b1.w};
;                                 float o[16]; float ss = 0.f;
; #pragma unroll
;                                 for (int e = 0; e < 8; ++e) { o[2 * e] = bflo(wa[e]) - lam * bflo(wb[e]); o[2 * e + 1] = bfhi(wa[e]) - lam * bfhi(wb[e]); ss += o[2 * e] * o[2 * e] + o[2 * e + 1] * o[2 * e + 1]; }
;                                 ss += __shfl_xor(ss, 1); ss += __shfl_xor(ss, 2); ss += __shfl_xor(ss, 4);
;                                 const float rs = (1.0f - LAMBDA_INIT) / sqrtf(ss * (1.0f / 128.0f) + EPS);
;                                 unsigned w[8];
; #pragma unroll
;                                 for (int e = 0; e < 8; ++e) w[e] = pk2(o[2 * e] * rs * gn[2 * e], o[2 * e + 1] * rs * gn[2 * e + 1]);
;                                 v4u* op = (v4u*)(AO + (rq + r) * DMODEL + h * 128) + ch * 2; op[0] = (v4u){w[0], w[1], w[2], w[3]}; op[1] = (v4u){w[4], w[5], w[6], w[7]}; }
	v_lshlrev_b32_e32 v39, 16, v23
	v_lshlrev_b32_e32 v38, 16, v22
	s_waitcnt vmcnt(2)
	v_lshlrev_b32_e32 v41, 16, v27
	v_lshlrev_b32_e32 v40, 16, v26
	v_fma_f32 v38, -v218, v40, v38
	v_fma_f32 v39, -v219, v41, v39
	v_lshlrev_b32_e32 v41, 16, v25
	v_lshlrev_b32_e32 v40, 16, v24
	v_lshlrev_b32_e32 v43, 16, v29
	v_lshlrev_b32_e32 v42, 16, v28
	v_fma_f32 v40, -v218, v42, v40
	v_fma_f32 v41, -v219, v43, v41
	s_waitcnt vmcnt(1)
	v_lshlrev_b32_e32 v43, 16, v31
	v_lshlrev_b32_e32 v42, 16, v30
	s_waitcnt vmcnt(0)
	v_lshlrev_b32_e32 v45, 16, v35
	v_lshlrev_b32_e32 v44, 16, v34
	v_and_b32_e32 v31, 0xffff0000, v31
	v_and_b32_e32 v30, 0xffff0000, v30
	v_and_b32_e32 v35, 0xffff0000, v35
	v_and_b32_e32 v34, 0xffff0000, v34
	v_fma_f32 v42, -v218, v44, v42
	v_fma_f32 v43, -v219, v45, v43
	v_fma_f32 v30, -v218, v34, v30
	v_fma_f32 v31, -v219, v35, v31
	v_lshlrev_b32_e32 v45, 16, v33
	v_lshlrev_b32_e32 v44, 16, v32
	v_lshlrev_b32_e32 v47, 16, v37
	v_lshlrev_b32_e32 v46, 16, v36
	v_and_b32_e32 v33, 0xffff0000, v33
	v_and_b32_e32 v32, 0xffff0000, v32
	v_and_b32_e32 v37, 0xffff0000, v37
	v_and_b32_e32 v36, 0xffff0000, v36
	v_mul_f32_e32 v34, v30, v30
	v_mul_f32_e32 v35, v31, v31
	v_fma_f32 v32, -v218, v36, v32
	v_fma_f32 v33, -v219, v37, v33
	v_and_b32_e32 v23, 0xffff0000, v23
	v_and_b32_e32 v22, 0xffff0000, v22
	v_and_b32_e32 v27, 0xffff0000, v27
	v_and_b32_e32 v26, 0xffff0000, v26
	v_fma_f32 v34, v42, v42, v34
	v_fma_f32 v35, v43, v43, v35
	v_fma_f32 v44, -v218, v46, v44
	v_fma_f32 v45, -v219, v47, v45
	v_mul_f32_e32 v36, v32, v32
	v_mul_f32_e32 v37, v33, v33
	v_fma_f32 v22, -v218, v26, v22
	v_fma_f32 v23, -v219, v27, v23
	v_fma_f32 v36, v44, v44, v36
	v_fma_f32 v37, v45, v45, v37
	v_add_f32_e32 v1, v34, v35
	v_mul_f32_e32 v26, v22, v22
	v_mul_f32_e32 v27, v23, v23
	v_and_b32_e32 v25, 0xffff0000, v25
	v_and_b32_e32 v24, 0xffff0000, v24
	v_and_b32_e32 v29, 0xffff0000, v29
	v_and_b32_e32 v28, 0xffff0000, v28
	v_add_f32_e32 v1, v36, v1
	v_fma_f32 v26, v38, v38, v26
	v_fma_f32 v27, v39, v39, v27
	v_fma_f32 v24, -v218, v28, v24
	v_fma_f32 v25, -v219, v29, v25
	v_add_f32_e32 v1, v37, v1
	v_mul_f32_e32 v28, v24, v24
	v_mul_f32_e32 v29, v25, v25
	v_add_f32_e32 v1, v26, v1
	v_fma_f32 v28, v40, v40, v28
	v_fma_f32 v29, v41, v41, v29
	v_add_f32_e32 v1, v27, v1
	v_add_f32_e32 v1, v28, v1
	v_add_f32_e32 v1, v29, v1
	ds_bpermute_b32 v26, v223, v1
	s_waitcnt lgkmcnt(0)
	v_add_f32_e32 v1, v1, v26
	ds_bpermute_b32 v26, v230, v1
	s_waitcnt lgkmcnt(0)
	v_add_f32_e32 v1, v1, v26
	ds_bpermute_b32 v26, v231, v1
	s_waitcnt lgkmcnt(0)
	v_add_f32_e32 v1, v1, v26
	v_fmamk_f32 v1, v1, 0x3c000000, v235
	v_mul_f32_e32 v26, 0x4f800000, v1
	v_cmp_gt_f32_e32 vcc, s0, v1
	s_nop 1
	v_cndmask_b32_e32 v1, v1, v26, vcc
	v_sqrt_f32_e32 v26, v1
	s_nop 0
	v_add_u32_e32 v27, -1, v26
	v_fma_f32 v28, -v27, v26, v1
	v_cmp_ge_f32_e64 s[6:7], 0, v28
	v_add_u32_e32 v28, 1, v26
	s_nop 0
	v_cndmask_b32_e64 v27, v26, v27, s[6:7]
	v_fma_f32 v26, -v28, v26, v1
	v_cmp_lt_f32_e64 s[6:7], 0, v26
	s_nop 1
	v_cndmask_b32_e64 v26, v27, v28, s[6:7]
	v_mul_f32_e32 v27, 0x37800000, v26
	v_cndmask_b32_e32 v26, v26, v27, vcc
	v_cmp_class_f32_e32 vcc, v1, v236
	s_nop 1
	v_cndmask_b32_e32 v1, v26, v1, vcc
	v_div_scale_f32 v26, s[6:7], v1, v1, s56
	v_rcp_f32_e32 v27, v26
	s_nop 0
	v_fma_f32 v28, -v26, v27, 1.0
	v_fmac_f32_e32 v27, v28, v27
	v_div_scale_f32 v28, vcc, s56, v1, s56
	v_mul_f32_e32 v29, v28, v27
	v_fma_f32 v34, -v26, v29, v28
	v_fmac_f32_e32 v29, v34, v27
	v_fma_f32 v26, -v26, v29, v28
	v_div_fmas_f32 v26, v26, v27, v29
	v_div_fixup_f32 v26, v26, v1, s56
	v_mul_f32_e32 v28, v42, v26
	v_mul_f32_e32 v29, v43, v26
	v_mul_f32_e32 v22, v22, v26
	v_mul_f32_e32 v23, v23, v26
	v_mul_f32_e32 v20, v20, v28
	v_mul_f32_e32 v21, v21, v29
	v_mul_f32_e32 v28, v30, v26
	v_mul_f32_e32 v29, v31, v26
	v_mul_f32_e32 v8, v8, v22
	v_mul_f32_e32 v9, v9, v23
	v_mul_f32_e32 v16, v16, v28
	v_mul_f32_e32 v17, v17, v29
	v_mul_f32_e32 v28, v44, v26
	v_mul_f32_e32 v29, v45, v26
	v_mul_f32_e32 v22, v40, v26
	v_mul_f32_e32 v23, v41, v26
	v_mul_f32_e32 v14, v14, v28
	v_mul_f32_e32 v15, v15, v29
	v_mul_f32_e32 v28, v32, v26
	v_mul_f32_e32 v29, v33, v26
	v_mul_f32_e32 v6, v6, v22
	v_mul_f32_e32 v7, v7, v23
	v_mul_f32_e32 v12, v12, v28
	v_mul_f32_e32 v13, v13, v29
	v_mul_f32_e32 v22, v24, v26
	v_mul_f32_e32 v23, v25, v26
	v_bfe_u32 v1, v13, 16, 1
	v_mul_f32_e32 v22, v4, v22
	v_mul_f32_e32 v23, v5, v23
	v_bfe_u32 v2, v12, 16, 1
	v_bfe_u32 v4, v16, 16, 1
	v_add3_u32 v16, v16, v4, s57
	v_add3_u32 v2, v12, v2, s57
	v_add3_u32 v1, v13, v1, s57
	v_bfe_u32 v4, v20, 16, 1
	v_bfe_u32 v5, v21, 16, 1
	v_bfe_u32 v12, v14, 16, 1
	v_bfe_u32 v13, v15, 16, 1
	v_bfe_u32 v3, v17, 16, 1
	v_add3_u32 v13, v15, v13, s57
	v_add3_u32 v12, v14, v12, s57
	v_add3_u32 v5, v21, v5, s57
	v_add3_u32 v4, v20, v4, s57
	v_add3_u32 v3, v17, v3, s57
	v_lshrrev_b32_e32 v14, 16, v4
	v_lshrrev_b32_e32 v15, 16, v5
	v_lshrrev_b32_e32 v4, 16, v12
	v_lshrrev_b32_e32 v5, 16, v13
	v_mul_f32_e32 v28, v38, v26
	v_mul_f32_e32 v29, v39, v26
	v_and_or_b32 v5, v1, s14, v5
	v_and_or_b32 v4, v2, s14, v4
	v_and_or_b32 v3, v3, s14, v15
	v_and_or_b32 v2, v16, s14, v14
	v_mul_f32_e32 v10, v10, v28
	v_mul_f32_e32 v11, v11, v29
	global_store_dwordx4 v[18:19], v[2:5], off
	v_bfe_u32 v12, v7, 16, 1
	v_bfe_u32 v1, v23, 16, 1
	v_bfe_u32 v3, v9, 16, 1
	v_bfe_u32 v4, v8, 16, 1
	v_add3_u32 v8, v8, v4, s57
	v_add3_u32 v3, v9, v3, s57
	v_bfe_u32 v4, v10, 16, 1
	v_bfe_u32 v5, v11, 16, 1
	v_bfe_u32 v9, v6, 16, 1
	v_bfe_u32 v2, v22, 16, 1
	v_add3_u32 v7, v7, v12, s57
	v_add3_u32 v6, v6, v9, s57
	v_add3_u32 v5, v11, v5, s57
	v_add3_u32 v4, v10, v4, s57
	v_add3_u32 v2, v22, v2, s57
	v_add3_u32 v1, v23, v1, s57
	v_lshrrev_b32_e32 v9, 16, v4
	v_lshrrev_b32_e32 v10, 16, v5
	v_lshrrev_b32_e32 v4, 16, v6
	v_lshrrev_b32_e32 v5, 16, v7
	v_and_or_b32 v5, v1, s14, v5
	v_and_or_b32 v4, v2, s14, v4
	v_and_or_b32 v3, v3, s14, v10
	v_and_or_b32 v2, v8, s14, v9
	global_store_dwordx4 v[18:19], v[2:5], off offset:16

; __device__ __forceinline__ unsigned pk2(float lo, float hi) { return f2bf(lo) | (f2bf(hi) << 16); }
; template <int l> __device__ __forceinline__ void layer_body(const Args& a, unsigned char* lds, const XcdBarrier& bar, int G, int bx, int vcu, int gw, int NGW, int lane_, int tid_k, int wave) {
;     ...
;             for (int lr = gw; lr < NBATCH * SEQ; lr += NGW) {
;                 const int b = lr / SEQ, pos = lr - b * SEQ; const size_t row = (size_t)b * TPB + CTXL + pos;
;                 const v4u* p1 = (const v4u*)(OP + (size_t)lr * 2048) + lane * 2; const v4u* p2 = p1 + 128;
;                 const v4u a0 = p1[0], a1 = p1[1], b0 = p2[0], b1 = p2[1];
;                 const unsigned wa[8] = {a0.x, a0.y, a0.z, a0.w, a1.x, a1.y, a1.z, a1.w}, wb[8] = {b0.x, b0.y, b0.z, b0.w, b1.x, b1.y, b1.z, b1.w};
;                 float o[16]; float ss = 0.f;
; #pragma unroll
;                 for (int e = 0; e < 8; ++e) { o[2 * e] = bflo(wa[e]) - lam * bflo(wb[e]); o[2 * e + 1] = bfhi(wa[e]) - lam * bfhi(wb[e]); ss += o[2 * e] * o[2 * e] + o[2 * e + 1] * o[2 * e + 1]; }
;                 ss += __shfl_xor(ss, 1); ss += __shfl_xor(ss, 2); ss += __shfl_xor(ss, 4);
;                 const float rs = (1.0f - LAMBDA_INIT) / sqrtf(ss * (1.0f / 128.0f) + EPS);
;                 unsigned w[8];
; #pragma unroll
;                 for (int e = 0; e < 8; ++e) w[e] = pk2(o[2 * e] * rs * gn[2 * e], o[2 * e + 1] * rs * gn[2 * e + 1]);
;                 v4u* op = (v4u*)(AO + row * DMODEL) + lane * 2; op[0] = (v4u){w[0], w[1], w[2], w[3]}; op[1] = (v4u){w[4], w[5], w[6], w[7]};
;             }
.LBB0_1236:
	global_load_dwordx4 v[32:35], v[24:25], off offset:-2048
	global_load_dwordx4 v[36:39], v[24:25], off
	global_load_dwordx4 v[18:21], v[24:25], off offset:-2064
	global_load_dwordx4 v[14:17], v[24:25], off offset:-16
	s_ashr_i32 s6, s12, 31
	s_lshr_b32 s6, s6, 19
	s_add_i32 s6, s12, s6
	s_ashr_i32 s7, s6, 13
	s_and_b32 s6, s6, 0xffffe000
	s_mul_hi_i32 s13, s7, 0x2100
	s_mulk_i32 s7, 0x2100
	s_ashr_i32 s14, s6, 31
	s_sub_u32 s6, s7, s6
	s_subb_u32 s7, s13, s14
	s_add_u32 s6, s10, s6
	s_addc_u32 s7, s11, s7
	s_lshl_b64 s[6:7], s[6:7], 11
	v_lshl_add_u64 v[40:41], v[22:23], 0, s[6:7]
	s_add_i32 s12, s12, s42
	s_add_u32 s10, s10, s42
	s_addc_u32 s11, s11, s43
	v_lshl_add_u64 v[24:25], v[24:25], 0, s[8:9]
	s_cmpk_gt_i32 s12, 0x7fff
	s_waitcnt vmcnt(3)
	v_lshlrev_b32_e32 v43, 16, v33
	v_lshlrev_b32_e32 v42, 16, v32
	s_waitcnt vmcnt(1)
	v_lshlrev_b32_e32 v51, 16, v19
	v_lshlrev_b32_e32 v50, 16, v18
	s_waitcnt vmcnt(0)
	v_lshlrev_b32_e32 v53, 16, v15
	v_lshlrev_b32_e32 v52, 16, v14
	v_and_b32_e32 v19, 0xffff0000, v19
	v_and_b32_e32 v18, 0xffff0000, v18
	v_and_b32_e32 v15, 0xffff0000, v15
	v_and_b32_e32 v14, 0xffff0000, v14
	v_lshlrev_b32_e32 v45, 16, v37
	v_lshlrev_b32_e32 v44, 16, v36
	v_and_b32_e32 v33, 0xffff0000, v33
	v_and_b32_e32 v32, 0xffff0000, v32
	v_and_b32_e32 v37, 0xffff0000, v37
	v_and_b32_e32 v36, 0xffff0000, v36
	v_lshlrev_b32_e32 v47, 16, v35
	v_lshlrev_b32_e32 v46, 16, v34
	v_lshlrev_b32_e32 v49, 16, v39
	v_lshlrev_b32_e32 v48, 16, v38
	v_and_b32_e32 v35, 0xffff0000, v35
	v_and_b32_e32 v34, 0xffff0000, v34
	v_and_b32_e32 v39, 0xffff0000, v39
	v_and_b32_e32 v38, 0xffff0000, v38
	v_lshlrev_b32_e32 v55, 16, v21
	v_lshlrev_b32_e32 v54, 16, v20
	v_lshlrev_b32_e32 v57, 16, v17
	v_lshlrev_b32_e32 v56, 16, v16
	v_and_b32_e32 v21, 0xffff0000, v21
	v_and_b32_e32 v20, 0xffff0000, v20
	v_and_b32_e32 v17, 0xffff0000, v17
	v_and_b32_e32 v16, 0xffff0000, v16
	v_fma_f32 v14, -v26, v14, v18
	v_fma_f32 v15, -v27, v15, v19
	v_fma_f32 v32, -v26, v36, v32
	v_fma_f32 v33, -v27, v37, v33
	v_fma_f32 v36, -v26, v48, v46
	v_fma_f32 v37, -v27, v49, v47
	v_fma_f32 v34, -v26, v38, v34
	v_fma_f32 v35, -v27, v39, v35
	v_fma_f32 v38, -v26, v52, v50
	v_fma_f32 v39, -v27, v53, v51
	v_fma_f32 v16, -v26, v16, v20
	v_fma_f32 v17, -v27, v17, v21
	v_mul_f32_e32 v46, v14, v14
	v_mul_f32_e32 v47, v15, v15
	v_fma_f32 v18, -v26, v56, v54
	v_fma_f32 v19, -v27, v57, v55
	v_mul_f32_e32 v48, v16, v16
	v_mul_f32_e32 v49, v17, v17
	v_fma_f32 v46, v38, v38, v46
	v_fma_f32 v47, v39, v39, v47
	v_fma_f32 v48, v18, v18, v48
	v_fma_f32 v49, v19, v19, v49
	v_add_f32_e32 v46, v46, v47
	v_fma_f32 v42, -v26, v44, v42
	v_fma_f32 v43, -v27, v45, v43
	v_mul_f32_e32 v20, v32, v32
	v_mul_f32_e32 v21, v33, v33
	v_add_f32_e32 v46, v48, v46
	v_fma_f32 v20, v42, v42, v20
	v_fma_f32 v21, v43, v43, v21
	v_add_f32_e32 v46, v49, v46
	v_mul_f32_e32 v44, v34, v34
	v_mul_f32_e32 v45, v35, v35
	v_add_f32_e32 v20, v20, v46
	v_fma_f32 v44, v36, v36, v44
	v_fma_f32 v45, v37, v37, v45
	v_add_f32_e32 v20, v21, v20
	v_add_f32_e32 v20, v44, v20
	v_add_f32_e32 v20, v45, v20
	ds_bpermute_b32 v21, v223, v20
	s_waitcnt lgkmcnt(0)
	v_add_f32_e32 v20, v20, v21
	ds_bpermute_b32 v21, v230, v20
	s_waitcnt lgkmcnt(0)
	v_add_f32_e32 v20, v20, v21
	ds_bpermute_b32 v21, v231, v20
	s_waitcnt lgkmcnt(0)
	v_add_f32_e32 v20, v20, v21
	v_fmamk_f32 v20, v20, 0x3c000000, v30
	v_mul_f32_e32 v21, 0x4f800000, v20
	v_cmp_gt_f32_e32 vcc, s4, v20
	s_nop 1
	v_cndmask_b32_e32 v20, v20, v21, vcc
	v_sqrt_f32_e32 v21, v20
	s_nop 0
	v_add_u32_e32 v44, -1, v21
	v_add_u32_e32 v45, 1, v21
	v_fma_f32 v46, -v44, v21, v20
	v_fma_f32 v47, -v45, v21, v20
	v_cmp_ge_f32_e64 s[6:7], 0, v46
	s_nop 1
	v_cndmask_b32_e64 v21, v21, v44, s[6:7]
	v_cmp_lt_f32_e64 s[6:7], 0, v47
	s_nop 1
	v_cndmask_b32_e64 v21, v21, v45, s[6:7]
	v_mul_f32_e32 v44, 0x37800000, v21
	v_cndmask_b32_e32 v21, v21, v44, vcc
	v_cmp_class_f32_e32 vcc, v20, v31
	s_nop 1
	v_cndmask_b32_e32 v20, v21, v20, vcc
	v_div_scale_f32 v21, s[6:7], v20, v20, s5
	v_rcp_f32_e32 v45, v21
	v_div_scale_f32 v44, vcc, s5, v20, s5
	v_fma_f32 v46, -v21, v45, 1.0
	v_fmac_f32_e32 v45, v46, v45
	v_mul_f32_e32 v46, v44, v45
	v_fma_f32 v47, -v21, v46, v44
	v_fmac_f32_e32 v46, v47, v45
	v_fma_f32 v21, -v21, v46, v44
	v_div_fmas_f32 v21, v21, v45, v46
	v_div_fixup_f32 v20, v21, v20, s5
	v_mul_f32_e32 v38, v38, v20
	v_mul_f32_e32 v39, v39, v20
	v_mul_f32_e32 v18, v18, v20
	v_mul_f32_e32 v19, v19, v20
	v_mul_f32_e32 v14, v14, v20
	v_mul_f32_e32 v15, v15, v20
	v_mul_f32_e32 v16, v16, v20
	v_mul_f32_e32 v17, v17, v20
	v_mul_f32_e32 v42, v42, v20
	v_mul_f32_e32 v43, v43, v20
	v_mul_f32_e32 v32, v32, v20
	v_mul_f32_e32 v33, v33, v20
	v_mul_f32_e32 v36, v36, v20
	v_mul_f32_e32 v37, v37, v20
	v_mul_f32_e32 v21, v35, v20
	v_mul_f32_e32 v20, v34, v20
	v_mul_f32_e32 v34, v0, v38
	v_mul_f32_e32 v35, v1, v39
	v_mul_f32_e32 v18, v4, v18
	v_mul_f32_e32 v19, v5, v19
	v_mul_f32_e32 v14, v28, v14
	v_mul_f32_e32 v15, v29, v15
	v_mul_f32_e32 v16, v2, v16
	v_mul_f32_e32 v17, v3, v17
	v_mul_f32_e32 v38, v8, v42
	v_mul_f32_e32 v39, v9, v43
	v_mul_f32_e32 v36, v12, v36
	v_mul_f32_e32 v37, v13, v37
	v_bfe_u32 v46, v34, 16, 1
	v_bfe_u32 v47, v35, 16, 1
	v_bfe_u32 v48, v18, 16, 1
	v_bfe_u32 v49, v19, 16, 1
	v_mul_f32_e32 v32, v6, v32
	v_mul_f32_e32 v33, v7, v33
	v_mul_f32_e32 v20, v10, v20
	v_mul_f32_e32 v21, v11, v21
	v_bfe_u32 v42, v17, 16, 1
	v_bfe_u32 v43, v16, 16, 1
	v_bfe_u32 v44, v15, 16, 1
	v_bfe_u32 v45, v14, 16, 1
	v_bfe_u32 v54, v38, 16, 1
	v_bfe_u32 v55, v39, 16, 1
	v_bfe_u32 v56, v36, 16, 1
	v_bfe_u32 v57, v37, 16, 1
	v_add3_u32 v19, v19, v49, s1
	v_add3_u32 v18, v18, v48, s1
	v_add3_u32 v35, v35, v47, s1
	v_add3_u32 v34, v34, v46, s1
	v_bfe_u32 v50, v21, 16, 1
	v_bfe_u32 v51, v20, 16, 1
	v_bfe_u32 v52, v33, 16, 1
	v_bfe_u32 v53, v32, 16, 1
	v_add3_u32 v14, v14, v45, s1
	v_add3_u32 v15, v15, v44, s1
	v_add3_u32 v16, v16, v43, s1
	v_add3_u32 v17, v17, v42, s1
	v_add3_u32 v37, v37, v57, s1
	v_add3_u32 v36, v36, v56, s1
	v_add3_u32 v39, v39, v55, s1
	v_add3_u32 v38, v38, v54, s1
	v_lshrrev_b32_e32 v34, 16, v34
	v_lshrrev_b32_e32 v35, 16, v35
	v_lshrrev_b32_e32 v18, 16, v18
	v_lshrrev_b32_e32 v19, 16, v19
	v_add3_u32 v32, v32, v53, s1
	v_add3_u32 v33, v33, v52, s1
	v_add3_u32 v20, v20, v51, s1
	v_add3_u32 v21, v21, v50, s1
	v_lshrrev_b32_e32 v38, 16, v38
	v_lshrrev_b32_e32 v39, 16, v39
	v_lshrrev_b32_e32 v36, 16, v36
	v_lshrrev_b32_e32 v37, 16, v37
	v_and_or_b32 v17, v17, s3, v19
	v_and_or_b32 v16, v16, s3, v18
	v_and_or_b32 v15, v15, s3, v35
	v_and_or_b32 v14, v14, s3, v34
	v_and_or_b32 v21, v21, s3, v37
	v_and_or_b32 v20, v20, s3, v36
	v_and_or_b32 v19, v33, s3, v39
	v_and_or_b32 v18, v32, s3, v38
	global_store_dwordx4 v[40:41], v[14:17], off
	global_store_dwordx4 v[40:41], v[18:21], off offset:16
	s_cbranch_scc0 .LBB0_1236

;     __device__ __forceinline__ void operator()(const f32x4 (&acc)[2][2][4][2], const Unit& u, int wr, int wc, int fr, int fq) const {
;         const int b = u.pm / 33, tt = u.pm - b * 33; const bool isctx = (tt == 0);
;         const float* g = gate + (isctx ? 4 : b) * 6144;
;         const float* src = isctx ? base_ctx + (size_t)b * ctx_bs : base_lat + (size_t)b * lat_bs + (size_t)(tt * 256 - 256) * 1024;
;         float* dst = out + (size_t)u.pm * 256 * 1024;
;         const int col0 = u.pn * BM + wc * 32 + 4 * fq;
;         const size_t off0 = (size_t)(wr * 64 + fr) * 1024 + col0;
; #pragma unroll
;         for (int bj = 0; bj < 2; ++bj)
; #pragma unroll
;             for (int n = 0; n < 2; ++n) { const f32x4 gv = *(const f32x4*)(g + col0 + bj * HALF + n * 16); f32x4 bs[2][4];
; #pragma unroll
;                 for (int ai = 0; ai < 2; ++ai)
; #pragma unroll
;                     for (int m = 0; m < 4; ++m) bs[ai][m] = *(const f32x4*)(src + off0 + (size_t)(ai * HALF + m * 16) * 1024 + bj * HALF + n * 16);
; #pragma unroll
;                 for (int ai = 0; ai < 2; ++ai)
; #pragma unroll
;                     for (int m = 0; m < 4; ++m) *(f32x4*)(dst + off0 + (size_t)(ai * HALF + m * 16) * 1024 + bj * HALF + n * 16) = bs[ai][m] + gv * acc[ai][bj][m][n];
;                 asm volatile("" ::: "memory"); }
.LBB0_1313:
	s_lshl_b64 s[50:51], s[50:51], 2
	v_lshl_or_b32 v142, s33, 8, v173
	s_add_u32 s50, s58, s50
	v_ashrrev_i32_e32 v143, 31, v142
	s_addc_u32 s51, s59, s51
	v_lshl_add_u64 v[144:145], v[132:133], 0, v[142:143]
	v_lshl_add_u64 v[148:149], v[142:143], 2, s[50:51]
	v_lshlrev_b64 v[142:143], 2, v[144:145]
	v_lshl_add_u64 v[150:151], s[40:41], 0, v[142:143]
	v_add_co_u32_e32 v152, vcc, s57, v150
	global_load_dwordx4 v[190:193], v[148:149], off
	s_nop 0
	v_addc_co_u32_e32 v153, vcc, 0, v151, vcc
	v_add_co_u32_e32 v156, vcc, s70, v150
	global_load_dwordx4 v[194:197], v[150:151], off
	global_load_dwordx4 v[198:201], v[152:153], off
	v_addc_co_u32_e32 v157, vcc, 0, v151, vcc
	v_add_co_u32_e32 v158, vcc, s71, v150
	s_ashr_i32 s37, s36, 31
	s_nop 0
	v_addc_co_u32_e32 v159, vcc, 0, v151, vcc
	v_add_co_u32_e32 v160, vcc, s72, v150
	global_load_dwordx4 v[202:205], v[156:157], off
	global_load_dwordx4 v[206:209], v[158:159], off
	v_addc_co_u32_e32 v161, vcc, 0, v151, vcc
	v_add_co_u32_e32 v164, vcc, s73, v150
	global_load_dwordx4 v[210:213], v[160:161], off
	s_nop 0
	v_addc_co_u32_e32 v165, vcc, 0, v151, vcc
	v_add_co_u32_e32 v166, vcc, s74, v150
	global_load_dwordx4 v[214:217], v[164:165], off
	s_nop 0
	v_addc_co_u32_e32 v167, vcc, 0, v151, vcc
	global_load_dwordx4 v[218:221], v[166:167], off
	v_add_co_u32_e32 v168, vcc, s75, v150
	s_lshl_b64 s[36:37], s[36:37], 20
	s_nop 0
	v_addc_co_u32_e32 v169, vcc, 0, v151, vcc
	global_load_dwordx4 v[224:227], v[168:169], off
	s_add_u32 s36, s48, s36
	s_addc_u32 s37, s49, s37
	v_lshl_add_u64 v[142:143], s[36:37], 0, v[142:143]
	v_add_co_u32_e32 v144, vcc, s57, v142
	s_waitcnt vmcnt(0)
	v_fma_f32 v126, v126, v192, v196
	v_fma_f32 v127, v127, v193, v197
	v_addc_co_u32_e32 v145, vcc, 0, v143, vcc
	v_add_co_u32_e32 v146, vcc, s70, v142
	v_fma_f32 v124, v124, v190, v194
	v_fma_f32 v125, v125, v191, v195
	s_nop 0
	v_addc_co_u32_e32 v147, vcc, 0, v143, vcc
	v_add_co_u32_e32 v154, vcc, s71, v142
	v_fma_f32 v122, v122, v192, v200
	v_fma_f32 v123, v123, v193, v201
	s_nop 0
	v_addc_co_u32_e32 v155, vcc, 0, v143, vcc
	v_add_co_u32_e32 v162, vcc, s72, v142
	v_fma_f32 v120, v120, v190, v198
	v_fma_f32 v121, v121, v191, v199
	s_nop 0
	v_addc_co_u32_e32 v163, vcc, 0, v143, vcc
	v_add_co_u32_e32 v170, vcc, s73, v142
	global_store_dwordx4 v[142:143], v[124:127], off
	s_nop 0
	v_addc_co_u32_e32 v171, vcc, 0, v143, vcc
	v_fma_f32 v100, v100, v190, v214
	v_fma_f32 v101, v101, v191, v215
	v_fma_f32 v118, v118, v192, v204
	v_fma_f32 v119, v119, v193, v205
	v_fma_f32 v116, v116, v190, v202
	v_fma_f32 v117, v117, v191, v203
	v_fma_f32 v114, v114, v192, v208
	v_fma_f32 v115, v115, v193, v209
	v_fma_f32 v112, v112, v190, v206
	v_fma_f32 v113, v113, v191, v207
	v_fma_f32 v106, v106, v192, v212
	v_fma_f32 v107, v107, v193, v213
	v_fma_f32 v104, v104, v190, v210
	v_fma_f32 v105, v105, v191, v211
	v_fma_f32 v102, v102, v192, v216
	v_fma_f32 v103, v103, v193, v217
	global_store_dwordx4 v[144:145], v[120:123], off
	global_store_dwordx4 v[146:147], v[116:119], off
	global_store_dwordx4 v[154:155], v[112:115], off
	global_store_dwordx4 v[162:163], v[104:107], off
	global_store_dwordx4 v[170:171], v[100:103], off
	s_nop 1
	v_fma_f32 v100, v92, v190, v218
	v_fma_f32 v101, v93, v191, v219
	v_add_co_u32_e32 v92, vcc, s74, v142
	v_fma_f32 v102, v94, v192, v220
	v_fma_f32 v103, v95, v193, v221
	s_nop 0
	v_addc_co_u32_e32 v93, vcc, 0, v143, vcc
	global_store_dwordx4 v[92:93], v[100:103], off
	s_nop 1
	v_fma_f32 v100, v80, v190, v224
	v_fma_f32 v101, v81, v191, v225
	v_add_co_u32_e32 v80, vcc, s75, v142
	v_fma_f32 v102, v82, v192, v226
	v_fma_f32 v103, v83, v193, v227
	s_nop 0
	v_addc_co_u32_e32 v81, vcc, 0, v143, vcc
	global_store_dwordx4 v[80:81], v[100:103], off
	global_load_dwordx4 v[100:103], v[148:149], off offset:64
	global_load_dwordx4 v[104:107], v[150:151], off offset:64
	global_load_dwordx4 v[112:115], v[152:153], off offset:64
	global_load_dwordx4 v[116:119], v[156:157], off offset:64
	global_load_dwordx4 v[120:123], v[158:159], off offset:64
	global_load_dwordx4 v[124:127], v[160:161], off offset:64
	global_load_dwordx4 v[190:193], v[164:165], off offset:64
	global_load_dwordx4 v[194:197], v[166:167], off offset:64
	global_load_dwordx4 v[198:201], v[168:169], off offset:64
	s_andn2_b64 vcc, exec, s[6:7]
	s_mov_b64 s[6:7], -1
	s_waitcnt vmcnt(7)
	v_fma_f32 v106, v110, v102, v106
	v_fma_f32 v107, v111, v103, v107
	v_fma_f32 v104, v108, v100, v104
	v_fma_f32 v105, v109, v101, v105
	s_waitcnt vmcnt(6)
	v_fma_f32 v98, v98, v102, v114
	v_fma_f32 v99, v99, v103, v115
	v_fma_f32 v96, v96, v100, v112
	v_fma_f32 v97, v97, v101, v113
	s_waitcnt vmcnt(5)
	v_fma_f32 v90, v90, v102, v118
	v_fma_f32 v91, v91, v103, v119
	v_fma_f32 v88, v88, v100, v116
	v_fma_f32 v89, v89, v101, v117
	s_waitcnt vmcnt(4)
	v_fma_f32 v86, v86, v102, v122
	v_fma_f32 v87, v87, v103, v123
	v_fma_f32 v84, v84, v100, v120
	v_fma_f32 v85, v85, v101, v121
	s_waitcnt vmcnt(3)
	v_fma_f32 v78, v78, v102, v126
	v_fma_f32 v79, v79, v103, v127
	v_fma_f32 v76, v76, v100, v124
	v_fma_f32 v77, v77, v101, v125
	s_waitcnt vmcnt(2)
; #define PG8_BAR __builtin_amdgcn_s_barrier()
;     __device__ __forceinline__ void operator()(const f32x4 (&acc)[2][2][4][2], const Unit& u, int wr, int wc, int fr, int fq) const {
;     ...
; #pragma unroll
;         for (int bj = 0; bj < 2; ++bj)
; #pragma unroll
;             for (int n = 0; n < 2; ++n) { const f32x4 gv = *(const f32x4*)(g + col0 + bj * HALF + n * 16); f32x4 bs[2][4];
; #pragma unroll
;                 for (int ai = 0; ai < 2; ++ai)
; #pragma unroll
;                     for (int m = 0; m < 4; ++m) bs[ai][m] = *(const f32x4*)(src + off0 + (size_t)(ai * HALF + m * 16) * 1024 + bj * HALF + n * 16);
; #pragma unroll
;                 for (int ai = 0; ai < 2; ++ai)
; #pragma unroll
;                     for (int m = 0; m < 4; ++m) *(f32x4*)(dst + off0 + (size_t)(ai * HALF + m * 16) * 1024 + bj * HALF + n * 16) = bs[ai][m] + gv * acc[ai][bj][m][n];
;                 asm volatile("" ::: "memory"); }
; template <class Epi, class Sched, bool ALIGN_EPI = false, bool SP2 = false>
; __device__ __forceinline__ void gemm_phase(PG8_LAS unsigned char* lds, const Gemm g, const Sched& S, const Epi& E) {
;     ...
;         if constexpr (ALIGN_EPI) { if (wr == 1) PG8_BAR; }
;     }
	v_fma_f32 v74, v74, v102, v192
	v_fma_f32 v75, v75, v103, v193
	v_fma_f32 v72, v72, v100, v190
	v_fma_f32 v73, v73, v101, v191
	s_waitcnt vmcnt(1)
	v_fma_f32 v66, v66, v102, v196
	v_fma_f32 v67, v67, v103, v197
	v_fma_f32 v64, v64, v100, v194
	v_fma_f32 v65, v65, v101, v195
	s_waitcnt vmcnt(0)
	v_fma_f32 v58, v58, v102, v200
	v_fma_f32 v59, v59, v103, v201
	v_fma_f32 v56, v56, v100, v198
	v_fma_f32 v57, v57, v101, v199
	global_store_dwordx4 v[142:143], v[104:107], off offset:64
	global_store_dwordx4 v[144:145], v[96:99], off offset:64
	global_store_dwordx4 v[146:147], v[88:91], off offset:64
	global_store_dwordx4 v[154:155], v[84:87], off offset:64
	global_store_dwordx4 v[162:163], v[76:79], off offset:64
	global_store_dwordx4 v[170:171], v[72:75], off offset:64
	global_store_dwordx4 v[92:93], v[64:67], off offset:64
	global_store_dwordx4 v[80:81], v[56:59], off offset:64
	global_load_dwordx4 v[56:59], v[148:149], off offset:512
	global_load_dwordx4 v[64:67], v[150:151], off offset:512
	global_load_dwordx4 v[72:75], v[152:153], off offset:512
	global_load_dwordx4 v[76:79], v[156:157], off offset:512
	global_load_dwordx4 v[82:85], v[158:159], off offset:512
	global_load_dwordx4 v[86:89], v[160:161], off offset:512
	global_load_dwordx4 v[94:97], v[164:165], off offset:512
	global_load_dwordx4 v[98:101], v[166:167], off offset:512
	global_load_dwordx4 v[102:105], v[168:169], off offset:512
	s_waitcnt vmcnt(7)
	v_fma_f32 v66, v70, v58, v66
	v_fma_f32 v67, v71, v59, v67
	v_fma_f32 v64, v68, v56, v64
	v_fma_f32 v65, v69, v57, v65
	s_waitcnt vmcnt(6)
	v_fma_f32 v62, v62, v58, v74
	v_fma_f32 v63, v63, v59, v75
	v_fma_f32 v60, v60, v56, v72
	v_fma_f32 v61, v61, v57, v73
	s_waitcnt vmcnt(5)
	v_fma_f32 v54, v54, v58, v78
	v_fma_f32 v55, v55, v59, v79
	v_fma_f32 v52, v52, v56, v76
	v_fma_f32 v53, v53, v57, v77
	s_waitcnt vmcnt(4)
	v_fma_f32 v50, v50, v58, v84
	v_fma_f32 v51, v51, v59, v85
	v_fma_f32 v48, v48, v56, v82
	v_fma_f32 v49, v49, v57, v83
	s_waitcnt vmcnt(3)
	v_fma_f32 v46, v46, v58, v88
	v_fma_f32 v47, v47, v59, v89
	v_fma_f32 v44, v44, v56, v86
	v_fma_f32 v45, v45, v57, v87
	s_waitcnt vmcnt(2)
	v_fma_f32 v38, v38, v58, v96
	v_fma_f32 v39, v39, v59, v97
	v_fma_f32 v36, v36, v56, v94
	v_fma_f32 v37, v37, v57, v95
	s_waitcnt vmcnt(1)
	v_fma_f32 v30, v30, v58, v100
	v_fma_f32 v31, v31, v59, v101
	v_fma_f32 v28, v28, v56, v98
	v_fma_f32 v29, v29, v57, v99
	s_waitcnt vmcnt(0)
	v_fma_f32 v22, v22, v58, v104
	v_fma_f32 v23, v23, v59, v105
	v_fma_f32 v20, v20, v56, v102
	v_fma_f32 v21, v21, v57, v103
	global_store_dwordx4 v[142:143], v[64:67], off offset:512
	global_store_dwordx4 v[144:145], v[60:63], off offset:512
	global_store_dwordx4 v[146:147], v[52:55], off offset:512
	global_store_dwordx4 v[154:155], v[48:51], off offset:512
	global_store_dwordx4 v[162:163], v[44:47], off offset:512
	global_store_dwordx4 v[170:171], v[36:39], off offset:512
	global_store_dwordx4 v[92:93], v[28:31], off offset:512
	global_store_dwordx4 v[80:81], v[20:23], off offset:512
	global_load_dwordx4 v[20:23], v[148:149], off offset:576
	global_load_dwordx4 v[28:31], v[150:151], off offset:576
	global_load_dwordx4 v[36:39], v[152:153], off offset:576
	global_load_dwordx4 v[44:47], v[156:157], off offset:576
	global_load_dwordx4 v[48:51], v[158:159], off offset:576
	global_load_dwordx4 v[52:55], v[160:161], off offset:576
	global_load_dwordx4 v[56:59], v[164:165], off offset:576
	global_load_dwordx4 v[60:63], v[166:167], off offset:576
	global_load_dwordx4 v[64:67], v[168:169], off offset:576
	s_waitcnt vmcnt(7)
	v_fma_f32 v30, v42, v22, v30
	v_fma_f32 v31, v43, v23, v31
	v_fma_f32 v28, v40, v20, v28
	v_fma_f32 v29, v41, v21, v29
	s_waitcnt vmcnt(6)
	v_fma_f32 v34, v34, v22, v38
	v_fma_f32 v35, v35, v23, v39
	v_fma_f32 v32, v32, v20, v36
	v_fma_f32 v33, v33, v21, v37
	s_waitcnt vmcnt(5)
	v_fma_f32 v26, v26, v22, v46
	v_fma_f32 v27, v27, v23, v47
	v_fma_f32 v24, v24, v20, v44
	v_fma_f32 v25, v25, v21, v45
	s_waitcnt vmcnt(4)
	v_fma_f32 v18, v18, v22, v50
	v_fma_f32 v19, v19, v23, v51
	v_fma_f32 v16, v16, v20, v48
	v_fma_f32 v17, v17, v21, v49
	s_waitcnt vmcnt(3)
	v_fma_f32 v14, v14, v22, v54
	v_fma_f32 v15, v15, v23, v55
	v_fma_f32 v12, v12, v20, v52
	v_fma_f32 v13, v13, v21, v53
	s_waitcnt vmcnt(2)
	v_fma_f32 v10, v10, v22, v58
	v_fma_f32 v11, v11, v23, v59
	v_fma_f32 v8, v8, v20, v56
	v_fma_f32 v9, v9, v21, v57
	s_waitcnt vmcnt(1)
	v_fma_f32 v6, v6, v22, v62
	v_fma_f32 v7, v7, v23, v63
	v_fma_f32 v4, v4, v20, v60
	v_fma_f32 v5, v5, v21, v61
	s_waitcnt vmcnt(0)
	v_fma_f32 v2, v2, v22, v66
	v_fma_f32 v3, v3, v23, v67
	v_fma_f32 v0, v0, v20, v64
	v_fma_f32 v1, v1, v21, v65
	global_store_dwordx4 v[142:143], v[28:31], off offset:576
	global_store_dwordx4 v[144:145], v[32:35], off offset:576
	global_store_dwordx4 v[146:147], v[24:27], off offset:576
	global_store_dwordx4 v[154:155], v[16:19], off offset:576
	global_store_dwordx4 v[162:163], v[12:15], off offset:576
	global_store_dwordx4 v[170:171], v[8:11], off offset:576
	global_store_dwordx4 v[92:93], v[4:7], off offset:576
	global_store_dwordx4 v[80:81], v[0:3], off offset:576
	s_cbranch_vccnz .LBB0_1299
	s_andn2_b64 vcc, exec, s[8:9]
	s_cbranch_vccnz .LBB0_1298
	s_barrier
	s_branch .LBB0_1298

; __device__ __forceinline__ unsigned pk2(float lo, float hi) { return f2bf(lo) | (f2bf(hi) << 16); }
; __device__ __forceinline__ void norm_mod_phase(const float* lat, long lat_bs, const float* cx, long ctx_bs, const float* modl, int shoff, int scoff, bf16* XN, int skip_ctx, int gw, int NGW, float* xcopy, const float* part, int nkc, const float* pgate) {
;     ...
;         if (skip_ctx && s == 4) continue;
; #pragma unroll
;         for (int j = 0; j < 4; ++j) ss += (v[j].x * v[j].x + v[j].y * v[j].y) + (v[j].z * v[j].z + v[j].w * v[j].w);
;         if (xcopy && s == 4) {
;             const int b_ = row / TPB, cr = b_ * CTXL + (row - b_ * TPB); const f32x4* gp = (const f32x4*)(pgate + 4 * NMOD6) + lane;
;             f32x4 sm[4];
; #pragma unroll
;             for (int j = 0; j < 4; ++j) sm[j] = (f32x4){0.f, 0.f, 0.f, 0.f};
;             for (int kc = 0; kc < nkc; ++kc) { const f32x4* pp = (const f32x4*)(part + ((size_t)kc * 1024 + cr) * DMODEL) + lane;
; #pragma unroll
;                 for (int j = 0; j < 4; ++j) sm[j] += pp[64 * j]; }
;             f32x4* xc = (f32x4*)(xcopy + (size_t)row * DMODEL) + lane; ss = 0.f;
; #pragma unroll
;             for (int j = 0; j < 4; ++j) { v[j] += gp[64 * j] * sm[j]; xc[64 * j] = v[j]; ss += (v[j].x * v[j].x + v[j].y * v[j].y) + (v[j].z * v[j].z + v[j].w * v[j].w); } }
;         const float rstd = 1.0f / sqrtf(wave_sum(ss) * (1.0f / DMODEL) + EPS);
;         const f32x4* sh = (const f32x4*)(modl + s * NMOD6 + shoff) + lane; const f32x4* sc = (const f32x4*)(modl + s * NMOD6 + scoff) + lane;
;         v2u* o8 = (v2u*)(XN + (size_t)row * DMODEL) + lane;
; #pragma unroll
;         for (int j = 0; j < 4; ++j) { const f32x4 a = sh[64 * j], m = sc[64 * j]; const f32x4 y = v[j] * rstd * (m + 1.0f) + a; v2u w; w.x = pk2(y.x, y.y); w.y = pk2(y.z, y.w); o8[64 * j] = w; }
.LBB0_1375:
	s_cmp_eq_u32 s6, 4
	s_cbranch_scc1 .LBB0_1372
	v_mul_f32_e32 v38, v30, v30
	v_mul_f32_e32 v39, v31, v31
	v_mul_f32_e32 v40, v28, v28
	v_mul_f32_e32 v41, v29, v29
	s_mulk_i32 s6, 0x1800
	v_mov_b32_e32 v42, v40
	v_mov_b32_e32 v43, v39
	v_pk_mov_b32 v[38:39], v[40:41], v[38:39] op_sel:[1,0]
	s_ashr_i32 s7, s6, 31
	v_add_f32_e32 v38, v38, v42
	v_add_f32_e32 v39, v39, v43
	s_lshl_b64 s[6:7], s[6:7], 2
	v_add_f32_e32 v46, v38, v38
	v_add_f32_e32 v47, v38, v39
	v_mul_f32_e32 v38, v26, v26
	v_mul_f32_e32 v39, v27, v27
	v_mul_f32_e32 v40, v24, v24
	v_mul_f32_e32 v41, v25, v25
	s_add_u32 s6, s86, s6
	v_mov_b32_e32 v42, v40
	v_mov_b32_e32 v43, v39
	v_pk_mov_b32 v[38:39], v[40:41], v[38:39] op_sel:[1,0]
	s_addc_u32 s7, s38, s7
	v_add_f32_e32 v38, v38, v42
	v_add_f32_e32 v39, v39, v43
	v_lshl_add_u64 v[54:55], s[6:7], 0, v[32:33]
	v_add_f32_e32 v48, v38, v38
	v_add_f32_e32 v49, v38, v39
	v_mul_f32_e32 v38, v4, v4
	v_add_co_u32_e32 v56, vcc, s3, v54
	v_fma_f32 v50, v4, v4, v38
	v_fma_f32 v51, v5, v5, v38
	v_mul_f32_e32 v38, v6, v6
	v_addc_co_u32_e32 v57, vcc, 0, v55, vcc
	v_fma_f32 v52, v6, v6, v38
	v_fma_f32 v53, v7, v7, v38
	global_load_dwordx4 v[38:41], v[56:57], off offset:-4096
	global_load_dwordx4 v[42:45], v[56:57], off
	v_mul_f32_e32 v50, v0, v0
	v_mul_f32_e32 v52, v1, v1
	v_mul_f32_e32 v48, v2, v2
	v_mul_f32_e32 v46, v3, v3
	v_add_f32_e32 v50, v50, v52
	v_add_f32_e32 v51, v51, v53
	v_add_f32_e32 v46, v48, v46
	v_add_f32_e32 v47, v49, v47
	s_waitcnt vmcnt(0)
	v_add_f32_e32 v42, 1.0, v42
	v_add_f32_e32 v43, 1.0, v43
	v_add_f32_e32 v46, v50, v46
	v_add_f32_e32 v47, v51, v47
	v_add_f32_e32 v44, 1.0, v44
	v_add_f32_e32 v45, 1.0, v45
	v_add_f32_e32 v46, v46, v47
	ds_bpermute_b32 v47, v223, v46
	s_waitcnt lgkmcnt(0)
	v_add_f32_e32 v46, v46, v47
	ds_bpermute_b32 v47, v230, v46
	s_waitcnt lgkmcnt(0)
	v_add_f32_e32 v46, v46, v47
	ds_bpermute_b32 v47, v231, v46
	s_waitcnt lgkmcnt(0)
	v_add_f32_e32 v46, v46, v47
	ds_bpermute_b32 v47, v232, v46
	s_waitcnt lgkmcnt(0)
	v_add_f32_e32 v46, v46, v47
	ds_bpermute_b32 v47, v233, v46
	s_waitcnt lgkmcnt(0)
	v_add_f32_e32 v46, v46, v47
	ds_bpermute_b32 v47, v234, v46
	s_waitcnt lgkmcnt(0)
	v_add_f32_e32 v46, v46, v47
	v_fmamk_f32 v46, v46, 0x3a800000, v36
	v_mul_f32_e32 v47, 0x4f800000, v46
	v_cmp_gt_f32_e32 vcc, s1, v46
	s_nop 1
	v_cndmask_b32_e32 v46, v46, v47, vcc
	v_sqrt_f32_e32 v47, v46
	s_nop 0
	v_add_u32_e32 v48, -1, v47
	v_add_u32_e32 v49, 1, v47
	v_fma_f32 v50, -v48, v47, v46
	v_fma_f32 v51, -v49, v47, v46
	v_cmp_ge_f32_e64 s[6:7], 0, v50
	s_nop 1
	v_cndmask_b32_e64 v47, v47, v48, s[6:7]
	v_cmp_lt_f32_e64 s[6:7], 0, v51
	s_nop 1
	v_cndmask_b32_e64 v47, v47, v49, s[6:7]
	v_mul_f32_e32 v48, 0x37800000, v47
	v_cndmask_b32_e32 v47, v47, v48, vcc
	v_cmp_class_f32_e32 vcc, v46, v37
	s_nop 1
	v_cndmask_b32_e32 v48, v47, v46, vcc
	v_div_scale_f32 v49, s[6:7], v48, v48, 1.0
	v_rcp_f32_e32 v50, v49
	v_div_scale_f32 v51, vcc, 1.0, v48, 1.0
	v_lshl_add_u64 v[46:47], v[54:55], 0, s[10:11]
	v_fma_f32 v52, -v49, v50, 1.0
	v_fmac_f32_e32 v50, v52, v50
	v_mul_f32_e32 v52, v51, v50
	v_fma_f32 v53, -v49, v52, v51
	v_fmac_f32_e32 v52, v53, v50
	v_fma_f32 v49, -v49, v52, v51
	v_div_fmas_f32 v49, v49, v50, v52
	v_div_fixup_f32 v48, v49, v48, 1.0
	v_mul_f32_e32 v28, v28, v48
	v_mul_f32_e32 v29, v29, v48
	v_mul_f32_e32 v30, v30, v48
	v_mul_f32_e32 v31, v31, v48
	v_fma_f32 v28, v42, v28, v38
	v_fma_f32 v29, v43, v29, v39
	v_fma_f32 v30, v44, v30, v40
	v_fma_f32 v31, v45, v31, v41
	v_bfe_u32 v38, v28, 16, 1
	v_bfe_u32 v39, v29, 16, 1
	v_add3_u32 v28, v28, v38, s4
	v_lshrrev_b32_e32 v28, 16, v28
	v_add3_u32 v29, v29, v39, s4
	v_and_or_b32 v28, v29, s5, v28
	v_bfe_u32 v29, v30, 16, 1
	v_add3_u32 v29, v30, v29, s4
	v_bfe_u32 v30, v31, 16, 1
	v_lshrrev_b32_e32 v29, 16, v29
	v_add3_u32 v30, v31, v30, s4
	v_and_or_b32 v29, v30, s5, v29
	global_store_dwordx2 v[34:35], v[28:29], off
	global_load_dwordx4 v[28:31], v[46:47], off offset:1024
	v_lshl_add_u64 v[42:43], v[54:55], 0, s[8:9]
	global_load_dwordx4 v[38:41], v[42:43], off offset:1024
	global_load_dwordx4 v[100:103], v[46:47], off offset:2048
	global_load_dwordx4 v[104:107], v[42:43], off offset:2048
	global_load_dwordx4 v[108:111], v[46:47], off offset:3072
	global_load_dwordx4 v[112:115], v[42:43], off offset:3072
	v_mul_f32_e32 v24, v24, v48
	v_mul_f32_e32 v25, v25, v48
	v_mul_f32_e32 v26, v26, v48
	v_mul_f32_e32 v27, v27, v48
	v_mul_f32_e32 v4, v4, v48
	v_mul_f32_e32 v5, v5, v48
	v_mul_f32_e32 v6, v6, v48
	v_mul_f32_e32 v7, v7, v48
	v_mul_f32_e32 v0, v0, v48
	v_mul_f32_e32 v1, v1, v48
	v_mul_f32_e32 v2, v2, v48
	v_mul_f32_e32 v3, v3, v48
	s_waitcnt vmcnt(5)
	v_add_f32_e32 v30, 1.0, v30
	v_add_f32_e32 v31, 1.0, v31
	v_add_f32_e32 v28, 1.0, v28
	v_add_f32_e32 v29, 1.0, v29
	s_waitcnt vmcnt(4)
	v_fma_f32 v26, v30, v26, v40
	v_fma_f32 v27, v31, v27, v41
	v_fma_f32 v24, v28, v24, v38
	v_fma_f32 v25, v29, v25, v39
	v_bfe_u32 v30, v26, 16, 1
	v_bfe_u32 v28, v24, 16, 1
	v_bfe_u32 v29, v25, 16, 1
	v_bfe_u32 v31, v27, 16, 1
	v_add3_u32 v24, v24, v28, s4
	v_add3_u32 v26, v26, v30, s4
	v_add3_u32 v25, v25, v29, s4
	v_add3_u32 v27, v27, v31, s4
	v_lshrrev_b32_e32 v24, 16, v24
	v_lshrrev_b32_e32 v26, 16, v26
	v_and_or_b32 v24, v25, s5, v24
	v_and_or_b32 v25, v27, s5, v26
	global_store_dwordx2 v[34:35], v[24:25], off offset:512
	s_nop 0
	s_waitcnt vmcnt(4)
	v_add_f32_e32 v26, 1.0, v102
	v_add_f32_e32 v27, 1.0, v103
	v_add_f32_e32 v24, 1.0, v100
	v_add_f32_e32 v25, 1.0, v101
	s_waitcnt vmcnt(3)
	v_fma_f32 v6, v6, v26, v106
	v_fma_f32 v7, v7, v27, v107
	v_fma_f32 v4, v4, v24, v104
	v_fma_f32 v5, v5, v25, v105
	v_bfe_u32 v26, v6, 16, 1
	v_bfe_u32 v24, v4, 16, 1
	v_bfe_u32 v25, v5, 16, 1
	v_bfe_u32 v27, v7, 16, 1
	v_add3_u32 v4, v4, v24, s4
	v_add3_u32 v6, v6, v26, s4
	v_add3_u32 v5, v5, v25, s4
	v_add3_u32 v7, v7, v27, s4
	v_lshrrev_b32_e32 v4, 16, v4
	v_lshrrev_b32_e32 v6, 16, v6
	v_and_or_b32 v4, v5, s5, v4
	v_and_or_b32 v5, v7, s5, v6
	global_store_dwordx2 v[34:35], v[4:5], off offset:1024
	s_nop 0
	s_waitcnt vmcnt(3)
	v_add_f32_e32 v6, 1.0, v110
	v_add_f32_e32 v7, 1.0, v111
	v_add_f32_e32 v4, 1.0, v108
	v_add_f32_e32 v5, 1.0, v109
	s_waitcnt vmcnt(2)
	v_fma_f32 v2, v2, v6, v114
	v_fma_f32 v3, v3, v7, v115
	v_fma_f32 v0, v0, v4, v112
	v_fma_f32 v1, v1, v5, v113
	v_bfe_u32 v6, v2, 16, 1
	v_bfe_u32 v4, v0, 16, 1
	v_bfe_u32 v5, v1, 16, 1
	v_bfe_u32 v7, v3, 16, 1
	v_add3_u32 v0, v0, v4, s4
	v_add3_u32 v2, v2, v6, s4
	v_add3_u32 v1, v1, v5, s4
	v_add3_u32 v3, v3, v7, s4
	v_lshrrev_b32_e32 v0, 16, v0
	v_lshrrev_b32_e32 v2, 16, v2
	v_and_or_b32 v0, v1, s5, v0
	v_and_or_b32 v1, v3, s5, v2
	global_store_dwordx2 v[34:35], v[0:1], off offset:1536
	s_branch .LBB0_1372

;     __device__ __forceinline__ void operator()(const f32x4 (&acc)[2][2][4][2], const Unit& u, int wr, int wc, int fr, int fq) const {
;         const int b = u.pm / 33, tt = u.pm - b * 33; const bool isctx = (tt == 0);
;         const float* g = gate + (isctx ? 4 : b) * 6144;
;         const float* src = isctx ? base_ctx + (size_t)b * ctx_bs : base_lat + (size_t)b * lat_bs + (size_t)(tt * 256 - 256) * 1024;
;         float* dst = out + (size_t)u.pm * 256 * 1024;
;         const int col0 = u.pn * BM + wc * 32 + 4 * fq;
;         const size_t off0 = (size_t)(wr * 64 + fr) * 1024 + col0;
; #pragma unroll
;         for (int bj = 0; bj < 2; ++bj)
; #pragma unroll
;             for (int n = 0; n < 2; ++n) { const f32x4 gv = *(const f32x4*)(g + col0 + bj * HALF + n * 16); f32x4 bs[2][4];
; #pragma unroll
;                 for (int ai = 0; ai < 2; ++ai)
; #pragma unroll
;                     for (int m = 0; m < 4; ++m) bs[ai][m] = *(const f32x4*)(src + off0 + (size_t)(ai * HALF + m * 16) * 1024 + bj * HALF + n * 16);
; #pragma unroll
;                 for (int ai = 0; ai < 2; ++ai)
; #pragma unroll
;                     for (int m = 0; m < 4; ++m) *(f32x4*)(dst + off0 + (size_t)(ai * HALF + m * 16) * 1024 + bj * HALF + n * 16) = bs[ai][m] + gv * acc[ai][bj][m][n];
;                 asm volatile("" ::: "memory"); }
.LBB0_1524:
	s_lshl_b64 s[22:23], s[22:23], 2
	v_lshl_or_b32 v142, s19, 8, v173
	s_add_u32 s22, s52, s22
	v_ashrrev_i32_e32 v143, 31, v142
	s_addc_u32 s23, s53, s23
	v_lshl_add_u64 v[144:145], v[132:133], 0, v[142:143]
	v_lshl_add_u64 v[148:149], v[142:143], 2, s[22:23]
	v_lshlrev_b64 v[142:143], 2, v[144:145]
	v_lshl_add_u64 v[150:151], s[20:21], 0, v[142:143]
	v_add_co_u32_e32 v152, vcc, s51, v150
	global_load_dwordx4 v[190:193], v[148:149], off
	s_nop 0
	v_addc_co_u32_e32 v153, vcc, 0, v151, vcc
	v_add_co_u32_e32 v156, vcc, s64, v150
	global_load_dwordx4 v[194:197], v[150:151], off
	global_load_dwordx4 v[198:201], v[152:153], off
	v_addc_co_u32_e32 v157, vcc, 0, v151, vcc
	v_add_co_u32_e32 v158, vcc, s65, v150
	s_ashr_i32 s19, s18, 31
	s_nop 0
	v_addc_co_u32_e32 v159, vcc, 0, v151, vcc
	v_add_co_u32_e32 v160, vcc, s66, v150
	global_load_dwordx4 v[202:205], v[156:157], off
	global_load_dwordx4 v[206:209], v[158:159], off
	v_addc_co_u32_e32 v161, vcc, 0, v151, vcc
	v_add_co_u32_e32 v164, vcc, s67, v150
	global_load_dwordx4 v[210:213], v[160:161], off
	s_nop 0
	v_addc_co_u32_e32 v165, vcc, 0, v151, vcc
	v_add_co_u32_e32 v166, vcc, s68, v150
	global_load_dwordx4 v[214:217], v[164:165], off
	s_nop 0
	v_addc_co_u32_e32 v167, vcc, 0, v151, vcc
	global_load_dwordx4 v[218:221], v[166:167], off
	v_add_co_u32_e32 v168, vcc, s69, v150
	s_lshl_b64 s[18:19], s[18:19], 20
	s_nop 0
	v_addc_co_u32_e32 v169, vcc, 0, v151, vcc
	global_load_dwordx4 v[224:227], v[168:169], off
	s_add_u32 s18, s48, s18
	s_addc_u32 s19, s49, s19
	v_lshl_add_u64 v[142:143], s[18:19], 0, v[142:143]
	v_add_co_u32_e32 v144, vcc, s51, v142
	s_waitcnt vmcnt(0)
	v_fma_f32 v126, v126, v192, v196
	v_fma_f32 v127, v127, v193, v197
	v_addc_co_u32_e32 v145, vcc, 0, v143, vcc
	v_add_co_u32_e32 v146, vcc, s64, v142
	v_fma_f32 v124, v124, v190, v194
	v_fma_f32 v125, v125, v191, v195
	s_nop 0
	v_addc_co_u32_e32 v147, vcc, 0, v143, vcc
	v_add_co_u32_e32 v154, vcc, s65, v142
	v_fma_f32 v122, v122, v192, v200
	v_fma_f32 v123, v123, v193, v201
	s_nop 0
	v_addc_co_u32_e32 v155, vcc, 0, v143, vcc
	v_add_co_u32_e32 v162, vcc, s66, v142
	v_fma_f32 v120, v120, v190, v198
	v_fma_f32 v121, v121, v191, v199
	s_nop 0
	v_addc_co_u32_e32 v163, vcc, 0, v143, vcc
	v_add_co_u32_e32 v170, vcc, s67, v142
	global_store_dwordx4 v[142:143], v[124:127], off
	s_nop 0
	v_addc_co_u32_e32 v171, vcc, 0, v143, vcc
	v_fma_f32 v100, v100, v190, v214
	v_fma_f32 v101, v101, v191, v215
	v_fma_f32 v118, v118, v192, v204
	v_fma_f32 v119, v119, v193, v205
	v_fma_f32 v116, v116, v190, v202
	v_fma_f32 v117, v117, v191, v203
	v_fma_f32 v114, v114, v192, v208
	v_fma_f32 v115, v115, v193, v209
	v_fma_f32 v112, v112, v190, v206
	v_fma_f32 v113, v113, v191, v207
	v_fma_f32 v106, v106, v192, v212
	v_fma_f32 v107, v107, v193, v213
	v_fma_f32 v104, v104, v190, v210
	v_fma_f32 v105, v105, v191, v211
	v_fma_f32 v102, v102, v192, v216
	v_fma_f32 v103, v103, v193, v217
	global_store_dwordx4 v[144:145], v[120:123], off
	global_store_dwordx4 v[146:147], v[116:119], off
	global_store_dwordx4 v[154:155], v[112:115], off
	global_store_dwordx4 v[162:163], v[104:107], off
	global_store_dwordx4 v[170:171], v[100:103], off
	s_nop 1
	v_fma_f32 v100, v92, v190, v218
	v_fma_f32 v101, v93, v191, v219
	v_add_co_u32_e32 v92, vcc, s68, v142
	v_fma_f32 v102, v94, v192, v220
	v_fma_f32 v103, v95, v193, v221
	s_nop 0
	v_addc_co_u32_e32 v93, vcc, 0, v143, vcc
	global_store_dwordx4 v[92:93], v[100:103], off
	s_nop 1
	v_fma_f32 v100, v80, v190, v224
	v_fma_f32 v101, v81, v191, v225
	v_add_co_u32_e32 v80, vcc, s69, v142
	v_fma_f32 v102, v82, v192, v226
	v_fma_f32 v103, v83, v193, v227
	s_nop 0
	v_addc_co_u32_e32 v81, vcc, 0, v143, vcc
	global_store_dwordx4 v[80:81], v[100:103], off
	global_load_dwordx4 v[100:103], v[148:149], off offset:64
	global_load_dwordx4 v[104:107], v[150:151], off offset:64
	global_load_dwordx4 v[112:115], v[152:153], off offset:64
	global_load_dwordx4 v[116:119], v[156:157], off offset:64
	global_load_dwordx4 v[120:123], v[158:159], off offset:64
	global_load_dwordx4 v[124:127], v[160:161], off offset:64
	global_load_dwordx4 v[190:193], v[164:165], off offset:64
	global_load_dwordx4 v[194:197], v[166:167], off offset:64
	global_load_dwordx4 v[198:201], v[168:169], off offset:64
	s_and_b64 vcc, exec, s[6:7]
	s_mov_b64 s[6:7], -1
	s_waitcnt vmcnt(7)
	v_fma_f32 v106, v110, v102, v106
	v_fma_f32 v107, v111, v103, v107
	v_fma_f32 v104, v108, v100, v104
	v_fma_f32 v105, v109, v101, v105
	s_waitcnt vmcnt(6)
	v_fma_f32 v98, v98, v102, v114
	v_fma_f32 v99, v99, v103, v115
	v_fma_f32 v96, v96, v100, v112
	v_fma_f32 v97, v97, v101, v113
	s_waitcnt vmcnt(5)
	v_fma_f32 v90, v90, v102, v118
	v_fma_f32 v91, v91, v103, v119
	v_fma_f32 v88, v88, v100, v116
	v_fma_f32 v89, v89, v101, v117
	s_waitcnt vmcnt(4)
	v_fma_f32 v86, v86, v102, v122
	v_fma_f32 v87, v87, v103, v123
	v_fma_f32 v84, v84, v100, v120
	v_fma_f32 v85, v85, v101, v121
	s_waitcnt vmcnt(3)
	v_fma_f32 v78, v78, v102, v126
	v_fma_f32 v79, v79, v103, v127
	v_fma_f32 v76, v76, v100, v124
	v_fma_f32 v77, v77, v101, v125
	s_waitcnt vmcnt(2)
; #define PG8_BAR __builtin_amdgcn_s_barrier()
;     __device__ __forceinline__ void operator()(const f32x4 (&acc)[2][2][4][2], const Unit& u, int wr, int wc, int fr, int fq) const {
;     ...
; #pragma unroll
;         for (int bj = 0; bj < 2; ++bj)
; #pragma unroll
;             for (int n = 0; n < 2; ++n) { const f32x4 gv = *(const f32x4*)(g + col0 + bj * HALF + n * 16); f32x4 bs[2][4];
; #pragma unroll
;                 for (int ai = 0; ai < 2; ++ai)
; #pragma unroll
;                     for (int m = 0; m < 4; ++m) bs[ai][m] = *(const f32x4*)(src + off0 + (size_t)(ai * HALF + m * 16) * 1024 + bj * HALF + n * 16);
; #pragma unroll
;                 for (int ai = 0; ai < 2; ++ai)
; #pragma unroll
;                     for (int m = 0; m < 4; ++m) *(f32x4*)(dst + off0 + (size_t)(ai * HALF + m * 16) * 1024 + bj * HALF + n * 16) = bs[ai][m] + gv * acc[ai][bj][m][n];
;                 asm volatile("" ::: "memory"); }
; template <class Epi, class Sched, bool ALIGN_EPI = false, bool SP2 = false>
; __device__ __forceinline__ void gemm_phase(PG8_LAS unsigned char* lds, const Gemm g, const Sched& S, const Epi& E) {
;     ...
;         if constexpr (ALIGN_EPI) { if (wr == 1) PG8_BAR; }
;     }
	v_fma_f32 v74, v74, v102, v192
	v_fma_f32 v75, v75, v103, v193
	v_fma_f32 v72, v72, v100, v190
	v_fma_f32 v73, v73, v101, v191
	s_waitcnt vmcnt(1)
	v_fma_f32 v66, v66, v102, v196
	v_fma_f32 v67, v67, v103, v197
	v_fma_f32 v64, v64, v100, v194
	v_fma_f32 v65, v65, v101, v195
	s_waitcnt vmcnt(0)
	v_fma_f32 v58, v58, v102, v200
	v_fma_f32 v59, v59, v103, v201
	v_fma_f32 v56, v56, v100, v198
	v_fma_f32 v57, v57, v101, v199
	global_store_dwordx4 v[142:143], v[104:107], off offset:64
	global_store_dwordx4 v[144:145], v[96:99], off offset:64
	global_store_dwordx4 v[146:147], v[88:91], off offset:64
	global_store_dwordx4 v[154:155], v[84:87], off offset:64
	global_store_dwordx4 v[162:163], v[76:79], off offset:64
	global_store_dwordx4 v[170:171], v[72:75], off offset:64
	global_store_dwordx4 v[92:93], v[64:67], off offset:64
	global_store_dwordx4 v[80:81], v[56:59], off offset:64
	global_load_dwordx4 v[56:59], v[148:149], off offset:512
	global_load_dwordx4 v[64:67], v[150:151], off offset:512
	global_load_dwordx4 v[72:75], v[152:153], off offset:512
	global_load_dwordx4 v[76:79], v[156:157], off offset:512
	global_load_dwordx4 v[82:85], v[158:159], off offset:512
	global_load_dwordx4 v[86:89], v[160:161], off offset:512
	global_load_dwordx4 v[94:97], v[164:165], off offset:512
	global_load_dwordx4 v[98:101], v[166:167], off offset:512
	global_load_dwordx4 v[102:105], v[168:169], off offset:512
	s_waitcnt vmcnt(7)
	v_fma_f32 v66, v70, v58, v66
	v_fma_f32 v67, v71, v59, v67
	v_fma_f32 v64, v68, v56, v64
	v_fma_f32 v65, v69, v57, v65
	s_waitcnt vmcnt(6)
	v_fma_f32 v62, v62, v58, v74
	v_fma_f32 v63, v63, v59, v75
	v_fma_f32 v60, v60, v56, v72
	v_fma_f32 v61, v61, v57, v73
	s_waitcnt vmcnt(5)
	v_fma_f32 v54, v54, v58, v78
	v_fma_f32 v55, v55, v59, v79
	v_fma_f32 v52, v52, v56, v76
	v_fma_f32 v53, v53, v57, v77
	s_waitcnt vmcnt(4)
	v_fma_f32 v50, v50, v58, v84
	v_fma_f32 v51, v51, v59, v85
	v_fma_f32 v48, v48, v56, v82
	v_fma_f32 v49, v49, v57, v83
	s_waitcnt vmcnt(3)
	v_fma_f32 v46, v46, v58, v88
	v_fma_f32 v47, v47, v59, v89
	v_fma_f32 v44, v44, v56, v86
	v_fma_f32 v45, v45, v57, v87
	s_waitcnt vmcnt(2)
	v_fma_f32 v38, v38, v58, v96
	v_fma_f32 v39, v39, v59, v97
	v_fma_f32 v36, v36, v56, v94
	v_fma_f32 v37, v37, v57, v95
	s_waitcnt vmcnt(1)
	v_fma_f32 v30, v30, v58, v100
	v_fma_f32 v31, v31, v59, v101
	v_fma_f32 v28, v28, v56, v98
	v_fma_f32 v29, v29, v57, v99
	s_waitcnt vmcnt(0)
	v_fma_f32 v22, v22, v58, v104
	v_fma_f32 v23, v23, v59, v105
	v_fma_f32 v20, v20, v56, v102
	v_fma_f32 v21, v21, v57, v103
	global_store_dwordx4 v[142:143], v[64:67], off offset:512
	global_store_dwordx4 v[144:145], v[60:63], off offset:512
	global_store_dwordx4 v[146:147], v[52:55], off offset:512
	global_store_dwordx4 v[154:155], v[48:51], off offset:512
	global_store_dwordx4 v[162:163], v[44:47], off offset:512
	global_store_dwordx4 v[170:171], v[36:39], off offset:512
	global_store_dwordx4 v[92:93], v[28:31], off offset:512
	global_store_dwordx4 v[80:81], v[20:23], off offset:512
	global_load_dwordx4 v[20:23], v[148:149], off offset:576
	global_load_dwordx4 v[28:31], v[150:151], off offset:576
	global_load_dwordx4 v[36:39], v[152:153], off offset:576
	global_load_dwordx4 v[44:47], v[156:157], off offset:576
	global_load_dwordx4 v[48:51], v[158:159], off offset:576
	global_load_dwordx4 v[52:55], v[160:161], off offset:576
	global_load_dwordx4 v[56:59], v[164:165], off offset:576
	global_load_dwordx4 v[60:63], v[166:167], off offset:576
	global_load_dwordx4 v[64:67], v[168:169], off offset:576
	s_waitcnt vmcnt(7)
	v_fma_f32 v30, v42, v22, v30
	v_fma_f32 v31, v43, v23, v31
	v_fma_f32 v28, v40, v20, v28
	v_fma_f32 v29, v41, v21, v29
	s_waitcnt vmcnt(6)
	v_fma_f32 v34, v34, v22, v38
	v_fma_f32 v35, v35, v23, v39
	v_fma_f32 v32, v32, v20, v36
	v_fma_f32 v33, v33, v21, v37
	s_waitcnt vmcnt(5)
	v_fma_f32 v26, v26, v22, v46
	v_fma_f32 v27, v27, v23, v47
	v_fma_f32 v24, v24, v20, v44
	v_fma_f32 v25, v25, v21, v45
	s_waitcnt vmcnt(4)
	v_fma_f32 v18, v18, v22, v50
	v_fma_f32 v19, v19, v23, v51
	v_fma_f32 v16, v16, v20, v48
	v_fma_f32 v17, v17, v21, v49
	s_waitcnt vmcnt(3)
	v_fma_f32 v14, v14, v22, v54
	v_fma_f32 v15, v15, v23, v55
	v_fma_f32 v12, v12, v20, v52
	v_fma_f32 v13, v13, v21, v53
	s_waitcnt vmcnt(2)
	v_fma_f32 v10, v10, v22, v58
	v_fma_f32 v11, v11, v23, v59
	v_fma_f32 v8, v8, v20, v56
	v_fma_f32 v9, v9, v21, v57
	s_waitcnt vmcnt(1)
	v_fma_f32 v6, v6, v22, v62
	v_fma_f32 v7, v7, v23, v63
	v_fma_f32 v4, v4, v20, v60
	v_fma_f32 v5, v5, v21, v61
	s_waitcnt vmcnt(0)
	v_fma_f32 v2, v2, v22, v66
	v_fma_f32 v3, v3, v23, v67
	v_fma_f32 v0, v0, v20, v64
	v_fma_f32 v1, v1, v21, v65
	global_store_dwordx4 v[142:143], v[28:31], off offset:576
	global_store_dwordx4 v[144:145], v[32:35], off offset:576
	global_store_dwordx4 v[146:147], v[24:27], off offset:576
	global_store_dwordx4 v[154:155], v[16:19], off offset:576
	global_store_dwordx4 v[162:163], v[12:15], off offset:576
	global_store_dwordx4 v[170:171], v[8:11], off offset:576
	global_store_dwordx4 v[92:93], v[4:7], off offset:576
	global_store_dwordx4 v[80:81], v[0:3], off offset:576
	s_cbranch_vccnz .LBB0_1506
	s_andn2_b64 vcc, exec, s[8:9]
	s_cbranch_vccnz .LBB0_1505
	s_barrier
	s_branch .LBB0_1505

; __global__ void __launch_bounds__(NTHREADS, 2) fwd_megakernel(Args a) {
;     ...
;     for (int lr = gw; lr < NBATCH * SEQ; lr += NGW) {
;         f32x4 v[4]; float ss = 0.f;
; #pragma unroll
;         for (int j = 0; j < 4; ++j) v[j] = vn[j];
;         if (lr + NGW < NBATCH * SEQ) { const int ln = lr + NGW, b = ln / SEQ, pos = ln - b * SEQ; const f32x4* xr = (const f32x4*)(X + ((size_t)b * TPB + CTXL + pos) * DMODEL) + lane;
; #pragma unroll
;             for (int j = 0; j < 4; ++j) vn[j] = xr[64 * j]; }
; #pragma unroll
;         for (int j = 0; j < 4; ++j) ss += (v[j].x * v[j].x + v[j].y * v[j].y) + (v[j].z * v[j].z + v[j].w * v[j].w);
;         const float rstd = 1.0f / sqrtf(wave_sum(ss) * (1.0f / DMODEL) + EPS);
;         const f32x4* gp = (const f32x4*)a.fgain + lane; f32x4* op = (f32x4*)(a.out + (size_t)lr * DMODEL) + lane;
; #pragma unroll
;         for (int j = 0; j < 4; ++j) op[64 * j] = v[j] * rstd * gp[64 * j];
;     } }
.LBB0_1583:
	v_mul_f32_e32 v40, v8, v8
	v_mul_f32_e32 v41, v9, v9
	v_mul_f32_e32 v42, v10, v10
	v_mul_f32_e32 v43, v11, v11
	v_mul_f32_e32 v44, v12, v12
	v_mul_f32_e32 v45, v13, v13
	v_mul_f32_e32 v46, v14, v14
	v_mul_f32_e32 v47, v15, v15
	v_mov_b32_e32 v48, v44
	v_mov_b32_e32 v49, v47
	v_pk_mov_b32 v[44:45], v[44:45], v[46:47] op_sel:[1,0]
	v_mov_b32_e32 v46, v40
	v_mov_b32_e32 v47, v43
	v_pk_mov_b32 v[40:41], v[40:41], v[42:43] op_sel:[1,0]
	v_add_f32_e32 v44, v44, v48
	v_add_f32_e32 v45, v45, v49
	v_add_f32_e32 v40, v40, v46
	v_add_f32_e32 v41, v41, v47
	v_mul_f32_e32 v46, v0, v0
	v_mul_f32_e32 v47, v1, v1
	v_add_f32_e32 v42, v44, v45
	v_add_f32_e32 v43, v45, v44
	v_pk_add_f32 v[40:41], v[40:41], v[40:41] op_sel:[0,1] op_sel_hi:[1,0]
	v_mov_b32_e32 v43, v46
	v_mov_b32_e32 v41, v47
	v_add_f32_e32 v44, v42, v40
	v_add_f32_e32 v45, v43, v41
	v_mul_f32_e32 v40, v5, v5
	v_fma_f32 v46, v4, v4, v40
	v_fma_f32 v47, v5, v5, v40
	global_load_dwordx4 v[40:43], v[34:35], off
	v_mul_f32_e32 v48, v2, v2
	v_mov_b32_e32 v47, v48
	v_mul_f32_e32 v48, v7, v7
	v_mul_f32_e32 v50, v3, v3
	v_fma_f32 v49, v7, v7, v48
	v_fma_f32 v48, v6, v6, v48
	s_add_u32 s6, s6, s42
	v_mov_b32_e32 v49, v50
	v_add_f32_e32 v46, v46, v48
	v_add_f32_e32 v47, v47, v49
	s_addc_u32 s7, s7, s43
	v_add_f32_e32 v44, v44, v46
	v_add_f32_e32 v45, v45, v47
	s_nop 0
	v_add_f32_e32 v44, v44, v45
	ds_bpermute_b32 v45, v223, v44
	s_waitcnt lgkmcnt(0)
	v_add_f32_e32 v44, v44, v45
	ds_bpermute_b32 v45, v230, v44
	s_waitcnt lgkmcnt(0)
	v_add_f32_e32 v44, v44, v45
	ds_bpermute_b32 v45, v231, v44
	s_waitcnt lgkmcnt(0)
	v_add_f32_e32 v44, v44, v45
	ds_bpermute_b32 v45, v232, v44
	s_waitcnt lgkmcnt(0)
	v_add_f32_e32 v44, v44, v45
	ds_bpermute_b32 v45, v233, v44
	s_waitcnt lgkmcnt(0)
	v_add_f32_e32 v44, v44, v45
	ds_bpermute_b32 v45, v234, v44
	s_waitcnt lgkmcnt(0)
	v_add_f32_e32 v44, v44, v45
	v_fmamk_f32 v44, v44, 0x3a800000, v38
	v_mul_f32_e32 v45, 0x4f800000, v44
	v_cmp_gt_f32_e32 vcc, s8, v44
	s_nop 1
	v_cndmask_b32_e32 v44, v44, v45, vcc
	v_sqrt_f32_e32 v45, v44
	s_nop 0
	v_add_u32_e32 v46, -1, v45
	v_add_u32_e32 v47, 1, v45
	v_fma_f32 v48, -v46, v45, v44
	v_fma_f32 v49, -v47, v45, v44
	v_cmp_ge_f32_e64 s[0:1], 0, v48
	s_nop 1
	v_cndmask_b32_e64 v45, v45, v46, s[0:1]
	v_cmp_lt_f32_e64 s[0:1], 0, v49
	s_nop 1
	v_cndmask_b32_e64 v45, v45, v47, s[0:1]
	v_mul_f32_e32 v46, 0x37800000, v45
	v_cndmask_b32_e32 v45, v45, v46, vcc
	v_cmp_class_f32_e32 vcc, v44, v39
	s_nop 1
	v_cndmask_b32_e32 v44, v45, v44, vcc
	v_div_scale_f32 v45, s[0:1], v44, v44, 1.0
	v_rcp_f32_e32 v46, v45
	v_div_scale_f32 v47, vcc, 1.0, v44, 1.0
	v_fma_f32 v48, -v45, v46, 1.0
	v_fmac_f32_e32 v46, v48, v46
	v_mul_f32_e32 v48, v47, v46
	v_fma_f32 v49, -v45, v48, v47
	v_fmac_f32_e32 v48, v49, v46
	v_fma_f32 v45, -v45, v48, v47
	v_div_fmas_f32 v45, v45, v46, v48
	v_div_fixup_f32 v44, v45, v44, 1.0
	v_mul_f32_e32 v12, v44, v12
	v_mul_f32_e32 v13, v44, v13
	v_mul_f32_e32 v14, v44, v14
	v_mul_f32_e32 v15, v44, v15
	s_waitcnt vmcnt(0)
	v_mul_f32_e32 v14, v14, v42
	v_mul_f32_e32 v15, v15, v43
	v_mul_f32_e32 v12, v12, v40
	v_mul_f32_e32 v13, v13, v41
	global_store_dwordx4 v[36:37], v[12:15], off
	global_load_dwordx4 v[12:15], v[34:35], off offset:1024
	global_load_dwordx4 v[100:103], v[34:35], off offset:2048
	global_load_dwordx4 v[104:107], v[34:35], off offset:3072
	v_mul_f32_e32 v10, v44, v10
	v_mul_f32_e32 v11, v44, v11
	v_mul_f32_e32 v8, v44, v8
	v_mul_f32_e32 v9, v44, v9
	v_mul_f32_e32 v6, v44, v6
	v_mul_f32_e32 v7, v44, v7
	v_mul_f32_e32 v4, v44, v4
	v_mul_f32_e32 v5, v44, v5
	v_mul_f32_e32 v46, v44, v2
	v_mul_f32_e32 v47, v44, v3
	v_mul_f32_e32 v45, v44, v1
	v_mul_f32_e32 v44, v44, v0
	s_and_b64 vcc, exec, s[4:5]
	v_mov_b32_e32 v0, v28
	v_mov_b32_e32 v1, v29
	v_mov_b32_e32 v2, v30
	v_mov_b32_e32 v3, v31
	s_waitcnt vmcnt(2)
	v_mul_f32_e32 v8, v8, v12
	v_mul_f32_e32 v9, v9, v13
	v_mul_f32_e32 v10, v10, v14
	v_mul_f32_e32 v11, v11, v15
	global_store_dwordx4 v[36:37], v[8:11], off offset:1024
	v_mov_b32_e32 v12, v16
	v_mov_b32_e32 v13, v17
	v_mov_b32_e32 v14, v18
	v_mov_b32_e32 v15, v19
	s_waitcnt vmcnt(2)
	v_mul_f32_e32 v4, v4, v100
	v_mul_f32_e32 v5, v5, v101
	v_mul_f32_e32 v6, v6, v102
	v_mul_f32_e32 v7, v7, v103
	global_store_dwordx4 v[36:37], v[4:7], off offset:2048
	v_mov_b32_e32 v8, v20
	v_mov_b32_e32 v9, v21
	v_mov_b32_e32 v10, v22
	v_mov_b32_e32 v11, v23
	v_mov_b32_e32 v4, v24
	v_mov_b32_e32 v5, v25
	v_mov_b32_e32 v6, v26
	v_mov_b32_e32 v7, v27
	s_waitcnt vmcnt(2)
	v_mul_f32_e32 v16, v44, v104
	v_mul_f32_e32 v17, v45, v105
	v_mul_f32_e32 v18, v46, v106
	v_mul_f32_e32 v19, v47, v107
	global_store_dwordx4 v[36:37], v[16:19], off offset:3072
	v_lshl_add_u64 v[36:37], v[36:37], 0, s[2:3]
	s_cbranch_vccnz .LBB0_1586
